# RWKV units: XOR-swizzled column (key=(row>>1)&3) for the prepared-block LDS arrays Wb/Hb: the preppers' 8-way bank-conflicted ds_write_b64/b128 become 2-way, stage-H readers apply the same key
# speedup vs baseline: 1.0354x; 1.0173x over previous
.LBB0_351:
	v_readlane_b32 s36, v254, 21
	v_and_b32_e32 v66, 63, v64
	v_readlane_b32 s48, v254, 33
	v_readlane_b32 s49, v254, 34
	v_lshlrev_b32_sdwa v173, v162, v123 dst_sel:DWORD dst_unused:UNUSED_PAD src0_sel:DWORD src1_sel:WORD_0
	v_readlane_b32 s38, v254, 23
	v_readlane_b32 s39, v254, 24
	v_readlane_b32 s44, v254, 29
	v_readlane_b32 s45, v254, 30
	v_readlane_b32 s46, v254, 31
	v_readlane_b32 s47, v254, 32
	v_lshl_add_u64 v[40:41], s[48:49], 0, v[4:5]
	s_andn2_b64 vcc, exec, s[4:5]
	v_cmp_gt_u32_e64 s[6:7], 8, v63
	v_cmp_eq_u32_e64 s[4:5], v66, v65
	v_readlane_b32 s37, v254, 22
	v_readlane_b32 s40, v254, 25
	v_readlane_b32 s41, v254, 26
	v_readlane_b32 s42, v254, 27
	v_readlane_b32 s43, v254, 28
	v_readlane_b32 s50, v254, 35
	v_readlane_b32 s51, v254, 36
	s_cbranch_vccnz .LBB0_355
	s_lshl_b32 s8, s26, 3
	v_or_b32_e32 v172, s8, v65
	v_bitop3_b32 v1, s8, v163, v65 bitop3:0x36
	v_cndmask_b32_e64 v1, v1, v172, s[2:3]
	v_or_b32_e32 v1, v1, v173
	v_mov_b64_e32 v[56:57], s[38:39]
	v_mad_u64_u32 v[20:21], s[10:11], v1, s87, v[56:57]
	v_lshlrev_b32_e32 v2, 4, v23
	v_lshl_add_u64 v[4:5], v[20:21], 0, v[2:3]
	v_add_co_u32_e32 v24, vcc, 0x3000, v4
	v_or_b32_e32 v43, v62, v69
	s_nop 0
	v_addc_co_u32_e32 v25, vcc, 0, v5, vcc
	global_load_dwordx4 v[70:73], v[24:25], off offset:1568
	global_load_dwordx4 v[74:77], v[24:25], off offset:1632
	v_lshlrev_b32_e32 v4, 1, v68
	v_or_b32_e32 v109, v43, v67
	v_add3_u32 v98, 0, v2, v4
	v_lshlrev_b32_e32 v60, 1, v109
	s_mov_b64 s[10:11], 0x1e20
	v_mov_b32_e32 v61, v3
	v_mov_b32_e32 v59, v3
	v_add_u32_e32 v102, 0xe000, v98
	v_or_b32_e32 v58, 32, v60
	v_lshl_add_u64 v[22:23], v[20:21], 0, s[10:11]
	s_mov_b64 s[12:13], 0x2420
	s_mov_b64 s[14:15], 0x2a20
	ds_read_b128 v[78:81], v98 offset:57344
	ds_read_b128 v[36:39], v98 offset:57408
	ds_read_b128 v[8:11], v98 offset:59648
	ds_read_b128 v[4:7], v98 offset:59712
	ds_read_b128 v[32:35], v98 offset:61952
	ds_read_b128 v[28:31], v98 offset:62016
	ds_read_b128 v[82:85], v102 offset:9216
	ds_read_b128 v[86:89], v102 offset:9280
	ds_read_b128 v[16:19], v102 offset:11520
	ds_read_b128 v[12:15], v102 offset:11584
	v_lshl_add_u64 v[26:27], v[20:21], 0, s[12:13]
	v_lshl_add_u64 v[44:45], v[20:21], 0, s[14:15]
	v_lshl_add_u64 v[46:47], v[22:23], 0, v[60:61]
	v_lshl_add_u64 v[90:91], v[22:23], 0, v[58:59]
	global_load_dwordx4 v[20:23], v[24:25], off offset:1696
	v_lshl_add_u64 v[50:51], v[26:27], 0, v[60:61]
	v_lshl_add_u64 v[54:55], v[44:45], 0, v[60:61]
	v_lshl_add_u64 v[26:27], v[26:27], 0, v[58:59]
	v_lshl_add_u64 v[92:93], v[44:45], 0, v[58:59]
	global_load_dwordx2 v[48:49], v[46:47], off
	global_load_dwordx2 v[52:53], v[50:51], off
	s_nop 0
	global_load_dwordx2 v[50:51], v[54:55], off
	global_load_dwordx2 v[44:45], v[90:91], off
	s_nop 0
	global_load_dwordx2 v[54:55], v[26:27], off
	global_load_dwordx2 v[46:47], v[92:93], off
	s_nop 0
	global_load_dwordx4 v[24:27], v[24:25], off offset:1760
	v_bitop3_b32 v107, s8, v164, v65 bitop3:0x36
	v_or_b32_e32 v106, 32, v172
	v_add_u32_e32 v107, 0x100, v107
	v_cndmask_b32_e64 v106, v107, v106, s[2:3]
	v_or_b32_e32 v106, v106, v173
	v_mad_u64_u32 v[56:57], s[8:9], v106, s87, v[56:57]
	v_lshl_add_u64 v[106:107], v[56:57], 0, v[2:3]
	s_movk_i32 s8, 0x3000
	v_add_co_u32_e32 v106, vcc, s8, v106
	v_lshl_add_u64 v[112:113], v[56:57], 0, s[12:13]
	s_nop 0
	v_addc_co_u32_e32 v107, vcc, 0, v107, vcc
	v_lshlrev_b32_e32 v2, 2, v0
	v_lshl_add_u64 v[116:117], v[112:113], 0, v[60:61]
	v_cmp_lt_i32_e32 vcc, v157, v158
	v_lshl_or_b32 v174, v172, 6, v43
	v_bfe_u32 v246, v238, 1, 2
	v_lshlrev_b32_e32 v246, 2, v246
	v_xor_b32_e32 v174, v174, v246
	v_lshl_add_u32 v43, v174, 2, 0
	s_mov_b64 s[72:73], 0x2420
	s_mov_b64 s[74:75], 0x2a20
	s_waitcnt vmcnt(7) lgkmcnt(3)
	v_mfma_f32_16x16x32_f16 v[82:85], v[82:85], v[20:23], 0
	v_cndmask_b32_e64 v70, v72, v70, s[6:7]
	v_cndmask_b32_e64 v71, v73, v71, s[6:7]
	v_cndmask_b32_e64 v72, v76, v74, s[6:7]
	v_cndmask_b32_e64 v73, v77, v75, s[6:7]
	v_cvt_f32_f16_e32 v74, v70
	v_cvt_f32_f16_sdwa v70, v70 dst_sel:DWORD dst_unused:UNUSED_PAD src0_sel:WORD_1
	v_cvt_f32_f16_e32 v75, v71
	v_cvt_f32_f16_sdwa v71, v71 dst_sel:DWORD dst_unused:UNUSED_PAD src0_sel:WORD_1
	v_cvt_f32_f16_e32 v77, v73
	v_cvt_f32_f16_sdwa v73, v73 dst_sel:DWORD dst_unused:UNUSED_PAD src0_sel:WORD_1
	v_cvt_f32_f16_e32 v76, v72
	v_cvt_f32_f16_sdwa v72, v72 dst_sel:DWORD dst_unused:UNUSED_PAD src0_sel:WORD_1
	v_add_f32_e32 v74, v74, v74
	v_add_f32_e32 v70, v70, v70
	v_add_f32_e32 v75, v75, v75
	v_add_f32_e32 v71, v71, v71
	v_add_f32_e32 v73, v73, v73
	v_mul_f32_e32 v74, 0x3fb8aa3b, v74
	v_mul_f32_e32 v70, 0x3fb8aa3b, v70
	v_mul_f32_e32 v75, 0x3fb8aa3b, v75
	v_mul_f32_e32 v71, 0x3fb8aa3b, v71
	v_mul_f32_e32 v90, 0x3fb8aa3b, v73
	v_exp_f32_e32 v73, v74
	v_exp_f32_e32 v70, v70
	v_exp_f32_e32 v74, v75
	v_exp_f32_e32 v71, v71
	v_add_f32_e32 v76, v76, v76
	v_add_f32_e32 v72, v72, v72
	v_mul_f32_e32 v76, 0x3fb8aa3b, v76
	v_mul_f32_e32 v72, 0x3fb8aa3b, v72
	v_exp_f32_e32 v75, v76
	v_exp_f32_e32 v76, v72
	v_add_f32_e32 v72, 1.0, v73
	v_add_f32_e32 v73, 1.0, v70
	v_add_f32_e32 v74, 1.0, v74
	v_add_f32_e32 v91, 1.0, v71
	v_rcp_f32_e32 v70, v72
	v_rcp_f32_e32 v71, v73
	v_add_f32_e32 v77, v77, v77
	v_rcp_f32_e32 v72, v74
	v_rcp_f32_e32 v73, v91
	v_mul_f32_e32 v77, 0x3fb8aa3b, v77
	v_exp_f32_e32 v77, v77
	v_exp_f32_e32 v90, v90
	v_add_f32_e32 v75, 1.0, v75
	v_pk_fma_f32 v[70:71], v[70:71], 2.0, 1.0 op_sel_hi:[1,0,0] neg_lo:[1,0,0] neg_hi:[1,0,0]
	v_rcp_f32_e32 v74, v75
	v_pk_fma_f32 v[72:73], v[72:73], 2.0, 1.0 op_sel_hi:[1,0,0] neg_lo:[1,0,0] neg_hi:[1,0,0]
	v_cvt_pk_f16_f32 v75, v70, v71
	v_add_f32_e32 v76, 1.0, v76
	v_cvt_pk_f16_f32 v73, v72, v73
	v_mov_b32_dpp v72, v75 row_ror:8 row_mask:0xf bank_mask:0xf bound_ctrl:1
	v_cndmask_b32_e64 v70, v72, v75, s[6:7]
	v_cndmask_b32_e64 v72, v75, v72, s[6:7]
	v_rcp_f32_e32 v75, v76
	v_add_f32_e32 v76, 1.0, v77
	v_add_f32_e32 v77, 1.0, v90
	v_rcp_f32_e32 v76, v76
	v_rcp_f32_e32 v77, v77
	v_mov_b32_dpp v91, v73 row_ror:8 row_mask:0xf bank_mask:0xf bound_ctrl:1
	v_pk_fma_f32 v[74:75], v[74:75], 2.0, 1.0 op_sel_hi:[1,0,0] neg_lo:[1,0,0] neg_hi:[1,0,0]
	v_cndmask_b32_e64 v71, v91, v73, s[6:7]
	v_cndmask_b32_e64 v73, v73, v91, s[6:7]
	v_cvt_pk_f16_f32 v90, v74, v75
	v_pk_fma_f32 v[74:75], v[76:77], 2.0, 1.0 op_sel_hi:[1,0,0] neg_lo:[1,0,0] neg_hi:[1,0,0]
	v_mfma_f32_16x16x32_f16 v[8:11], v[8:11], v[70:73], 0
	v_cvt_pk_f16_f32 v91, v74, v75
	s_waitcnt vmcnt(6)
	v_cvt_f32_f16_sdwa v122, v49 dst_sel:DWORD dst_unused:UNUSED_PAD src0_sel:WORD_1
	v_mfma_f32_16x16x32_f16 v[74:77], v[78:81], v[70:73], 0
	v_mov_b32_dpp v80, v90 row_ror:8 row_mask:0xf bank_mask:0xf bound_ctrl:1
	v_mov_b32_dpp v81, v91 row_ror:8 row_mask:0xf bank_mask:0xf bound_ctrl:1
	v_cndmask_b32_e64 v78, v80, v90, s[6:7]
	s_waitcnt lgkmcnt(1)
	v_mfma_f32_16x16x32_f16 v[16:19], v[16:19], v[20:23], 0
	v_cndmask_b32_e64 v79, v81, v91, s[6:7]
	v_cndmask_b32_e64 v80, v90, v80, s[6:7]
	v_cndmask_b32_e64 v81, v91, v81, s[6:7]
	v_mfma_f32_16x16x32_f16 v[32:35], v[32:35], v[70:73], 0
	s_nop 0
	v_mfma_f32_16x16x32_f16 v[36:39], v[36:39], v[78:81], v[74:77]
	s_nop 2
	ds_read_b128 v[74:77], v102 offset:13824
	ds_read_b128 v[90:93], v102 offset:13888
	ds_read_b128 v[94:97], v98 offset:64256
	ds_read_b128 v[98:101], v98 offset:64320
	s_waitcnt vmcnt(0)
	v_mfma_f32_16x16x32_f16 v[82:85], v[86:89], v[24:27], v[82:85]
	ds_read_b128 v[86:89], v102 offset:16128
	ds_read_b128 v[102:105], v102 offset:16192
	v_mfma_f32_16x16x32_f16 v[124:127], v[4:7], v[78:81], v[8:11]
	global_load_dwordx4 v[4:7], v[106:107], off offset:1568
	s_nop 1
	global_load_dwordx4 v[8:11], v[106:107], off offset:1632
	s_waitcnt lgkmcnt(6)
	v_mfma_f32_16x16x32_f16 v[128:131], v[12:15], v[24:27], v[16:19]
	s_nop 2
	global_load_dwordx4 v[16:19], v[106:107], off offset:1696
	global_load_dwordx4 v[12:15], v[106:107], off offset:1760
	v_lshl_add_u64 v[106:107], v[56:57], 0, s[10:11]
	v_lshl_add_u64 v[56:57], v[56:57], 0, s[14:15]
	v_readlane_b32 s8, v254, 53
	v_readlane_b32 s10, v254, 55
	v_readlane_b32 s11, v254, 56
	v_readlane_b32 s14, v254, 59
	v_readlane_b32 s15, v254, 60
	v_mfma_f32_16x16x32_f16 v[132:135], v[28:31], v[78:81], v[32:35]
	v_lshl_add_u64 v[110:111], v[106:107], 0, v[60:61]
	v_lshl_add_u64 v[28:29], v[112:113], 0, v[58:59]
	v_lshl_add_u64 v[60:61], v[56:57], 0, v[60:61]
	v_lshl_add_u64 v[32:33], s[10:11], 0, v[2:3]
	v_lshl_add_u64 v[34:35], s[14:15], 0, v[2:3]
	v_lshlrev_b32_e32 v2, 2, v109
	v_lshl_add_u64 v[32:33], v[32:33], 0, v[2:3]
	v_lshl_add_u64 v[106:107], v[106:107], 0, v[58:59]
	global_load_dwordx2 v[114:115], v[110:111], off
	global_load_dwordx2 v[118:119], v[116:117], off
	s_nop 0
	global_load_dwordx2 v[116:117], v[60:61], off
	global_load_dwordx2 v[110:111], v[106:107], off
	v_lshl_add_u64 v[30:31], v[56:57], 0, v[58:59]
	global_load_dwordx2 v[120:121], v[28:29], off
	global_load_dwordx2 v[112:113], v[30:31], off
	s_waitcnt lgkmcnt(0)
	s_barrier
	global_load_dwordx4 v[56:59], v[32:33], off
	v_lshl_add_u64 v[60:61], v[34:35], 0, v[2:3]
	v_mfma_f32_16x16x32_f16 v[28:31], v[94:97], v[70:73], 0
	global_load_dwordx4 v[70:73], v[60:61], off
	v_readlane_b32 s18, v254, 63
	v_readlane_b32 s19, v255, 0
	v_mfma_f32_16x16x32_f16 v[74:77], v[74:77], v[20:23], 0
	v_readlane_b32 s20, v255, 1
	v_readlane_b32 s21, v255, 2
	v_readlane_b32 s22, v255, 3
	v_mfma_f32_16x16x32_f16 v[20:23], v[86:89], v[20:23], 0
	global_load_dwordx4 v[86:89], v[32:33], off offset:64
	v_readlane_b32 s23, v255, 4
	v_cndmask_b32_e64 v36, v132, v36, s[6:7]
	v_mfma_f32_16x16x32_f16 v[74:77], v[90:93], v[24:27], v[74:77]
	v_cndmask_b32_e64 v37, v133, v37, s[6:7]
	v_cndmask_b32_e64 v38, v134, v38, s[6:7]
	v_cvt_f32_f16_e32 v106, v48
	v_mfma_f32_16x16x32_f16 v[78:81], v[98:101], v[78:81], v[28:31]
	v_cvt_f32_f16_sdwa v107, v48 dst_sel:DWORD dst_unused:UNUSED_PAD src0_sel:WORD_1
	v_cvt_f32_f16_e32 v109, v49
	v_readlane_b32 s9, v254, 54
	v_mfma_f32_16x16x32_f16 v[90:93], v[102:105], v[24:27], v[20:23]
	global_load_dwordx4 v[94:97], v2, s[18:19]
	global_load_dwordx4 v[32:35], v2, s[20:21]
	global_load_dwordx4 v[98:101], v[60:61], off offset:64
	global_load_dwordx4 v[28:31], v2, s[22:23]
	global_load_dwordx4 v[102:105], v2, s[18:19] offset:64
	global_load_dwordx4 v[24:27], v2, s[20:21] offset:64
	global_load_dwordx4 v[20:23], v2, s[22:23] offset:64
	v_cndmask_b32_e64 v2, v135, v39, s[6:7]
	v_cndmask_b32_e64 v39, v77, v85, s[6:7]
	v_cndmask_b32_e64 v60, v74, v82, s[6:7]
	v_cndmask_b32_e64 v61, v75, v83, s[6:7]
	v_cvt_f32_f16_e32 v74, v54
	v_cvt_f32_f16_sdwa v75, v54 dst_sel:DWORD dst_unused:UNUSED_PAD src0_sel:WORD_1
	v_readlane_b32 s12, v254, 57
	v_readlane_b32 s13, v254, 58
	v_readlane_b32 s16, v254, 61
	v_readlane_b32 s17, v254, 62
	s_waitcnt vmcnt(9)
	v_add_f32_e32 v2, v2, v59
	v_add_f32_e32 v36, v36, v56
	v_cndmask_b32_e64 v56, v76, v84, s[6:7]
	v_mul_f32_e32 v2, 0xbfb8aa3b, v2
	s_waitcnt vmcnt(8)
	v_add_f32_e32 v56, v56, v72
	v_exp_f32_e32 v2, v2
	v_mul_f32_e32 v56, 0xbfb8aa3b, v56
	v_exp_f32_e32 v56, v56
	v_add_f32_e32 v60, v60, v70
	v_add_f32_e32 v2, 1.0, v2
	v_rcp_f32_e32 v2, v2
	v_add_f32_e32 v39, v39, v73
	v_mul_f32_e32 v60, 0xbfb8aa3b, v60
	v_add_f32_e32 v56, 1.0, v56
	v_mul_f32_e32 v39, 0xbfb8aa3b, v39
	v_exp_f32_e32 v60, v60
	v_rcp_f32_e32 v70, v56
	v_exp_f32_e32 v56, v39
	v_mul_f32_e32 v2, 0xbf1b4598, v2
	v_mul_f32_e32 v2, 0x3fb8aa3b, v2
	v_add_f32_e32 v37, v37, v57
	v_add_f32_e32 v57, 1.0, v60
	v_exp_f32_e32 v39, v2
	v_add_f32_e32 v2, 1.0, v56
	v_rcp_f32_e32 v60, v57
	v_add_f32_e32 v57, v61, v71
	v_rcp_f32_e32 v71, v2
	v_cndmask_b32_e64 v2, v81, v127, s[6:7]
	v_add_f32_e32 v38, v38, v58
	v_cndmask_b32_e64 v58, v80, v126, s[6:7]
	s_waitcnt vmcnt(7)
	v_add_f32_e32 v2, v2, v89
	v_add_f32_e32 v58, v58, v88
	v_mul_f32_e32 v2, 0xbfb8aa3b, v2
	v_mul_f32_e32 v57, 0xbfb8aa3b, v57
	v_mul_f32_e32 v58, 0xbfb8aa3b, v58
	v_exp_f32_e32 v2, v2
	v_exp_f32_e32 v57, v57
	v_exp_f32_e32 v58, v58
	v_cndmask_b32_e64 v59, v93, v131, s[6:7]
	v_add_f32_e32 v2, 1.0, v2
	v_add_f32_e32 v57, 1.0, v57
	v_cndmask_b32_e64 v80, v92, v130, s[6:7]
	v_add_f32_e32 v54, 1.0, v58
	v_rcp_f32_e32 v2, v2
	s_waitcnt vmcnt(4)
	v_add_f32_e32 v59, v59, v101
	v_rcp_f32_e32 v61, v57
	v_cndmask_b32_e64 v56, v78, v124, s[6:7]
	v_cndmask_b32_e64 v57, v79, v125, s[6:7]
	v_rcp_f32_e32 v54, v54
	v_add_f32_e32 v58, v80, v100
	v_mul_f32_e32 v59, 0xbfb8aa3b, v59
	v_add_f32_e32 v56, v56, v86
	v_add_f32_e32 v57, v57, v87
	v_mul_f32_e32 v58, 0xbfb8aa3b, v58
	v_exp_f32_e32 v82, v59
	v_cvt_f32_f16_e32 v86, v52
	v_cvt_f32_f16_sdwa v87, v52 dst_sel:DWORD dst_unused:UNUSED_PAD src0_sel:WORD_1
	v_exp_f32_e32 v80, v58
	v_cvt_f32_f16_e32 v52, v53
	v_cvt_f32_f16_sdwa v53, v53 dst_sel:DWORD dst_unused:UNUSED_PAD src0_sel:WORD_1
	v_mul_f32_e32 v2, 0xbf1b4598, v2
	v_mul_f32_e32 v54, 0xbf1b4598, v54
	v_mul_f32_e32 v2, 0x3fb8aa3b, v2
	v_mul_f32_e32 v54, 0x3fb8aa3b, v54
	v_exp_f32_e32 v59, v2
	v_add_f32_e32 v2, 1.0, v82
	v_pk_mul_f32 v[88:89], v[94:95], v[86:87]
	v_cndmask_b32_e64 v73, v91, v129, s[6:7]
	v_cndmask_b32_e64 v72, v90, v128, s[6:7]
	v_exp_f32_e32 v58, v54
	v_add_f32_e32 v54, 1.0, v80
	v_cvt_f32_f16_e32 v80, v55
	v_cvt_f32_f16_sdwa v81, v55 dst_sel:DWORD dst_unused:UNUSED_PAD src0_sel:WORD_1
	v_rcp_f32_e32 v55, v2
	v_cndmask_b32_e32 v2, v156, v157, vcc
	v_pk_mul_f32 v[90:91], v[88:89], v[88:89]
	v_pk_mul_f32 v[92:93], v[96:97], v[52:53]
	s_waitcnt vmcnt(2)
	v_pk_mul_f32 v[76:77], v[102:103], v[74:75]
	v_lshlrev_b32_e32 v102, 2, v2
	v_pk_mul_f32 v[94:95], v[92:93], v[92:93]
	v_add_f32_e32 v2, v90, v91
	v_add_f32_e32 v2, v94, v2
	v_pk_mul_f32 v[78:79], v[76:77], v[76:77]
	v_add_f32_e32 v2, v95, v2
	v_pk_mul_f32 v[82:83], v[104:105], v[80:81]
	v_add_f32_e32 v2, v2, v78
	v_pk_mul_f32 v[84:85], v[82:83], v[82:83]
	v_add_f32_e32 v2, v79, v2
	v_add_f32_e32 v2, v84, v2
	v_add_f32_e32 v2, v85, v2
	v_cmp_lt_i32_e32 vcc, v159, v158
	v_mul_f32_e32 v36, 0xbfb8aa3b, v36
	v_add_f32_dpp v2, v2, v2 row_ror:8 row_mask:0xf bank_mask:0xf bound_ctrl:1
	ds_bpermute_b32 v84, v102, v2
	v_cndmask_b32_e32 v78, v156, v159, vcc
	v_lshlrev_b32_e32 v90, 2, v78
	v_mul_f32_e32 v37, 0xbfb8aa3b, v37
	v_mul_f32_e32 v38, 0xbfb8aa3b, v38
	s_waitcnt lgkmcnt(0)
	v_add_f32_e32 v2, v2, v84
	ds_bpermute_b32 v84, v90, v2
	v_exp_f32_e32 v36, v36
	v_exp_f32_e32 v37, v37
	v_exp_f32_e32 v38, v38
	v_add_f32_e32 v72, v72, v98
	s_waitcnt lgkmcnt(0)
	v_add_f32_e32 v2, v2, v84
	v_add_f32_e32 v36, 1.0, v36
	v_add_f32_e32 v37, 1.0, v37
	v_add_f32_e32 v38, 1.0, v38
	v_add_f32_e32 v73, v73, v99
	v_max_f32_e32 v2, 0x179abe15, v2
	v_rcp_f32_e32 v36, v36
	v_rcp_f32_e32 v37, v37
	v_rcp_f32_e32 v38, v38
	v_mul_f32_e32 v72, 0xbfb8aa3b, v72
	v_mul_f32_e32 v73, 0xbfb8aa3b, v73
	v_pk_add_f32 v[78:79], v[60:61], -1.0 op_sel_hi:[1,0]
	v_rsq_f32_e32 v2, v2
	v_exp_f32_e32 v72, v72
	v_exp_f32_e32 v73, v73
	v_pk_fma_f32 v[32:33], v[32:33], v[78:79], 1.0 op_sel_hi:[1,1,0]
	v_mul_f32_e32 v36, 0xbf1b4598, v36
	v_pk_mul_f32 v[32:33], v[32:33], v[86:87]
	v_mul_f32_e32 v37, 0xbf1b4598, v37
	v_mul_f32_e32 v78, v32, v106
	v_mul_f32_e32 v38, 0xbf1b4598, v38
	v_fma_f32 v86, v28, v78, 0
	v_pk_mul_f32 v[78:79], v[92:93], v[2:3] op_sel_hi:[1,0]
	v_mul_f32_e32 v36, 0x3fb8aa3b, v36
	v_mul_f32_e32 v37, 0x3fb8aa3b, v37
	v_mul_f32_e32 v38, 0x3fb8aa3b, v38
	v_add_f32_e32 v72, 1.0, v72
	v_add_f32_e32 v73, 1.0, v73
	v_pk_mul_f32 v[84:85], v[70:71], v[78:79]
	v_pk_add_f32 v[70:71], v[70:71], -1.0 op_sel_hi:[1,0]
	v_exp_f32_e32 v36, v36
	v_exp_f32_e32 v37, v37
	v_exp_f32_e32 v38, v38
	v_rcp_f32_e32 v72, v72
	v_rcp_f32_e32 v73, v73
	v_pk_fma_f32 v[34:35], v[34:35], v[70:71], 1.0 op_sel_hi:[1,1,0]
	v_mul_f32_e32 v28, v33, v107
	v_pk_mul_f32 v[34:35], v[34:35], v[52:53]
	v_fmac_f32_e32 v86, v29, v28
	v_cvt_pk_f16_f32 v28, v32, v33
	v_pk_mul_f32 v[32:33], v[88:89], v[2:3] op_sel_hi:[1,0]
	v_mul_f32_e32 v29, v34, v109
	v_cvt_f32_f16_e32 v98, v44
	v_pk_mul_f32 v[60:61], v[60:61], v[32:33]
	v_mul_f32_e32 v52, v35, v122
	v_fmac_f32_e32 v86, v30, v29
	v_cvt_pk_f16_f32 v30, -v32, -v33
	v_lshlrev_b32_e32 v32, 1, v174
	v_cvt_f32_f16_sdwa v99, v44 dst_sel:DWORD dst_unused:UNUSED_PAD src0_sel:WORD_1
	v_fmac_f32_e32 v86, v31, v52
	v_cvt_pk_f16_f32 v29, v34, v35
	v_cvt_pk_f16_f32 v31, -v78, -v79
	ds_write_b128 v43, v[36:39]
	v_sub_u32_e32 v36, v43, v32
	v_pk_add_f32 v[34:35], v[72:73], -1.0 op_sel_hi:[1,0]
	v_rcp_f32_e32 v54, v54
	v_cvt_pk_f16_f32 v60, v60, v61
	v_cvt_pk_f16_f32 v61, v84, v85
	ds_write_b64 v36, v[30:31] offset:20480
	ds_write_b64 v36, v[60:61] offset:24576
	ds_write_b64 v36, v[48:49] offset:28672
	ds_write_b64 v36, v[50:51] offset:32768
	v_pk_mul_f32 v[30:31], v[76:77], v[2:3] op_sel_hi:[1,0]
	s_waitcnt vmcnt(1)
	v_pk_fma_f32 v[24:25], v[24:25], v[34:35], 1.0 op_sel_hi:[1,1,0]
	v_pk_mul_f32 v[32:33], v[72:73], v[30:31]
	v_pk_mul_f32 v[24:25], v[24:25], v[74:75]
	v_cvt_pk_f16_f32 v32, v32, v33
	v_mul_f32_e32 v33, v24, v98
	v_cvt_f32_f16_e32 v100, v45
	v_mul_f32_e32 v34, v25, v99
	s_waitcnt vmcnt(0)
	v_fmac_f32_e32 v86, v20, v33
	v_cvt_f32_f16_sdwa v101, v45 dst_sel:DWORD dst_unused:UNUSED_PAD src0_sel:WORD_1
	v_fmac_f32_e32 v86, v21, v34
	v_pk_add_f32 v[20:21], v[54:55], -1.0 op_sel_hi:[1,0]
	v_mul_f32_e32 v56, 0xbfb8aa3b, v56
	v_pk_fma_f32 v[20:21], v[26:27], v[20:21], 1.0 op_sel_hi:[1,1,0]
	v_mul_f32_e32 v57, 0xbfb8aa3b, v57
	v_pk_mul_f32 v[26:27], v[20:21], v[80:81]
	v_exp_f32_e32 v56, v56
	v_exp_f32_e32 v57, v57
	v_mul_f32_e32 v20, v26, v100
	v_mul_f32_e32 v21, v27, v101
	v_fmac_f32_e32 v86, v22, v20
	v_fmac_f32_e32 v86, v23, v21
	v_add_f32_e32 v56, 1.0, v56
	v_add_f32_e32 v57, 1.0, v57
	v_add_f32_dpp v23, v86, v86 row_ror:8 row_mask:0xf bank_mask:0xf bound_ctrl:1
	ds_bpermute_b32 v34, v102, v23
	v_rcp_f32_e32 v56, v56
	v_rcp_f32_e32 v57, v57
	v_cvt_pk_f16_f32 v22, v24, v25
	v_pk_mul_f32 v[24:25], v[82:83], v[2:3] op_sel_hi:[1,0]
	v_mul_f32_e32 v56, 0xbf1b4598, v56
	v_mul_f32_e32 v57, 0xbf1b4598, v57
	v_pk_mul_f32 v[20:21], v[54:55], v[24:25]
	s_waitcnt lgkmcnt(0)
	v_add_f32_e32 v2, v23, v34
	v_mul_f32_e32 v56, 0x3fb8aa3b, v56
	v_mul_f32_e32 v57, 0x3fb8aa3b, v57
	v_cvt_pk_f16_f32 v33, v20, v21
	ds_bpermute_b32 v20, v90, v2
	v_exp_f32_e32 v56, v56
	v_exp_f32_e32 v57, v57
	v_cvt_pk_f16_f32 v23, v26, v27
	v_add_u32_e32 v21, 0x4000, v36
	v_cvt_pk_f16_f32 v25, -v24, -v25
	v_cvt_pk_f16_f32 v24, -v30, -v31
	ds_write_b128 v43, v[56:59] offset:64
	ds_write2_b64 v21, v[28:29], v[22:23] offset1:4
	ds_write_b64 v36, v[24:25] offset:20512
	ds_write_b64 v36, v[32:33] offset:24608
	ds_write_b64 v36, v[44:45] offset:28704
	ds_write_b64 v36, v[46:47] offset:32800
	s_and_saveexec_b64 s[6:7], s[4:5]
	s_cbranch_execz .LBB0_354
	s_waitcnt lgkmcnt(6)
	v_add_f32_e32 v22, v2, v20
	v_mad_u64_u32 v[20:21], s[4:5], v1, 48, v[40:41]
	v_lshlrev_b32_e32 v2, 2, v108
	v_lshl_add_u64 v[20:21], v[20:21], 0, v[2:3]
	global_store_dword v[20:21], v22, off

.LBB0_355:
	v_mov_b32_e32 v23, s47
	v_mov_b32_e32 v24, s45
	v_cndmask_b32_e64 v25, v23, v24, s[2:3]
	v_mov_b32_e32 v23, s46
	v_mov_b32_e32 v24, s44
	v_cndmask_b32_e64 v24, v23, v24, s[2:3]
	v_lshlrev_b32_e32 v23, 1, v64
	v_bfe_u32 v28, v64, 5, 1
	v_and_b32_e32 v29, 62, v23
	v_lshl_or_b32 v23, v28, 6, v29
	v_readlane_b32 s6, v255, 38
	v_lshlrev_b32_e32 v30, 2, v29
	v_readlane_b32 s7, v255, 39
	v_mad_u32_u24 v178, v23, 40, s6
	v_lshlrev_b32_e32 v23, 8, v28
	v_lshlrev_b32_e32 v31, 1, v122
	v_add3_u32 v179, s7, v23, v30
	v_lshl_add_u32 v180, v122, 2, s7
	v_add_u32_e32 v32, s6, v31
	v_readlane_b32 s6, v255, 28
	v_readlane_b32 s7, v255, 29
	v_lshl_add_u64 v[24:25], v[2:3], 1, v[24:25]
	s_lshl_b32 s6, s26, 5
	s_mov_b32 s9, s7
	v_writelane_b32 v255, s8, 28
	v_lshl_add_u64 v[24:25], v[24:25], 0, s[6:7]
	v_lshlrev_b32_e32 v26, 1, v63
	v_mov_b32_e32 v27, v3
	v_writelane_b32 v255, s9, 29
	v_lshl_add_u64 v[126:127], v[24:25], 0, v[26:27]
	v_lshlrev_b32_e32 v23, 1, v124
	v_lshlrev_b32_e32 v26, 1, v22
	v_add3_u32 v181, 0, v23, v26
	v_or3_b32 v2, v2, v21, v122
	v_lshlrev_b32_e32 v22, 2, v108
	v_mov_b32_e32 v23, v3
	v_mul_u32_u24_e32 v21, 0x900, v28
	v_lshlrev_b32_e32 v27, 1, v29
	v_readlane_b32 s27, v255, 40
	v_lshl_add_u64 v[128:129], v[40:41], 0, v[22:23]
	v_cmp_eq_u32_e32 vcc, v122, v63
	v_add3_u32 v183, s27, v21, v27
	v_lshl_or_b32 v21, v28, 4, 1
	v_or_b32_e32 v22, 1, v122
	v_lshlrev_b32_e32 v184, 6, v21
	v_mul_u32_u24_e32 v21, 0x90, v21
	v_cndmask_b32_e64 v215, 0, 1.0, vcc
	v_cmp_lt_u32_e64 s[14:15], v22, v63
	v_cmp_eq_u32_e32 vcc, v22, v63
	v_or_b32_e32 v22, 2, v122
	v_add3_u32 v185, s27, v21, v27
	v_add_u32_e32 v21, s27, v26
	v_lshlrev_b32_e32 v20, 1, v20
	v_cndmask_b32_e64 v217, 0, 1.0, vcc
	v_cmp_lt_u32_e64 s[16:17], v22, v63
	v_cmp_lt_u32_e64 s[18:19], v63, v22
	v_cmp_eq_u32_e32 vcc, v22, v63
	v_or_b32_e32 v22, 3, v122
	v_add_u32_e32 v214, v21, v20
	v_cndmask_b32_e64 v218, 0, 1.0, vcc
	v_cmp_lt_u32_e64 s[20:21], v22, v63
	v_cmp_lt_u32_e64 s[22:23], v63, v22
	v_cmp_eq_u32_e32 vcc, v22, v63
	v_add_u32_e32 v220, v21, v31
	v_or_b32_e32 v21, 16, v63
	v_mov_b32_e32 v22, s27
	v_mad_u32_u24 v21, v21, s92, v22
	v_readlane_b32 s36, v254, 53
	v_add_u32_e32 v226, v21, v20
	v_lshlrev_b32_e32 v20, 12, v28
	v_lshlrev_b64 v[0:1], 2, v[0:1]
	v_readlane_b32 s38, v254, 55
	v_readlane_b32 s39, v254, 56
	v_readlane_b32 s42, v254, 59
	v_readlane_b32 s43, v254, 60
	v_add_u32_e32 v227, v21, v31
	v_add3_u32 v232, 0, v30, v20
	v_readlane_b32 s46, v254, 63
	v_readlane_b32 s47, v255, 0
	v_readlane_b32 s48, v255, 1
	v_readlane_b32 s49, v255, 2
	v_readlane_b32 s50, v255, 3
	v_readlane_b32 s51, v255, 4
	v_lshl_add_u64 v[20:21], s[38:39], 0, v[0:1]
	v_lshl_add_u64 v[0:1], s[42:43], 0, v[0:1]
	v_lshlrev_b64 v[22:23], 2, v[2:3]
	v_or_b32_e32 v24, 16, v2
	v_mov_b32_e32 v25, v3
	v_lshl_or_b32 v216, s26, 4, v63
	v_mul_u32_u24_e32 v26, 40, v63
	v_readlane_b32 s37, v254, 54
	v_readlane_b32 s40, v254, 57
	v_readlane_b32 s41, v254, 58
	v_readlane_b32 s44, v254, 61
	v_readlane_b32 s45, v254, 62
	v_lshl_add_u64 v[130:131], v[20:21], 0, v[22:23]
	v_lshl_add_u64 v[132:133], v[0:1], 0, v[22:23]
	v_lshl_add_u64 v[134:135], s[46:47], 0, v[22:23]
	v_lshl_add_u64 v[136:137], s[48:49], 0, v[22:23]
	v_lshl_add_u64 v[138:139], s[50:51], 0, v[22:23]
	v_mov_b32_e32 v22, v3
	v_mov_b32_e32 v23, v3
	v_bfe_u32 v176, v64, 6, 2
	v_lshlrev_b32_e32 v177, 10, v28
	v_mad_u32_u24 v221, v216, 40, v32
	v_mad_u32_u24 v222, v63, 40, v32
	v_add_u32_e32 v233, 0, v27
	v_mov_b32_e32 v20, v3
	v_mov_b32_e32 v21, v3
	v_add_u32_e32 v236, v32, v26
	v_lshlrev_b64 v[142:143], 1, v[24:25]
	v_mov_b64_e32 v[34:35], v[22:23]
	v_mov_b64_e32 v[30:31], v[22:23]
	v_mov_b64_e32 v[26:27], v[22:23]
	v_readlane_b32 s36, v255, 5
	s_mov_b32 s76, 0
	v_cmp_eq_u32_e64 s[4:5], 0, v176
	v_add_u32_e32 v182, 0xe000, v181
	v_cmp_gt_u32_e64 s[6:7], 8, v63
	v_cmp_eq_u32_e64 s[8:9], v66, v65
	v_mov_b32_e32 v109, v3
	v_or_b32_e32 v186, 0x80, v177
	v_add_u32_e32 v187, 0x90, v185
	v_or_b32_e32 v188, 0xc0, v177
	v_add_u32_e32 v189, 0x120, v185
	v_or_b32_e32 v190, 0x100, v177
	v_add_u32_e32 v191, 0x1b0, v185
	v_or_b32_e32 v192, 0x140, v177
	v_add_u32_e32 v193, 0x240, v185
	v_or_b32_e32 v194, 0x180, v177
	v_add_u32_e32 v195, 0x2d0, v185
	v_or_b32_e32 v196, 0x1c0, v177
	v_add_u32_e32 v197, 0x360, v185
	v_or_b32_e32 v198, 0x200, v177
	v_add_u32_e32 v199, 0x3f0, v185
	v_or_b32_e32 v200, 0x240, v177
	v_add_u32_e32 v201, 0x480, v185
	v_or_b32_e32 v202, 0x280, v177
	v_add_u32_e32 v203, 0x510, v185
	v_or_b32_e32 v204, 0x2c0, v177
	v_add_u32_e32 v205, 0x5a0, v185
	v_or_b32_e32 v206, 0x300, v177
	v_add_u32_e32 v207, 0x630, v185
	v_or_b32_e32 v208, 0x340, v177
	v_add_u32_e32 v209, 0x6c0, v185
	v_or_b32_e32 v210, 0x380, v177
	v_add_u32_e32 v211, 0x750, v185
	v_or_b32_e32 v212, 0x3c0, v177
	v_add_u32_e32 v213, 0x7e0, v185
	v_and_b32_e32 v244, 31, v238
	v_lshlrev_b32_e32 v244, 1, v244
	v_xor_b32_e32 v245, 4, v244
	v_sub_u32_e32 v245, v245, v244
	v_xor_b32_e32 v246, 8, v244
	v_sub_u32_e32 v246, v246, v244
	v_xor_b32_e32 v247, 12, v244
	v_sub_u32_e32 v247, v247, v244
	v_add_u32_e32 v186, v186, v245
	v_add_u32_e32 v188, v188, v245
	v_add_u32_e32 v190, v190, v246
	v_add_u32_e32 v192, v192, v246
	v_add_u32_e32 v194, v194, v247
	v_add_u32_e32 v196, v196, v247
	v_add_u32_e32 v202, v202, v245
	v_add_u32_e32 v204, v204, v245
	v_add_u32_e32 v206, v206, v246
	v_add_u32_e32 v208, v208, v246
	v_add_u32_e32 v210, v210, v247
	v_add_u32_e32 v212, v212, v247
	v_cmp_lt_u32_e64 s[10:11], v122, v63
	v_cmp_lt_u32_e64 s[12:13], v63, v122
	v_cndmask_b32_e64 v219, 0, 1.0, vcc
	v_add_u32_e32 v223, 0x280, v222
	v_add_u32_e32 v224, 0x500, v222
	v_add_u32_e32 v225, 0x780, v222
	v_add_u32_e32 v228, 0xa00, v222
	v_add_u32_e32 v229, 0xc80, v222
	v_add_u32_e32 v230, 0xf00, v222
	v_add_u32_e32 v231, 0x1180, v222
	v_sub_u32_e32 v234, 0xdf, v172
	v_sub_u32_e32 v235, 0, v62
	s_mov_b32 s77, 64
	v_lshlrev_b64 v[140:141], 1, v[2:3]
	s_mov_b32 s26, 0
	v_mov_b64_e32 v[32:33], v[20:21]
	v_mov_b64_e32 v[28:29], v[20:21]
	v_mov_b64_e32 v[24:25], v[20:21]
	v_readlane_b32 s37, v255, 6
	v_readlane_b32 s38, v255, 7
	v_readlane_b32 s39, v255, 8
	v_readlane_b32 s40, v255, 9
	v_readlane_b32 s41, v255, 10
	v_readlane_b32 s42, v255, 11
	v_readlane_b32 s43, v255, 12
	v_readlane_b32 s44, v255, 13
	v_readlane_b32 s45, v255, 14
	v_readlane_b32 s46, v255, 15
	v_readlane_b32 s47, v255, 16
	v_readlane_b32 s48, v255, 17
	v_readlane_b32 s49, v255, 18
	v_readlane_b32 s50, v255, 19
	v_readlane_b32 s51, v255, 20
	s_waitcnt lgkmcnt(0)
	s_barrier
	s_andn2_b64 vcc, exec, s[24:25]
	s_mov_b64 s[28:29], -1
	s_cbranch_vccnz .LBB0_363
.LBB0_356:
	s_and_b32 s27, s26, 1
	v_lshl_add_u32 v0, s27, 13, v232
	ds_read2_b64 v[36:39], v0 offset1:32
	v_mad_u32_u24 v2, s27, v165, v233
	s_waitcnt lgkmcnt(0)
	v_pk_mul_f32 v[66:67], v[36:37], v[38:39]
	v_xor_b32_e32 v90, 16, v0
	ds_read2_b64 v[38:41], v90 offset0:64 offset1:96
	s_waitcnt lgkmcnt(0)
	v_pk_mul_f32 v[64:65], v[66:67], v[38:39]
	s_nop 0
	v_pk_mul_f32 v[60:61], v[64:65], v[40:41]
	v_xor_b32_e32 v91, 32, v0
	ds_read2_b64 v[38:41], v91 offset0:128 offset1:160
	s_waitcnt lgkmcnt(0)
	v_pk_mul_f32 v[54:55], v[60:61], v[38:39]
	s_nop 0
	v_pk_mul_f32 v[48:49], v[54:55], v[40:41]
	v_xor_b32_e32 v92, 48, v0
	ds_read2_b64 v[38:41], v92 offset0:192 offset1:224
	v_add_u32_e32 v0, 0x800, v0
	v_xor_b32_e32 v91, 32, v0
	ds_read2_b64 v[68:71], v91 offset0:128 offset1:160
	s_waitcnt lgkmcnt(1)
	v_pk_mul_f32 v[44:45], v[48:49], v[38:39]
	s_nop 0
	v_pk_mul_f32 v[38:39], v[44:45], v[40:41]
	ds_read2_b64 v[40:43], v0 offset1:32
	s_waitcnt lgkmcnt(0)
	v_pk_mul_f32 v[58:59], v[38:39], v[40:41]
	s_nop 0
	v_pk_mul_f32 v[50:51], v[58:59], v[42:43]
	v_xor_b32_e32 v90, 16, v0
	ds_read2_b64 v[40:43], v90 offset0:64 offset1:96
	s_waitcnt lgkmcnt(0)
	v_pk_mul_f32 v[46:47], v[50:51], v[40:41]
	s_nop 0
	v_pk_mul_f32 v[42:43], v[46:47], v[42:43]
	v_rcp_f32_e32 v40, v38
	v_pk_mul_f32 v[62:63], v[42:43], v[68:69]
	v_rcp_f32_e32 v41, v39
	v_pk_mul_f32 v[56:57], v[62:63], v[70:71]
	v_xor_b32_e32 v92, 48, v0
	ds_read2_b64 v[68:71], v92 offset0:192 offset1:224
	s_waitcnt lgkmcnt(0)
	v_pk_mul_f32 v[52:53], v[56:57], v[68:69]
	s_nop 0
	v_pk_mul_f32 v[0:1], v[52:53], v[70:71]
	s_and_saveexec_b64 s[28:29], s[4:5]
	s_cbranch_execz .LBB0_358
	v_lshl_add_u32 v253, v177, 1, v2
	ds_read2st64_b32 v[72:73], v253 offset0:96 offset1:112
	ds_read2st64_b32 v[68:69], v253 offset0:64 offset1:80
	v_lshl_add_u32 v74, v177, 1, v2
	s_nop 0
	ds_read_b32 v84, v74 offset:32768
	s_nop 0
	v_rcp_f32_e32 v70, v36
	v_rcp_f32_e32 v71, v37
	s_nop 0
	s_nop 0
	s_waitcnt lgkmcnt(2)
	v_cvt_f32_f16_e32 v78, v73
	v_cvt_f32_f16_sdwa v79, v73 dst_sel:DWORD dst_unused:UNUSED_PAD src0_sel:WORD_1
	v_lshl_add_u32 v253, v184, 1, v2
	ds_read2st64_b32 v[148:149], v253 offset0:64 offset1:80
	s_waitcnt lgkmcnt(2)
	v_cvt_f32_f16_e32 v74, v68
	v_cvt_f32_f16_sdwa v75, v68 dst_sel:DWORD dst_unused:UNUSED_PAD src0_sel:WORD_1
	v_cvt_f32_f16_e32 v76, v72
	ds_read2st64_b32 v[240:241], v253 offset0:96 offset1:112
	v_cvt_f32_f16_sdwa v77, v72 dst_sel:DWORD dst_unused:UNUSED_PAD src0_sel:WORD_1
	v_cvt_f32_f16_e32 v72, v69
	v_cvt_f32_f16_sdwa v73, v69 dst_sel:DWORD dst_unused:UNUSED_PAD src0_sel:WORD_1
	v_pk_mul_f32 v[78:79], v[36:37], v[78:79]
	v_pk_mul_f32 v[76:77], v[70:71], v[76:77]
	v_pk_mul_f32 v[70:71], v[70:71], v[74:75]
	v_pk_mul_f32 v[72:73], v[40:41], v[72:73]
	v_pk_mul_f32 v[74:75], v[40:41], v[78:79]
	v_cvt_pk_f16_f32 v68, v78, v79
	v_pk_mul_f32 v[80:81], v[38:39], v[76:77]
	v_pk_mul_f32 v[82:83], v[38:39], v[70:71]
	ds_write2st64_b32 v183, v69, v68 offset1:18
	v_cvt_pk_f16_f32 v68, v72, v73
	v_cvt_pk_f16_f32 v69, v74, v75
	v_pk_mul_f32 v[76:77], v[0:1], v[76:77]
	ds_write2st64_b32 v183, v68, v69 offset0:36 offset1:54
	v_cvt_pk_f16_f32 v68, v80, v81
	v_cvt_pk_f16_f32 v69, v82, v83
	ds_write2st64_b32 v183, v68, v69 offset0:72 offset1:90
	v_cvt_f16_f32_e32 v68, v76
	v_pk_mul_f32 v[70:71], v[0:1], v[70:71]
	v_cvt_f16_f32_e32 v69, v77
	v_cvt_f16_f32_e32 v70, v70
	v_cvt_f16_f32_e32 v71, v71
	ds_write_b16 v178, v68
	ds_write_b16 v178, v69 offset:40
	ds_write_b16 v178, v70 offset:5120
	ds_write_b16 v178, v71 offset:5160
	s_waitcnt lgkmcnt(9)
	ds_write_b16 v178, v84 offset:10240
	v_lshl_add_u32 v74, v184, 1, v2
	s_nop 0
	s_nop 0
	ds_read_b32 v82, v74 offset:32768
	v_rcp_f32_e32 v70, v66
	v_rcp_f32_e32 v71, v67
	s_waitcnt lgkmcnt(10)
	v_cvt_f32_f16_e32 v76, v149
	v_cvt_f32_f16_sdwa v77, v149 dst_sel:DWORD dst_unused:UNUSED_PAD src0_sel:WORD_1
	s_waitcnt lgkmcnt(9)
	v_cvt_f32_f16_e32 v80, v241
	v_cvt_f32_f16_sdwa v81, v241 dst_sel:DWORD dst_unused:UNUSED_PAD src0_sel:WORD_1
	v_lshl_add_u32 v253, v186, 1, v2
	ds_read2st64_b32 v[242:243], v253 offset0:64 offset1:80
	v_cvt_f32_f16_e32 v74, v148
	v_cvt_f32_f16_e32 v78, v240
	v_cvt_f32_f16_sdwa v79, v240 dst_sel:DWORD dst_unused:UNUSED_PAD src0_sel:WORD_1
	ds_read2st64_b32 v[240:241], v253 offset0:96 offset1:112
	v_cvt_f32_f16_sdwa v75, v148 dst_sel:DWORD dst_unused:UNUSED_PAD src0_sel:WORD_1
	v_pk_mul_f32 v[36:37], v[36:37], v[76:77]
	v_pk_mul_f32 v[68:69], v[66:67], v[80:81]
	v_pk_mul_f32 v[72:73], v[70:71], v[78:79]
	v_pk_mul_f32 v[70:71], v[70:71], v[74:75]
	v_pk_mul_f32 v[74:75], v[40:41], v[36:37]
	v_pk_mul_f32 v[76:77], v[40:41], v[68:69]
	v_cvt_pk_f16_f32 v36, v36, v37
	v_cvt_pk_f16_f32 v37, v68, v69
	v_pk_mul_f32 v[78:79], v[38:39], v[72:73]
	v_pk_mul_f32 v[80:81], v[38:39], v[70:71]
	ds_write2st64_b32 v185, v36, v37 offset1:18
	v_cvt_pk_f16_f32 v36, v74, v75
	v_cvt_pk_f16_f32 v37, v76, v77
	v_pk_mul_f32 v[72:73], v[0:1], v[72:73]
	ds_write2st64_b32 v185, v36, v37 offset0:36 offset1:54
	v_cvt_pk_f16_f32 v36, v78, v79
	v_cvt_pk_f16_f32 v37, v80, v81
	ds_write2st64_b32 v185, v36, v37 offset0:72 offset1:90
	v_cvt_f16_f32_e32 v36, v72
	v_pk_mul_f32 v[70:71], v[0:1], v[70:71]
	v_cvt_f16_f32_e32 v37, v73
	v_cvt_f16_f32_e32 v68, v70
	v_cvt_f16_f32_e32 v69, v71
	ds_write_b16 v178, v36 offset:2
	s_waitcnt lgkmcnt(14)
	ds_write_b16 v178, v37 offset:42
	s_waitcnt lgkmcnt(14)
	ds_write_b16 v178, v68 offset:5122
	s_waitcnt lgkmcnt(14)
	ds_write_b16 v178, v69 offset:5162
	s_waitcnt lgkmcnt(9)
	ds_write_b16 v178, v82 offset:10242
	v_lshl_add_u32 v72, v186, 1, v2
	s_nop 0
	s_nop 0
	ds_read_b32 v80, v72 offset:32768
	v_rcp_f32_e32 v68, v64
	v_rcp_f32_e32 v69, v65
	s_waitcnt lgkmcnt(10)
	v_cvt_f32_f16_e32 v74, v243
	v_cvt_f32_f16_sdwa v75, v243 dst_sel:DWORD dst_unused:UNUSED_PAD src0_sel:WORD_1
	s_waitcnt lgkmcnt(9)
	v_cvt_f32_f16_e32 v78, v241
	v_cvt_f32_f16_sdwa v79, v241 dst_sel:DWORD dst_unused:UNUSED_PAD src0_sel:WORD_1
	v_lshl_add_u32 v253, v188, 1, v2
	ds_read2st64_b32 v[148:149], v253 offset0:64 offset1:80
	v_cvt_f32_f16_e32 v72, v242
	v_cvt_f32_f16_e32 v76, v240
	v_cvt_f32_f16_sdwa v77, v240 dst_sel:DWORD dst_unused:UNUSED_PAD src0_sel:WORD_1
	ds_read2st64_b32 v[240:241], v253 offset0:96 offset1:112
	v_cvt_f32_f16_sdwa v73, v242 dst_sel:DWORD dst_unused:UNUSED_PAD src0_sel:WORD_1
	v_pk_mul_f32 v[36:37], v[66:67], v[74:75]
	v_pk_mul_f32 v[66:67], v[64:65], v[78:79]
	v_pk_mul_f32 v[70:71], v[68:69], v[76:77]
	v_pk_mul_f32 v[68:69], v[68:69], v[72:73]
	v_pk_mul_f32 v[72:73], v[40:41], v[36:37]
	v_pk_mul_f32 v[74:75], v[40:41], v[66:67]
	v_cvt_pk_f16_f32 v36, v36, v37
	v_cvt_pk_f16_f32 v37, v66, v67
	v_pk_mul_f32 v[76:77], v[38:39], v[70:71]
	v_pk_mul_f32 v[78:79], v[38:39], v[68:69]
	ds_write2st64_b32 v187, v36, v37 offset1:18
	v_cvt_pk_f16_f32 v36, v72, v73
	v_cvt_pk_f16_f32 v37, v74, v75
	v_pk_mul_f32 v[70:71], v[0:1], v[70:71]
	ds_write2st64_b32 v187, v36, v37 offset0:36 offset1:54
	v_cvt_pk_f16_f32 v36, v76, v77
	v_cvt_pk_f16_f32 v37, v78, v79
	ds_write2st64_b32 v187, v36, v37 offset0:72 offset1:90
	v_cvt_f16_f32_e32 v36, v70
	v_pk_mul_f32 v[68:69], v[0:1], v[68:69]
	v_cvt_f16_f32_e32 v37, v71
	v_cvt_f16_f32_e32 v66, v68
	v_cvt_f16_f32_e32 v67, v69
	ds_write_b16 v178, v36 offset:4
	s_waitcnt lgkmcnt(14)
	ds_write_b16 v178, v37 offset:44
	s_waitcnt lgkmcnt(14)
	ds_write_b16 v178, v66 offset:5124
	s_waitcnt lgkmcnt(14)
	ds_write_b16 v178, v67 offset:5164
	s_waitcnt lgkmcnt(9)
	ds_write_b16 v178, v80 offset:10244
	v_lshl_add_u32 v70, v188, 1, v2
	s_nop 0
	s_nop 0
	ds_read_b32 v78, v70 offset:32768
	v_rcp_f32_e32 v66, v60
	v_rcp_f32_e32 v67, v61
	s_waitcnt lgkmcnt(10)
	v_cvt_f32_f16_e32 v72, v149
	v_cvt_f32_f16_sdwa v73, v149 dst_sel:DWORD dst_unused:UNUSED_PAD src0_sel:WORD_1
	s_waitcnt lgkmcnt(9)
	v_cvt_f32_f16_e32 v76, v241
	v_cvt_f32_f16_sdwa v77, v241 dst_sel:DWORD dst_unused:UNUSED_PAD src0_sel:WORD_1
	v_cvt_f32_f16_e32 v70, v148
	v_cvt_f32_f16_e32 v74, v240
	v_cvt_f32_f16_sdwa v75, v240 dst_sel:DWORD dst_unused:UNUSED_PAD src0_sel:WORD_1
	v_cvt_f32_f16_sdwa v71, v148 dst_sel:DWORD dst_unused:UNUSED_PAD src0_sel:WORD_1
	v_pk_mul_f32 v[36:37], v[64:65], v[72:73]
	v_pk_mul_f32 v[64:65], v[60:61], v[76:77]
	v_pk_mul_f32 v[68:69], v[66:67], v[74:75]
	v_pk_mul_f32 v[66:67], v[66:67], v[70:71]
	v_pk_mul_f32 v[70:71], v[40:41], v[36:37]
	v_pk_mul_f32 v[72:73], v[40:41], v[64:65]
	v_cvt_pk_f16_f32 v36, v36, v37
	v_cvt_pk_f16_f32 v37, v64, v65
	v_pk_mul_f32 v[74:75], v[38:39], v[68:69]
	v_pk_mul_f32 v[76:77], v[38:39], v[66:67]
	ds_write2st64_b32 v189, v36, v37 offset1:18
	v_cvt_pk_f16_f32 v36, v70, v71
	v_cvt_pk_f16_f32 v37, v72, v73
	v_pk_mul_f32 v[68:69], v[0:1], v[68:69]
	ds_write2st64_b32 v189, v36, v37 offset0:36 offset1:54
	v_cvt_pk_f16_f32 v36, v74, v75
	v_cvt_pk_f16_f32 v37, v76, v77
	ds_write2st64_b32 v189, v36, v37 offset0:72 offset1:90
	v_cvt_f16_f32_e32 v36, v68
	v_pk_mul_f32 v[66:67], v[0:1], v[66:67]
	v_cvt_f16_f32_e32 v37, v69
	v_cvt_f16_f32_e32 v64, v66
	v_cvt_f16_f32_e32 v65, v67
	ds_write_b16 v178, v36 offset:6
	ds_write_b16 v178, v37 offset:46
	ds_write_b16 v178, v64 offset:5126
	s_waitcnt lgkmcnt(14)
	ds_write_b16 v178, v65 offset:5166
	s_nop 0
	s_waitcnt lgkmcnt(7)
	ds_write_b16 v178, v78 offset:10246
	v_perm_b32 v36, v82, v84, s82
	v_perm_b32 v37, v78, v80, s82
	ds_write_b64 v178, v[36:37] offset:10280

.LBB0_448:
	s_mov_b64 s[66:67], s[50:51]
	s_mov_b64 s[64:65], s[48:49]
	s_mov_b64 s[62:63], s[46:47]
	s_mov_b64 s[60:61], s[44:45]
	s_mov_b64 s[58:59], s[42:43]
	s_mov_b64 s[56:57], s[40:41]
	s_mov_b64 s[54:55], s[38:39]
	s_mov_b64 s[52:53], s[36:37]
	v_readlane_b32 s36, v254, 21
	v_readlane_b32 s48, v254, 33
	v_readlane_b32 s49, v254, 34
	s_mov_b32 s6, 0xc0000
	s_waitcnt vmcnt(1)
	v_lshl_add_u32 v151, v21, 11, v168
	v_mov_b64_e32 v[22:23], s[48:49]
	v_mad_u64_u32 v[58:59], s[6:7], v20, s6, v[22:23]
	v_readlane_b32 s38, v254, 23
	v_readlane_b32 s39, v254, 24
	v_readlane_b32 s44, v254, 29
	v_readlane_b32 s45, v254, 30
	v_readlane_b32 s46, v254, 31
	v_readlane_b32 s47, v254, 32
	s_andn2_b64 vcc, exec, s[4:5]
	v_cmp_gt_u32_e64 s[6:7], 8, v74
	v_cmp_eq_u32_e64 s[4:5], v78, v79
	v_readlane_b32 s37, v254, 22
	v_readlane_b32 s40, v254, 25
	v_readlane_b32 s41, v254, 26
	v_readlane_b32 s42, v254, 27
	v_readlane_b32 s43, v254, 28
	v_readlane_b32 s50, v254, 35
	v_readlane_b32 s51, v254, 36
	s_cbranch_vccnz .LBB0_452
	s_lshl_b32 s9, s9, 3
	v_or_b32_e32 v150, s9, v79
	v_bitop3_b32 v2, s9, v169, v79 bitop3:0x36
	v_cndmask_b32_e64 v2, v2, v150, s[2:3]
	v_or_b32_e32 v57, v2, v151
	v_mov_b64_e32 v[20:21], s[38:39]
	v_mad_i64_i32 v[34:35], s[10:11], v57, s87, v[20:21]
	v_mov_b32_e32 v45, v3
	v_lshl_add_u64 v[22:23], v[34:35], 0, v[44:45]
	v_add_co_u32_e32 v36, vcc, 0x3000, v22
	v_lshlrev_b32_e32 v2, 1, v81
	s_nop 0
	v_addc_co_u32_e32 v37, vcc, 0, v23, vcc
	global_load_dwordx4 v[22:25], v[36:37], off offset:1568
	global_load_dwordx4 v[26:29], v[36:37], off offset:1632
	v_or_b32_e32 v61, v77, v82
	v_add3_u32 v2, 0, v44, v2
	v_or_b32_e32 v46, v61, v80
	v_add_u32_e32 v83, 0xe000, v2
	v_or_b32_e32 v38, 16, v46
	ds_read_b128 v[30:33], v2 offset:57344
	ds_read_b128 v[52:55], v2 offset:57408
	ds_read_b128 v[84:87], v2 offset:59648
	ds_read_b128 v[88:91], v2 offset:59712
	ds_read_b128 v[92:95], v83 offset:9216
	ds_read_b128 v[96:99], v83 offset:9280
	global_load_dwordx4 v[40:43], v[36:37], off offset:1696
	v_ashrrev_i32_e32 v47, 31, v46
	v_ashrrev_i32_e32 v39, 31, v38
	s_mov_b64 s[12:13], 0x1e20
	s_mov_b64 s[14:15], 0x2420
	s_mov_b64 s[16:17], 0x2a20
	v_lshlrev_b64 v[50:51], 1, v[46:47]
	v_lshlrev_b64 v[48:49], 1, v[38:39]
	v_lshl_add_u64 v[38:39], v[34:35], 0, s[12:13]
	v_lshl_add_u64 v[62:63], v[34:35], 0, s[14:15]
	v_lshl_add_u64 v[34:35], v[34:35], 0, s[16:17]
	v_lshl_add_u64 v[64:65], v[38:39], 0, v[50:51]
	v_lshl_add_u64 v[68:69], v[62:63], 0, v[50:51]
	v_lshl_add_u64 v[72:73], v[34:35], 0, v[50:51]
	v_lshl_add_u64 v[38:39], v[38:39], 0, v[48:49]
	v_lshl_add_u64 v[100:101], v[62:63], 0, v[48:49]
	v_lshl_add_u64 v[34:35], v[34:35], 0, v[48:49]
	global_load_dwordx2 v[66:67], v[64:65], off
	global_load_dwordx2 v[70:71], v[68:69], off
	s_nop 0
	global_load_dwordx2 v[68:69], v[72:73], off
	global_load_dwordx2 v[62:63], v[38:39], off
	s_nop 0
	global_load_dwordx2 v[72:73], v[100:101], off
	global_load_dwordx2 v[64:65], v[34:35], off
	s_nop 0
	global_load_dwordx4 v[36:39], v[36:37], off offset:1760
	v_readlane_b32 s36, v254, 53
	v_readlane_b32 s37, v254, 54
	v_readlane_b32 s38, v254, 55
	v_readlane_b32 s39, v254, 56
	v_lshlrev_b64 v[46:47], 2, v[46:47]
	v_readlane_b32 s42, v254, 59
	v_readlane_b32 s43, v254, 60
	s_mov_b64 s[22:23], s[42:43]
	v_readlane_b32 s46, v254, 63
	v_readlane_b32 s47, v255, 0
	v_readlane_b32 s48, v255, 1
	v_readlane_b32 s49, v255, 2
	v_readlane_b32 s50, v255, 3
	v_readlane_b32 s51, v255, 4
	s_mov_b64 s[28:29], s[48:49]
	s_mov_b64 s[26:27], s[46:47]
	s_mov_b64 s[30:31], s[50:51]
	v_lshl_add_u64 v[148:149], s[30:31], 0, v[46:47]
	s_waitcnt vmcnt(10)
	v_lshl_or_b32 v152, v150, 6, v61
	v_bfe_u32 v246, v238, 1, 2
	v_lshlrev_b32_e32 v246, 2, v246
	v_xor_b32_e32 v152, v152, v246
	v_lshl_add_u32 v61, v152, 2, 0
	s_mov_b64 s[72:73], 0x2420
	s_mov_b64 s[74:75], 0x2a20
	v_readlane_b32 s40, v254, 57
	v_readlane_b32 s41, v254, 58
	v_readlane_b32 s44, v254, 61
	v_readlane_b32 s45, v254, 62
	s_waitcnt vmcnt(9)
	v_cndmask_b32_e64 v22, v24, v22, s[6:7]
	v_cndmask_b32_e64 v23, v25, v23, s[6:7]
	s_waitcnt vmcnt(8)
	v_cndmask_b32_e64 v24, v28, v26, s[6:7]
	v_cvt_f32_f16_e32 v26, v22
	v_cvt_f32_f16_sdwa v22, v22 dst_sel:DWORD dst_unused:UNUSED_PAD src0_sel:WORD_1
	v_cndmask_b32_e64 v25, v29, v27, s[6:7]
	v_cvt_f32_f16_e32 v27, v23
	v_cvt_f32_f16_sdwa v23, v23 dst_sel:DWORD dst_unused:UNUSED_PAD src0_sel:WORD_1
	v_cvt_f32_f16_e32 v29, v25
	v_cvt_f32_f16_sdwa v25, v25 dst_sel:DWORD dst_unused:UNUSED_PAD src0_sel:WORD_1
	v_add_f32_e32 v26, v26, v26
	v_add_f32_e32 v22, v22, v22
	v_add_f32_e32 v23, v23, v23
	v_mul_f32_e32 v26, 0x3fb8aa3b, v26
	v_mul_f32_e32 v22, 0x3fb8aa3b, v22
	v_cvt_f32_f16_e32 v28, v24
	v_cvt_f32_f16_sdwa v24, v24 dst_sel:DWORD dst_unused:UNUSED_PAD src0_sel:WORD_1
	v_mul_f32_e32 v23, 0x3fb8aa3b, v23
	v_exp_f32_e32 v26, v26
	v_exp_f32_e32 v22, v22
	v_exp_f32_e32 v23, v23
	v_add_f32_e32 v25, v25, v25
	v_add_f32_e32 v27, v27, v27
	v_mul_f32_e32 v25, 0x3fb8aa3b, v25
	v_add_f32_e32 v24, v24, v24
	v_mul_f32_e32 v27, 0x3fb8aa3b, v27
	v_exp_f32_e32 v34, v25
	v_add_f32_e32 v25, 1.0, v26
	v_add_f32_e32 v26, 1.0, v22
	v_mul_f32_e32 v24, 0x3fb8aa3b, v24
	v_exp_f32_e32 v27, v27
	v_add_f32_e32 v35, 1.0, v23
	v_rcp_f32_e32 v22, v25
	v_rcp_f32_e32 v23, v26
	v_add_f32_e32 v28, v28, v28
	v_add_f32_e32 v29, v29, v29
	v_exp_f32_e32 v24, v24
	v_mul_f32_e32 v28, 0x3fb8aa3b, v28
	v_mul_f32_e32 v29, 0x3fb8aa3b, v29
	v_exp_f32_e32 v28, v28
	v_exp_f32_e32 v29, v29
	v_add_f32_e32 v27, 1.0, v27
	v_pk_fma_f32 v[22:23], v[22:23], 2.0, 1.0 op_sel_hi:[1,0,0] neg_lo:[1,0,0] neg_hi:[1,0,0]
	v_add_f32_e32 v100, 1.0, v24
	v_rcp_f32_e32 v24, v27
	v_rcp_f32_e32 v25, v35
	v_cvt_pk_f16_f32 v22, v22, v23
	v_add_f32_e32 v28, 1.0, v28
	v_add_f32_e32 v29, 1.0, v29
	v_mov_b32_dpp v23, v22 row_ror:8 row_mask:0xf bank_mask:0xf bound_ctrl:1
	v_rcp_f32_e32 v27, v100
	v_cndmask_b32_e64 v100, v23, v22, s[6:7]
	v_cndmask_b32_e64 v102, v22, v23, s[6:7]
	v_add_f32_e32 v23, 1.0, v34
	v_rcp_f32_e32 v26, v28
	v_rcp_f32_e32 v22, v29
	v_rcp_f32_e32 v23, v23
	v_pk_fma_f32 v[24:25], v[24:25], 2.0, 1.0 op_sel_hi:[1,0,0] neg_lo:[1,0,0] neg_hi:[1,0,0]
	v_pk_fma_f32 v[22:23], v[22:23], 2.0, 1.0 op_sel_hi:[1,0,0] neg_lo:[1,0,0] neg_hi:[1,0,0]
	v_cvt_pk_f16_f32 v24, v24, v25
	v_cvt_pk_f16_f32 v35, v22, v23
	s_nop 0
	v_mov_b32_dpp v25, v24 row_ror:8 row_mask:0xf bank_mask:0xf bound_ctrl:1
	v_cndmask_b32_e64 v101, v25, v24, s[6:7]
	v_cndmask_b32_e64 v103, v24, v25, s[6:7]
	v_pk_fma_f32 v[24:25], v[26:27], 2.0, 1.0 op_sel_hi:[1,0,0] neg_lo:[1,0,0] neg_hi:[1,0,0]
	s_waitcnt vmcnt(7) lgkmcnt(1)
	v_mfma_f32_16x16x32_f16 v[26:29], v[92:95], v[40:43], 0
	v_cvt_pk_f16_f32 v34, v24, v25
	v_mfma_f32_16x16x32_f16 v[22:25], v[30:33], v[100:103], 0
	s_nop 0
	v_mov_b32_dpp v30, v34 row_ror:8 row_mask:0xf bank_mask:0xf bound_ctrl:1
	v_mov_b32_dpp v31, v35 row_ror:8 row_mask:0xf bank_mask:0xf bound_ctrl:1
	v_cndmask_b32_e64 v104, v30, v34, s[6:7]
	v_cndmask_b32_e64 v105, v31, v35, s[6:7]
	v_cndmask_b32_e64 v106, v34, v30, s[6:7]
	v_cndmask_b32_e64 v107, v35, v31, s[6:7]
	v_bitop3_b32 v34, s9, v164, v79 bitop3:0x36
	v_add_u32_e32 v34, 0x800, v34
	v_mfma_f32_16x16x32_f16 v[52:55], v[52:55], v[104:107], v[22:25]
	s_nop 2
	ds_read_b128 v[22:25], v83 offset:11520
	ds_read_b128 v[30:33], v83 offset:11584
	ds_read_b128 v[92:95], v2 offset:61952
	ds_read_b128 v[108:111], v2 offset:62016
	ds_read_b128 v[112:115], v83 offset:13824
	ds_read_b128 v[116:119], v83 offset:13888
	ds_read_b128 v[120:123], v2 offset:64256
	ds_read_b128 v[124:127], v2 offset:64320
	v_or_b32_e32 v2, 32, v150
	s_waitcnt vmcnt(0) lgkmcnt(8)
	v_mfma_f32_16x16x32_f16 v[96:99], v[96:99], v[36:39], v[26:29]
	v_cndmask_b32_e64 v2, v34, v2, s[2:3]
	v_or_b32_e32 v2, v2, v151
	v_mad_i64_i32 v[136:137], s[10:11], v2, s87, v[20:21]
	v_mfma_f32_16x16x32_f16 v[26:29], v[84:87], v[100:103], 0
	v_lshl_add_u64 v[20:21], v[136:137], 0, v[44:45]
	s_movk_i32 s9, 0x3000
	v_lshl_add_u64 v[44:45], v[136:137], 0, s[12:13]
	s_waitcnt lgkmcnt(5)
	v_mfma_f32_16x16x32_f16 v[92:95], v[92:95], v[100:103], 0
	v_lshl_add_u64 v[140:141], v[136:137], 0, s[14:15]
	ds_read_b128 v[84:87], v83 offset:16128
	ds_read_b128 v[128:131], v83 offset:16192
	v_lshl_add_u64 v[142:143], v[136:137], 0, s[16:17]
	v_mfma_f32_16x16x32_f16 v[22:25], v[22:25], v[40:43], 0
	v_lshl_add_u64 v[144:145], v[44:45], 0, v[50:51]
	v_lshl_add_u64 v[44:45], v[44:45], 0, v[48:49]
	s_mov_b64 s[16:17], s[36:37]
	s_waitcnt lgkmcnt(5)
	v_mfma_f32_16x16x32_f16 v[112:115], v[112:115], v[40:43], 0
	v_lshlrev_b32_e32 v2, 2, v56
	s_mov_b64 s[18:19], s[38:39]
	v_mfma_f32_16x16x32_f16 v[88:91], v[88:91], v[104:107], v[26:29]
	s_nop 2
	v_add_co_u32_e32 v28, vcc, s9, v20
	v_mfma_f32_16x16x32_f16 v[92:95], v[108:111], v[104:107], v[92:95]
	s_nop 0
	v_addc_co_u32_e32 v29, vcc, 0, v21, vcc
	v_lshl_add_u64 v[108:109], v[140:141], 0, v[50:51]
	v_mfma_f32_16x16x32_f16 v[132:135], v[30:33], v[36:39], v[22:25]
	s_nop 2
	global_load_dwordx4 v[20:23], v[28:29], off offset:1568
	global_load_dwordx4 v[24:27], v[28:29], off offset:1632
	global_load_dwordx4 v[32:35], v[28:29], off offset:1696
	s_nop 0
	global_load_dwordx4 v[28:31], v[28:29], off offset:1760
	v_lshl_add_u64 v[50:51], v[142:143], 0, v[50:51]
	s_waitcnt lgkmcnt(4)
	v_mfma_f32_16x16x32_f16 v[136:139], v[116:119], v[36:39], v[112:115]
	s_nop 2
	global_load_dwordx2 v[112:113], v[144:145], off
	global_load_dwordx2 v[116:117], v[108:109], off
	global_load_dwordx2 v[114:115], v[50:51], off
	s_nop 0
	global_load_dwordx2 v[108:109], v[44:45], off
	v_lshl_add_u64 v[44:45], v[140:141], 0, v[48:49]
	v_lshl_add_u64 v[48:49], v[142:143], 0, v[48:49]
	global_load_dwordx2 v[118:119], v[44:45], off
	global_load_dwordx2 v[110:111], v[48:49], off
	v_lshl_add_u64 v[44:45], s[18:19], 0, v[2:3]
	s_waitcnt lgkmcnt(3)
	v_mfma_f32_16x16x32_f16 v[100:103], v[120:123], v[100:103], 0
	v_lshl_add_u64 v[44:45], v[44:45], 0, v[46:47]
	s_waitcnt lgkmcnt(0)
	s_barrier
	v_mfma_f32_16x16x32_f16 v[40:43], v[84:87], v[40:43], 0
	global_load_dwordx4 v[84:87], v[44:45], off
	v_lshl_add_u64 v[48:49], s[22:23], 0, v[2:3]
	v_lshl_add_u64 v[48:49], v[48:49], 0, v[46:47]
	v_mfma_f32_16x16x32_f16 v[100:103], v[124:127], v[104:107], v[100:103]
	global_load_dwordx4 v[104:107], v[48:49], off
	global_load_dwordx4 v[120:123], v[44:45], off offset:64
	v_cndmask_b32_e64 v2, v95, v55, s[6:7]
	v_cndmask_b32_e64 v52, v92, v52, s[6:7]
	v_mfma_f32_16x16x32_f16 v[124:127], v[128:131], v[36:39], v[40:43]
	v_lshl_add_u64 v[36:37], s[26:27], 0, v[46:47]
	v_lshl_add_u64 v[38:39], s[28:29], 0, v[46:47]
	global_load_dwordx4 v[128:131], v[48:49], off offset:64
	global_load_dwordx4 v[140:143], v[36:37], off
	global_load_dwordx4 v[144:147], v[36:37], off offset:64
	s_nop 0
	global_load_dwordx4 v[48:51], v[38:39], off
	global_load_dwordx4 v[40:43], v[38:39], off offset:64
	global_load_dwordx4 v[44:47], v[148:149], off
	s_nop 0
	global_load_dwordx4 v[36:39], v[148:149], off offset:64
	v_cndmask_b32_e64 v55, v139, v99, s[6:7]
	v_cndmask_b32_e64 v53, v93, v53, s[6:7]
	v_cndmask_b32_e64 v54, v94, v54, s[6:7]
	v_cndmask_b32_e64 v92, v136, v96, s[6:7]
	v_cndmask_b32_e64 v83, v138, v98, s[6:7]
	v_cmp_lt_i32_e32 vcc, v157, v158
	v_cvt_f32_f16_e32 v136, v66
	v_cvt_f32_f16_sdwa v138, v67 dst_sel:DWORD dst_unused:UNUSED_PAD src0_sel:WORD_1
	s_waitcnt vmcnt(9)
	v_add_f32_e32 v2, v2, v87
	v_add_f32_e32 v52, v52, v84
	v_cndmask_b32_e64 v84, v137, v97, s[6:7]
	v_mul_f32_e32 v2, 0xbfb8aa3b, v2
	s_waitcnt vmcnt(8)
	v_add_f32_e32 v84, v84, v105
	v_exp_f32_e32 v2, v2
	v_mul_f32_e32 v84, 0xbfb8aa3b, v84
	v_exp_f32_e32 v84, v84
	v_add_f32_e32 v55, v55, v107
	v_add_f32_e32 v2, 1.0, v2
	v_rcp_f32_e32 v2, v2
	v_add_f32_e32 v84, 1.0, v84
	v_mul_f32_e32 v55, 0xbfb8aa3b, v55
	v_rcp_f32_e32 v93, v84
	v_exp_f32_e32 v84, v55
	v_mul_f32_e32 v2, 0xbf1b4598, v2
	v_mul_f32_e32 v2, 0x3fb8aa3b, v2
	v_exp_f32_e32 v55, v2
	v_add_f32_e32 v2, 1.0, v84
	v_rcp_f32_e32 v95, v2
	v_cndmask_b32_e64 v2, v103, v91, s[6:7]
	v_add_f32_e32 v54, v54, v86
	v_cndmask_b32_e64 v86, v102, v90, s[6:7]
	s_waitcnt vmcnt(7)
	v_add_f32_e32 v2, v2, v123
	v_add_f32_e32 v86, v86, v122
	v_mul_f32_e32 v2, 0xbfb8aa3b, v2
	v_mul_f32_e32 v86, 0xbfb8aa3b, v86
	v_exp_f32_e32 v2, v2
	v_exp_f32_e32 v86, v86
	v_add_f32_e32 v92, v92, v104
	v_mul_f32_e32 v92, 0xbfb8aa3b, v92
	v_cndmask_b32_e64 v87, v127, v135, s[6:7]
	v_add_f32_e32 v2, 1.0, v2
	v_exp_f32_e32 v92, v92
	v_cndmask_b32_e64 v84, v100, v88, s[6:7]
	v_cndmask_b32_e64 v100, v126, v134, s[6:7]
	v_cvt_f32_f16_e32 v90, v72
	v_cvt_f32_f16_sdwa v91, v72 dst_sel:DWORD dst_unused:UNUSED_PAD src0_sel:WORD_1
	v_add_f32_e32 v72, 1.0, v86
	v_rcp_f32_e32 v2, v2
	s_waitcnt vmcnt(6)
	v_add_f32_e32 v87, v87, v131
	v_rcp_f32_e32 v72, v72
	v_add_f32_e32 v86, v100, v130
	v_mul_f32_e32 v87, 0xbfb8aa3b, v87
	v_add_f32_e32 v83, v83, v106
	v_mul_f32_e32 v86, 0xbfb8aa3b, v86
	v_exp_f32_e32 v102, v87
	v_cvt_f32_f16_e32 v106, v70
	v_cvt_f32_f16_sdwa v107, v70 dst_sel:DWORD dst_unused:UNUSED_PAD src0_sel:WORD_1
	v_exp_f32_e32 v100, v86
	v_cvt_f32_f16_e32 v70, v71
	v_cvt_f32_f16_sdwa v71, v71 dst_sel:DWORD dst_unused:UNUSED_PAD src0_sel:WORD_1
	v_add_f32_e32 v53, v53, v85
	v_add_f32_e32 v85, 1.0, v92
	v_mul_f32_e32 v2, 0xbf1b4598, v2
	v_rcp_f32_e32 v92, v85
	v_cndmask_b32_e64 v85, v101, v89, s[6:7]
	v_mul_f32_e32 v72, 0xbf1b4598, v72
	v_mul_f32_e32 v2, 0x3fb8aa3b, v2
	v_add_f32_e32 v84, v84, v120
	v_add_f32_e32 v85, v85, v121
	v_mul_f32_e32 v72, 0x3fb8aa3b, v72
	v_exp_f32_e32 v87, v2
	v_add_f32_e32 v2, 1.0, v102
	s_waitcnt vmcnt(5)
	v_pk_mul_f32 v[120:121], v[140:141], v[106:107]
	v_cndmask_b32_e64 v89, v125, v133, s[6:7]
	v_cndmask_b32_e64 v88, v124, v132, s[6:7]
	v_exp_f32_e32 v86, v72
	v_add_f32_e32 v72, 1.0, v100
	v_cvt_f32_f16_e32 v100, v73
	v_cvt_f32_f16_sdwa v101, v73 dst_sel:DWORD dst_unused:UNUSED_PAD src0_sel:WORD_1
	v_rcp_f32_e32 v73, v2
	v_cndmask_b32_e32 v2, v156, v157, vcc
	v_pk_mul_f32 v[122:123], v[120:121], v[120:121]
	v_pk_mul_f32 v[124:125], v[142:143], v[70:71]
	v_lshlrev_b32_e32 v132, 2, v2
	v_pk_mul_f32 v[126:127], v[124:125], v[124:125]
	v_add_f32_e32 v2, v122, v123
	s_waitcnt vmcnt(4)
	v_pk_mul_f32 v[96:97], v[144:145], v[90:91]
	v_add_f32_e32 v2, v126, v2
	v_pk_mul_f32 v[98:99], v[96:97], v[96:97]
	v_add_f32_e32 v2, v127, v2
	v_pk_mul_f32 v[102:103], v[146:147], v[100:101]
	v_add_f32_e32 v2, v2, v98
	v_pk_mul_f32 v[104:105], v[102:103], v[102:103]
	v_add_f32_e32 v2, v99, v2
	v_add_f32_e32 v2, v104, v2
	v_add_f32_e32 v2, v105, v2
	v_cmp_lt_i32_e32 vcc, v159, v158
	v_mul_f32_e32 v52, 0xbfb8aa3b, v52
	v_add_f32_dpp v2, v2, v2 row_ror:8 row_mask:0xf bank_mask:0xf bound_ctrl:1
	ds_bpermute_b32 v104, v132, v2
	v_cndmask_b32_e32 v98, v156, v159, vcc
	v_lshlrev_b32_e32 v122, 2, v98
	v_mul_f32_e32 v53, 0xbfb8aa3b, v53
	v_mul_f32_e32 v54, 0xbfb8aa3b, v54
	s_waitcnt lgkmcnt(0)
	v_add_f32_e32 v2, v2, v104
	ds_bpermute_b32 v104, v122, v2
	v_exp_f32_e32 v52, v52
	v_exp_f32_e32 v53, v53
	v_exp_f32_e32 v54, v54
	v_mul_f32_e32 v83, 0xbfb8aa3b, v83
	v_exp_f32_e32 v83, v83
	s_waitcnt lgkmcnt(0)
	v_add_f32_e32 v2, v2, v104
	v_add_f32_e32 v52, 1.0, v52
	v_add_f32_e32 v53, 1.0, v53
	v_add_f32_e32 v54, 1.0, v54
	v_add_f32_e32 v88, v88, v128
	v_add_f32_e32 v89, v89, v129
	v_max_f32_e32 v2, 0x179abe15, v2
	v_rcp_f32_e32 v52, v52
	v_rcp_f32_e32 v53, v53
	v_rcp_f32_e32 v54, v54
	v_add_f32_e32 v83, 1.0, v83
	v_mul_f32_e32 v88, 0xbfb8aa3b, v88
	v_mul_f32_e32 v89, 0xbfb8aa3b, v89
	v_pk_add_f32 v[98:99], v[92:93], -1.0 op_sel_hi:[1,0]
	v_rsq_f32_e32 v2, v2
	v_rcp_f32_e32 v94, v83
	v_exp_f32_e32 v88, v88
	v_exp_f32_e32 v89, v89
	s_waitcnt vmcnt(3)
	v_pk_fma_f32 v[48:49], v[48:49], v[98:99], 1.0 op_sel_hi:[1,1,0]
	v_cvt_f32_f16_sdwa v137, v66 dst_sel:DWORD dst_unused:UNUSED_PAD src0_sel:WORD_1
	v_pk_mul_f32 v[48:49], v[48:49], v[106:107]
	v_mul_f32_e32 v52, 0xbf1b4598, v52
	v_mul_f32_e32 v98, v48, v136
	v_mul_f32_e32 v53, 0xbf1b4598, v53
	v_mul_f32_e32 v54, 0xbf1b4598, v54
	v_cvt_f32_f16_e32 v83, v67
	s_waitcnt vmcnt(1)
	v_fma_f32 v106, v44, v98, 0
	v_pk_mul_f32 v[98:99], v[124:125], v[2:3] op_sel_hi:[1,0]
	v_mul_f32_e32 v52, 0x3fb8aa3b, v52
	v_mul_f32_e32 v53, 0x3fb8aa3b, v53
	v_mul_f32_e32 v54, 0x3fb8aa3b, v54
	v_add_f32_e32 v88, 1.0, v88
	v_add_f32_e32 v89, 1.0, v89
	v_pk_mul_f32 v[104:105], v[94:95], v[98:99]
	v_pk_add_f32 v[94:95], v[94:95], -1.0 op_sel_hi:[1,0]
	v_exp_f32_e32 v52, v52
	v_exp_f32_e32 v53, v53
	v_exp_f32_e32 v54, v54
	v_rcp_f32_e32 v88, v88
	v_rcp_f32_e32 v89, v89
	v_pk_fma_f32 v[50:51], v[50:51], v[94:95], 1.0 op_sel_hi:[1,1,0]
	v_mul_f32_e32 v44, v49, v137
	v_pk_mul_f32 v[50:51], v[50:51], v[70:71]
	v_fmac_f32_e32 v106, v45, v44
	v_cvt_pk_f16_f32 v44, v48, v49
	v_pk_mul_f32 v[48:49], v[120:121], v[2:3] op_sel_hi:[1,0]
	v_mul_f32_e32 v45, v50, v83
	v_cvt_f32_f16_e32 v128, v62
	v_pk_mul_f32 v[92:93], v[92:93], v[48:49]
	v_mul_f32_e32 v70, v51, v138
	v_fmac_f32_e32 v106, v46, v45
	v_cvt_pk_f16_f32 v46, -v48, -v49
	v_lshlrev_b32_e32 v48, 1, v152
	v_cvt_f32_f16_sdwa v129, v62 dst_sel:DWORD dst_unused:UNUSED_PAD src0_sel:WORD_1
	v_fmac_f32_e32 v106, v47, v70
	v_cvt_pk_f16_f32 v45, v50, v51
	v_cvt_pk_f16_f32 v47, -v98, -v99
	ds_write_b128 v61, v[52:55]
	v_sub_u32_e32 v52, v61, v48
	v_pk_add_f32 v[50:51], v[88:89], -1.0 op_sel_hi:[1,0]
	v_rcp_f32_e32 v72, v72
	v_cvt_pk_f16_f32 v92, v92, v93
	v_cvt_pk_f16_f32 v93, v104, v105
	ds_write_b64 v52, v[46:47] offset:20480
	ds_write_b64 v52, v[92:93] offset:24576
	ds_write_b64 v52, v[66:67] offset:28672
	ds_write_b64 v52, v[68:69] offset:32768
	v_pk_mul_f32 v[46:47], v[96:97], v[2:3] op_sel_hi:[1,0]
	v_pk_fma_f32 v[40:41], v[40:41], v[50:51], 1.0 op_sel_hi:[1,1,0]
	v_pk_mul_f32 v[48:49], v[88:89], v[46:47]
	v_pk_mul_f32 v[40:41], v[40:41], v[90:91]
	v_cvt_pk_f16_f32 v48, v48, v49
	v_mul_f32_e32 v49, v40, v128
	v_cvt_f32_f16_e32 v130, v63
	v_mul_f32_e32 v50, v41, v129
	s_waitcnt vmcnt(0)
	v_fmac_f32_e32 v106, v36, v49
	v_cvt_f32_f16_sdwa v131, v63 dst_sel:DWORD dst_unused:UNUSED_PAD src0_sel:WORD_1
	v_fmac_f32_e32 v106, v37, v50
	v_pk_add_f32 v[36:37], v[72:73], -1.0 op_sel_hi:[1,0]
	v_mul_f32_e32 v84, 0xbfb8aa3b, v84
	v_pk_fma_f32 v[36:37], v[42:43], v[36:37], 1.0 op_sel_hi:[1,1,0]
	v_mul_f32_e32 v85, 0xbfb8aa3b, v85
	v_pk_mul_f32 v[42:43], v[36:37], v[100:101]
	v_exp_f32_e32 v84, v84
	v_exp_f32_e32 v85, v85
	v_mul_f32_e32 v36, v42, v130
	v_mul_f32_e32 v37, v43, v131
	v_fmac_f32_e32 v106, v38, v36
	v_fmac_f32_e32 v106, v39, v37
	v_add_f32_e32 v84, 1.0, v84
	v_add_f32_e32 v85, 1.0, v85
	v_add_f32_dpp v39, v106, v106 row_ror:8 row_mask:0xf bank_mask:0xf bound_ctrl:1
	ds_bpermute_b32 v50, v132, v39
	v_rcp_f32_e32 v84, v84
	v_rcp_f32_e32 v85, v85
	v_cvt_pk_f16_f32 v38, v40, v41
	v_pk_mul_f32 v[40:41], v[102:103], v[2:3] op_sel_hi:[1,0]
	v_mul_f32_e32 v84, 0xbf1b4598, v84
	v_mul_f32_e32 v85, 0xbf1b4598, v85
	v_pk_mul_f32 v[36:37], v[72:73], v[40:41]
	s_waitcnt lgkmcnt(0)
	v_add_f32_e32 v2, v39, v50
	v_mul_f32_e32 v84, 0x3fb8aa3b, v84
	v_mul_f32_e32 v85, 0x3fb8aa3b, v85
	v_cvt_pk_f16_f32 v49, v36, v37
	ds_bpermute_b32 v36, v122, v2
	v_exp_f32_e32 v84, v84
	v_exp_f32_e32 v85, v85
	v_cvt_pk_f16_f32 v39, v42, v43
	v_add_u32_e32 v37, 0x4000, v52
	v_cvt_pk_f16_f32 v41, -v40, -v41
	v_cvt_pk_f16_f32 v40, -v46, -v47
	ds_write_b128 v61, v[84:87] offset:64
	ds_write2_b64 v37, v[44:45], v[38:39] offset1:4
	ds_write_b64 v52, v[40:41] offset:20512
	ds_write_b64 v52, v[48:49] offset:24608
	ds_write_b64 v52, v[62:63] offset:28704
	ds_write_b64 v52, v[64:65] offset:32800
	s_and_saveexec_b64 s[6:7], s[4:5]
	s_cbranch_execz .LBB0_451
	s_waitcnt lgkmcnt(6)
	v_add_f32_e32 v2, v2, v36
	v_mad_i64_i32 v[36:37], s[4:5], v57, 48, v[58:59]
	v_lshl_add_u64 v[36:37], v[0:1], 2, v[36:37]
	global_store_dword v[36:37], v2, off

.LBB0_452:
	v_mov_b32_e32 v2, s47
	v_mov_b32_e32 v37, s45
	v_cndmask_b32_e64 v43, v2, v37, s[2:3]
	v_mov_b32_e32 v2, s46
	v_mov_b32_e32 v37, s44
	v_cndmask_b32_e64 v42, v2, v37, s[2:3]
	v_lshlrev_b32_e32 v2, 1, v76
	v_bfe_u32 v44, v76, 5, 1
	v_and_b32_e32 v45, 62, v2
	v_lshl_or_b32 v2, v44, 6, v45
	v_readlane_b32 s6, v255, 38
	v_lshlrev_b32_e32 v46, 2, v45
	v_readlane_b32 s7, v255, 39
	v_mad_u32_u24 v174, v2, 40, s6
	v_lshlrev_b32_e32 v2, 8, v44
	s_waitcnt vmcnt(0)
	v_lshlrev_b32_e32 v47, 1, v153
	v_add3_u32 v175, s7, v2, v46
	v_lshl_add_u32 v176, v153, 2, s7
	v_add_u32_e32 v48, s6, v47
	v_readlane_b32 s6, v255, 28
	v_ashrrev_i32_e32 v37, 31, v36
	v_readlane_b32 s7, v255, 29
	v_lshl_add_u64 v[42:43], v[36:37], 1, v[42:43]
	s_lshl_b32 s6, s8, 1
	s_mov_b32 s9, s7
	v_writelane_b32 v255, s8, 28
	v_lshl_add_u64 v[42:43], v[42:43], 0, s[6:7]
	v_lshlrev_b32_e32 v2, 1, v74
	v_writelane_b32 v255, s9, 29
	v_lshl_add_u64 v[122:123], v[42:43], 0, v[2:3]
	v_lshlrev_b32_e32 v2, 1, v120
	v_lshlrev_b32_e32 v42, 1, v40
	v_add3_u32 v177, 0, v2, v42
	v_lshl_add_u64 v[124:125], v[0:1], 2, v[58:59]
	v_mul_u32_u24_e32 v0, 0x900, v44
	v_lshlrev_b32_e32 v2, 1, v45
	v_readlane_b32 s26, v255, 40
	v_lshlrev_b32_e32 v1, 1, v38
	v_cmp_eq_u32_e32 vcc, v153, v74
	v_add3_u32 v179, s26, v0, v2
	v_lshl_or_b32 v0, v44, 4, 1
	v_or_b32_e32 v38, 1, v153
	v_lshlrev_b32_e32 v180, 6, v0
	v_mul_u32_u24_e32 v0, 0x90, v0
	v_cndmask_b32_e64 v211, 0, 1.0, vcc
	v_cmp_lt_u32_e64 s[14:15], v38, v74
	v_cmp_eq_u32_e32 vcc, v38, v74
	v_or_b32_e32 v38, 2, v153
	v_add3_u32 v181, s26, v0, v2
	v_add_u32_e32 v0, s26, v42
	v_cndmask_b32_e64 v212, 0, 1.0, vcc
	v_cmp_lt_u32_e64 s[16:17], v38, v74
	v_cmp_lt_u32_e64 s[18:19], v74, v38
	v_cmp_eq_u32_e32 vcc, v38, v74
	v_or_b32_e32 v38, 3, v153
	v_add_u32_e32 v210, v0, v1
	v_cndmask_b32_e64 v213, 0, 1.0, vcc
	v_cmp_lt_u32_e64 s[20:21], v38, v74
	v_cmp_lt_u32_e64 s[22:23], v74, v38
	v_cmp_eq_u32_e32 vcc, v38, v74
	v_add_u32_e32 v215, v0, v47
	v_or_b32_e32 v0, 16, v74
	v_mov_b32_e32 v38, s26
	v_or3_b32 v36, v36, v39, v153
	v_mad_u32_u24 v0, v0, s92, v38
	v_ashrrev_i32_e32 v37, 31, v36
	v_add_u32_e32 v221, v0, v1
	v_add_u32_e32 v222, v0, v47
	v_lshlrev_b32_e32 v0, 12, v44
	v_readlane_b32 s36, v254, 53
	v_or_b32_e32 v40, 16, v36
	v_add3_u32 v227, 0, v46, v0
	v_lshlrev_b64 v[0:1], 2, v[56:57]
	v_readlane_b32 s37, v254, 54
	v_readlane_b32 s38, v254, 55
	v_readlane_b32 s39, v254, 56
	v_readlane_b32 s40, v254, 57
	v_readlane_b32 s41, v254, 58
	v_readlane_b32 s42, v254, 59
	v_readlane_b32 s43, v254, 60
	v_readlane_b32 s44, v254, 61
	v_readlane_b32 s45, v254, 62
	v_readlane_b32 s46, v254, 63
	v_readlane_b32 s47, v255, 0
	v_readlane_b32 s48, v255, 1
	v_readlane_b32 s49, v255, 2
	v_readlane_b32 s50, v255, 3
	v_readlane_b32 s51, v255, 4
	v_lshlrev_b64 v[42:43], 2, v[36:37]
	v_bfe_u32 v172, v76, 6, 2
	v_lshlrev_b32_e32 v173, 10, v44
	v_ashrrev_i32_e32 v41, 31, v40
	v_mul_u32_u24_e32 v45, 40, v74
	v_mad_u32_u24 v217, v74, 40, v48
	v_lshl_add_u64 v[38:39], s[38:39], 0, v[0:1]
	v_lshl_add_u64 v[0:1], s[42:43], 0, v[0:1]
	v_lshl_add_u64 v[130:131], s[46:47], 0, v[42:43]
	v_lshl_add_u64 v[132:133], s[48:49], 0, v[42:43]
	v_lshl_add_u64 v[134:135], s[50:51], 0, v[42:43]
	s_mov_b64 s[36:37], s[52:53]
	s_mov_b32 s70, 0
	v_cmp_eq_u32_e64 s[4:5], 0, v172
	v_add_u32_e32 v178, 0xe000, v177
	v_cmp_gt_u32_e64 s[6:7], 8, v74
	v_cmp_eq_u32_e64 s[8:9], v78, v79
	v_or_b32_e32 v182, 0x80, v173
	v_add_u32_e32 v183, 0x90, v181
	v_or_b32_e32 v184, 0xc0, v173
	v_add_u32_e32 v185, 0x120, v181
	v_or_b32_e32 v186, 0x100, v173
	v_add_u32_e32 v187, 0x1b0, v181
	v_or_b32_e32 v188, 0x140, v173
	v_add_u32_e32 v189, 0x240, v181
	v_or_b32_e32 v190, 0x180, v173
	v_add_u32_e32 v191, 0x2d0, v181
	v_or_b32_e32 v192, 0x1c0, v173
	v_add_u32_e32 v193, 0x360, v181
	v_or_b32_e32 v194, 0x200, v173
	v_add_u32_e32 v195, 0x3f0, v181
	v_or_b32_e32 v196, 0x240, v173
	v_add_u32_e32 v197, 0x480, v181
	v_or_b32_e32 v198, 0x280, v173
	v_add_u32_e32 v199, 0x510, v181
	v_or_b32_e32 v200, 0x2c0, v173
	v_add_u32_e32 v201, 0x5a0, v181
	v_or_b32_e32 v202, 0x300, v173
	v_add_u32_e32 v203, 0x630, v181
	v_or_b32_e32 v204, 0x340, v173
	v_add_u32_e32 v205, 0x6c0, v181
	v_or_b32_e32 v206, 0x380, v173
	v_add_u32_e32 v207, 0x750, v181
	v_or_b32_e32 v208, 0x3c0, v173
	v_add_u32_e32 v209, 0x7e0, v181
	v_and_b32_e32 v244, 31, v238
	v_lshlrev_b32_e32 v244, 1, v244
	v_xor_b32_e32 v245, 4, v244
	v_sub_u32_e32 v245, v245, v244
	v_xor_b32_e32 v246, 8, v244
	v_sub_u32_e32 v246, v246, v244
	v_xor_b32_e32 v247, 12, v244
	v_sub_u32_e32 v247, v247, v244
	v_add_u32_e32 v182, v182, v245
	v_add_u32_e32 v184, v184, v245
	v_add_u32_e32 v186, v186, v246
	v_add_u32_e32 v188, v188, v246
	v_add_u32_e32 v190, v190, v247
	v_add_u32_e32 v192, v192, v247
	v_add_u32_e32 v198, v198, v245
	v_add_u32_e32 v200, v200, v245
	v_add_u32_e32 v202, v202, v246
	v_add_u32_e32 v204, v204, v246
	v_add_u32_e32 v206, v206, v247
	v_add_u32_e32 v208, v208, v247
	v_cmp_lt_u32_e64 s[10:11], v153, v74
	v_cmp_lt_u32_e64 s[12:13], v74, v153
	v_cndmask_b32_e64 v214, 0, 1.0, vcc
	v_mad_u32_u24 v216, v75, 40, v48
	v_add_u32_e32 v218, 0x280, v217
	v_add_u32_e32 v219, 0x500, v217
	v_add_u32_e32 v220, 0x780, v217
	v_add_u32_e32 v223, 0xa00, v217
	v_add_u32_e32 v224, 0xc80, v217
	v_add_u32_e32 v225, 0xf00, v217
	v_add_u32_e32 v226, 0x1180, v217
	v_lshl_add_u64 v[126:127], v[38:39], 0, v[42:43]
	v_lshl_add_u64 v[128:129], v[0:1], 0, v[42:43]
	v_add_u32_e32 v228, 0, v2
	v_sub_u32_e32 v229, 0x7df, v150
	v_sub_u32_e32 v230, 0, v77
	s_mov_b32 s71, 64
	v_add_u32_e32 v231, v48, v45
	v_lshlrev_b64 v[136:137], 1, v[36:37]
	v_lshlrev_b64 v[138:139], 1, v[40:41]
	s_mov_b32 s76, 0
	s_mov_b64 s[38:39], s[54:55]
	s_mov_b64 s[40:41], s[56:57]
	s_mov_b64 s[42:43], s[58:59]
	s_mov_b64 s[44:45], s[60:61]
	s_mov_b64 s[46:47], s[62:63]
	s_mov_b64 s[48:49], s[64:65]
	s_mov_b64 s[50:51], s[66:67]
	s_waitcnt lgkmcnt(0)
	s_barrier
	s_branch .LBB0_455

.LBB0_455:
	s_andn2_b64 vcc, exec, s[24:25]
	s_mov_b64 s[26:27], -1
	s_cbranch_vccnz .LBB0_463
	s_and_b32 s26, s76, 1
	v_lshl_add_u32 v0, s26, 13, v227
	ds_read2_b64 v[36:39], v0 offset1:32
	v_mad_u32_u24 v2, s26, v165, v228
	s_waitcnt lgkmcnt(0)
	v_pk_mul_f32 v[66:67], v[36:37], v[38:39]
	v_xor_b32_e32 v90, 16, v0
	ds_read2_b64 v[38:41], v90 offset0:64 offset1:96
	s_waitcnt lgkmcnt(0)
	v_pk_mul_f32 v[64:65], v[66:67], v[38:39]
	s_nop 0
	v_pk_mul_f32 v[60:61], v[64:65], v[40:41]
	v_xor_b32_e32 v91, 32, v0
	ds_read2_b64 v[38:41], v91 offset0:128 offset1:160
	s_waitcnt lgkmcnt(0)
	v_pk_mul_f32 v[54:55], v[60:61], v[38:39]
	s_nop 0
	v_pk_mul_f32 v[48:49], v[54:55], v[40:41]
	v_xor_b32_e32 v92, 48, v0
	ds_read2_b64 v[38:41], v92 offset0:192 offset1:224
	v_add_u32_e32 v0, 0x800, v0
	v_xor_b32_e32 v91, 32, v0
	ds_read2_b64 v[68:71], v91 offset0:128 offset1:160
	s_waitcnt lgkmcnt(1)
	v_pk_mul_f32 v[44:45], v[48:49], v[38:39]
	s_nop 0
	v_pk_mul_f32 v[38:39], v[44:45], v[40:41]
	ds_read2_b64 v[40:43], v0 offset1:32
	s_waitcnt lgkmcnt(0)
	v_pk_mul_f32 v[58:59], v[38:39], v[40:41]
	s_nop 0
	v_pk_mul_f32 v[50:51], v[58:59], v[42:43]
	v_xor_b32_e32 v90, 16, v0
	ds_read2_b64 v[40:43], v90 offset0:64 offset1:96
	s_waitcnt lgkmcnt(0)
	v_pk_mul_f32 v[46:47], v[50:51], v[40:41]
	s_nop 0
	v_pk_mul_f32 v[42:43], v[46:47], v[42:43]
	v_rcp_f32_e32 v40, v38
	v_pk_mul_f32 v[62:63], v[42:43], v[68:69]
	v_rcp_f32_e32 v41, v39
	v_pk_mul_f32 v[56:57], v[62:63], v[70:71]
	v_xor_b32_e32 v92, 48, v0
	ds_read2_b64 v[68:71], v92 offset0:192 offset1:224
	s_waitcnt lgkmcnt(0)
	v_pk_mul_f32 v[52:53], v[56:57], v[68:69]
	s_nop 0
	v_pk_mul_f32 v[0:1], v[52:53], v[70:71]
	s_and_saveexec_b64 s[26:27], s[4:5]
	s_cbranch_execz .LBB0_458
	v_lshl_add_u32 v253, v173, 1, v2
	ds_read2st64_b32 v[72:73], v253 offset0:96 offset1:112
	ds_read2st64_b32 v[68:69], v253 offset0:64 offset1:80
	v_lshl_add_u32 v74, v173, 1, v2
	s_nop 0
	ds_read_b32 v84, v74 offset:32768
	s_nop 0
	v_rcp_f32_e32 v70, v36
	v_rcp_f32_e32 v71, v37
	s_nop 0
	s_nop 0
	s_waitcnt lgkmcnt(2)
	v_cvt_f32_f16_e32 v78, v73
	v_cvt_f32_f16_sdwa v79, v73 dst_sel:DWORD dst_unused:UNUSED_PAD src0_sel:WORD_1
	v_lshl_add_u32 v253, v180, 1, v2
	ds_read2st64_b32 v[146:147], v253 offset0:64 offset1:80
	s_waitcnt lgkmcnt(2)
	v_cvt_f32_f16_e32 v74, v68
	v_cvt_f32_f16_sdwa v75, v68 dst_sel:DWORD dst_unused:UNUSED_PAD src0_sel:WORD_1
	v_cvt_f32_f16_e32 v76, v72
	ds_read2st64_b32 v[148:149], v253 offset0:96 offset1:112
	v_cvt_f32_f16_sdwa v77, v72 dst_sel:DWORD dst_unused:UNUSED_PAD src0_sel:WORD_1
	v_cvt_f32_f16_e32 v72, v69
	v_cvt_f32_f16_sdwa v73, v69 dst_sel:DWORD dst_unused:UNUSED_PAD src0_sel:WORD_1
	v_pk_mul_f32 v[78:79], v[36:37], v[78:79]
	v_pk_mul_f32 v[76:77], v[70:71], v[76:77]
	v_pk_mul_f32 v[70:71], v[70:71], v[74:75]
	v_pk_mul_f32 v[72:73], v[40:41], v[72:73]
	v_pk_mul_f32 v[74:75], v[40:41], v[78:79]
	v_cvt_pk_f16_f32 v68, v78, v79
	v_pk_mul_f32 v[80:81], v[38:39], v[76:77]
	v_pk_mul_f32 v[82:83], v[38:39], v[70:71]
	ds_write2st64_b32 v179, v69, v68 offset1:18
	v_cvt_pk_f16_f32 v68, v72, v73
	v_cvt_pk_f16_f32 v69, v74, v75
	v_pk_mul_f32 v[76:77], v[0:1], v[76:77]
	ds_write2st64_b32 v179, v68, v69 offset0:36 offset1:54
	v_cvt_pk_f16_f32 v68, v80, v81
	v_cvt_pk_f16_f32 v69, v82, v83
	ds_write2st64_b32 v179, v68, v69 offset0:72 offset1:90
	v_cvt_f16_f32_e32 v68, v76
	v_pk_mul_f32 v[70:71], v[0:1], v[70:71]
	v_cvt_f16_f32_e32 v69, v77
	v_cvt_f16_f32_e32 v70, v70
	v_cvt_f16_f32_e32 v71, v71
	ds_write_b16 v174, v68
	ds_write_b16 v174, v69 offset:40
	ds_write_b16 v174, v70 offset:5120
	ds_write_b16 v174, v71 offset:5160
	s_waitcnt lgkmcnt(9)
	ds_write_b16 v174, v84 offset:10240
	v_lshl_add_u32 v74, v180, 1, v2
	s_nop 0
	s_nop 0
	ds_read_b32 v82, v74 offset:32768
	v_rcp_f32_e32 v70, v66
	v_rcp_f32_e32 v71, v67
	s_waitcnt lgkmcnt(10)
	v_cvt_f32_f16_e32 v76, v147
	v_cvt_f32_f16_sdwa v77, v147 dst_sel:DWORD dst_unused:UNUSED_PAD src0_sel:WORD_1
	s_waitcnt lgkmcnt(9)
	v_cvt_f32_f16_e32 v80, v149
	v_cvt_f32_f16_sdwa v81, v149 dst_sel:DWORD dst_unused:UNUSED_PAD src0_sel:WORD_1
	v_lshl_add_u32 v253, v182, 1, v2
	ds_read2st64_b32 v[232:233], v253 offset0:64 offset1:80
	v_cvt_f32_f16_e32 v74, v146
	v_cvt_f32_f16_e32 v78, v148
	v_cvt_f32_f16_sdwa v79, v148 dst_sel:DWORD dst_unused:UNUSED_PAD src0_sel:WORD_1
	ds_read2st64_b32 v[148:149], v253 offset0:96 offset1:112
	v_cvt_f32_f16_sdwa v75, v146 dst_sel:DWORD dst_unused:UNUSED_PAD src0_sel:WORD_1
	v_pk_mul_f32 v[36:37], v[36:37], v[76:77]
	v_pk_mul_f32 v[68:69], v[66:67], v[80:81]
	v_pk_mul_f32 v[72:73], v[70:71], v[78:79]
	v_pk_mul_f32 v[70:71], v[70:71], v[74:75]
	v_pk_mul_f32 v[74:75], v[40:41], v[36:37]
	v_pk_mul_f32 v[76:77], v[40:41], v[68:69]
	v_cvt_pk_f16_f32 v36, v36, v37
	v_cvt_pk_f16_f32 v37, v68, v69
	v_pk_mul_f32 v[78:79], v[38:39], v[72:73]
	v_pk_mul_f32 v[80:81], v[38:39], v[70:71]
	ds_write2st64_b32 v181, v36, v37 offset1:18
	v_cvt_pk_f16_f32 v36, v74, v75
	v_cvt_pk_f16_f32 v37, v76, v77
	v_pk_mul_f32 v[72:73], v[0:1], v[72:73]
	ds_write2st64_b32 v181, v36, v37 offset0:36 offset1:54
	v_cvt_pk_f16_f32 v36, v78, v79
	v_cvt_pk_f16_f32 v37, v80, v81
	ds_write2st64_b32 v181, v36, v37 offset0:72 offset1:90
	v_cvt_f16_f32_e32 v36, v72
	v_pk_mul_f32 v[70:71], v[0:1], v[70:71]
	v_cvt_f16_f32_e32 v37, v73
	v_cvt_f16_f32_e32 v68, v70
	v_cvt_f16_f32_e32 v69, v71
	ds_write_b16 v174, v36 offset:2
	s_waitcnt lgkmcnt(14)
	ds_write_b16 v174, v37 offset:42
	s_waitcnt lgkmcnt(14)
	ds_write_b16 v174, v68 offset:5122
	s_waitcnt lgkmcnt(14)
	ds_write_b16 v174, v69 offset:5162
	s_waitcnt lgkmcnt(9)
	ds_write_b16 v174, v82 offset:10242
	v_lshl_add_u32 v72, v182, 1, v2
	s_nop 0
	s_nop 0
	ds_read_b32 v80, v72 offset:32768
	v_rcp_f32_e32 v68, v64
	v_rcp_f32_e32 v69, v65
	s_waitcnt lgkmcnt(10)
	v_cvt_f32_f16_e32 v74, v233
	v_cvt_f32_f16_sdwa v75, v233 dst_sel:DWORD dst_unused:UNUSED_PAD src0_sel:WORD_1
	s_waitcnt lgkmcnt(9)
	v_cvt_f32_f16_e32 v78, v149
	v_cvt_f32_f16_sdwa v79, v149 dst_sel:DWORD dst_unused:UNUSED_PAD src0_sel:WORD_1
	v_lshl_add_u32 v253, v184, 1, v2
	ds_read2st64_b32 v[146:147], v253 offset0:64 offset1:80
	v_cvt_f32_f16_e32 v72, v232
	v_cvt_f32_f16_e32 v76, v148
	v_cvt_f32_f16_sdwa v77, v148 dst_sel:DWORD dst_unused:UNUSED_PAD src0_sel:WORD_1
	ds_read2st64_b32 v[148:149], v253 offset0:96 offset1:112
	v_cvt_f32_f16_sdwa v73, v232 dst_sel:DWORD dst_unused:UNUSED_PAD src0_sel:WORD_1
	v_pk_mul_f32 v[36:37], v[66:67], v[74:75]
	v_pk_mul_f32 v[66:67], v[64:65], v[78:79]
	v_pk_mul_f32 v[70:71], v[68:69], v[76:77]
	v_pk_mul_f32 v[68:69], v[68:69], v[72:73]
	v_pk_mul_f32 v[72:73], v[40:41], v[36:37]
	v_pk_mul_f32 v[74:75], v[40:41], v[66:67]
	v_cvt_pk_f16_f32 v36, v36, v37
	v_cvt_pk_f16_f32 v37, v66, v67
	v_pk_mul_f32 v[76:77], v[38:39], v[70:71]
	v_pk_mul_f32 v[78:79], v[38:39], v[68:69]
	ds_write2st64_b32 v183, v36, v37 offset1:18
	v_cvt_pk_f16_f32 v36, v72, v73
	v_cvt_pk_f16_f32 v37, v74, v75
	v_pk_mul_f32 v[70:71], v[0:1], v[70:71]
	ds_write2st64_b32 v183, v36, v37 offset0:36 offset1:54
	v_cvt_pk_f16_f32 v36, v76, v77
	v_cvt_pk_f16_f32 v37, v78, v79
	ds_write2st64_b32 v183, v36, v37 offset0:72 offset1:90
	v_cvt_f16_f32_e32 v36, v70
	v_pk_mul_f32 v[68:69], v[0:1], v[68:69]
	v_cvt_f16_f32_e32 v37, v71
	v_cvt_f16_f32_e32 v66, v68
	v_cvt_f16_f32_e32 v67, v69
	ds_write_b16 v174, v36 offset:4
	s_waitcnt lgkmcnt(14)
	ds_write_b16 v174, v37 offset:44
	s_waitcnt lgkmcnt(14)
	ds_write_b16 v174, v66 offset:5124
	s_waitcnt lgkmcnt(14)
	ds_write_b16 v174, v67 offset:5164
	s_waitcnt lgkmcnt(9)
	ds_write_b16 v174, v80 offset:10244
	v_lshl_add_u32 v70, v184, 1, v2
	s_nop 0
	s_nop 0
	ds_read_b32 v78, v70 offset:32768
	v_rcp_f32_e32 v66, v60
	v_rcp_f32_e32 v67, v61
	s_waitcnt lgkmcnt(10)
	v_cvt_f32_f16_e32 v72, v147
	v_cvt_f32_f16_sdwa v73, v147 dst_sel:DWORD dst_unused:UNUSED_PAD src0_sel:WORD_1
	s_waitcnt lgkmcnt(9)
	v_cvt_f32_f16_e32 v76, v149
	v_cvt_f32_f16_sdwa v77, v149 dst_sel:DWORD dst_unused:UNUSED_PAD src0_sel:WORD_1
	v_cvt_f32_f16_e32 v70, v146
	v_cvt_f32_f16_e32 v74, v148
	v_cvt_f32_f16_sdwa v75, v148 dst_sel:DWORD dst_unused:UNUSED_PAD src0_sel:WORD_1
	v_cvt_f32_f16_sdwa v71, v146 dst_sel:DWORD dst_unused:UNUSED_PAD src0_sel:WORD_1
	v_pk_mul_f32 v[36:37], v[64:65], v[72:73]
	v_pk_mul_f32 v[64:65], v[60:61], v[76:77]
	v_pk_mul_f32 v[68:69], v[66:67], v[74:75]
	v_pk_mul_f32 v[66:67], v[66:67], v[70:71]
	v_pk_mul_f32 v[70:71], v[40:41], v[36:37]
	v_pk_mul_f32 v[72:73], v[40:41], v[64:65]
	v_cvt_pk_f16_f32 v36, v36, v37
	v_cvt_pk_f16_f32 v37, v64, v65
	v_pk_mul_f32 v[74:75], v[38:39], v[68:69]
	v_pk_mul_f32 v[76:77], v[38:39], v[66:67]
	ds_write2st64_b32 v185, v36, v37 offset1:18
	v_cvt_pk_f16_f32 v36, v70, v71
	v_cvt_pk_f16_f32 v37, v72, v73
	v_pk_mul_f32 v[68:69], v[0:1], v[68:69]
	ds_write2st64_b32 v185, v36, v37 offset0:36 offset1:54
	v_cvt_pk_f16_f32 v36, v74, v75
	v_cvt_pk_f16_f32 v37, v76, v77
	ds_write2st64_b32 v185, v36, v37 offset0:72 offset1:90
	v_cvt_f16_f32_e32 v36, v68
	v_pk_mul_f32 v[66:67], v[0:1], v[66:67]
	v_cvt_f16_f32_e32 v37, v69
	v_cvt_f16_f32_e32 v64, v66
	v_cvt_f16_f32_e32 v65, v67
	ds_write_b16 v174, v36 offset:6
	ds_write_b16 v174, v37 offset:46
	ds_write_b16 v174, v64 offset:5126
	s_waitcnt lgkmcnt(14)
	ds_write_b16 v174, v65 offset:5166
	s_nop 0
	s_waitcnt lgkmcnt(7)
	ds_write_b16 v174, v78 offset:10246
	v_perm_b32 v36, v82, v84, s82
	v_perm_b32 v37, v78, v80, s82
	ds_write_b64 v174, v[36:37] offset:10280

.LBB0_924:
	v_readlane_b32 s36, v254, 21
	v_and_b32_e32 v66, 63, v64
	v_readlane_b32 s48, v254, 33
	v_readlane_b32 s49, v254, 34
	v_lshlrev_b32_sdwa v175, v159, v123 dst_sel:DWORD dst_unused:UNUSED_PAD src0_sel:DWORD src1_sel:WORD_0
	v_readlane_b32 s38, v254, 23
	v_readlane_b32 s39, v254, 24
	v_readlane_b32 s44, v254, 29
	v_readlane_b32 s45, v254, 30
	v_readlane_b32 s46, v254, 31
	v_readlane_b32 s47, v254, 32
	v_lshl_add_u64 v[40:41], s[48:49], 0, v[4:5]
	s_andn2_b64 vcc, exec, s[4:5]
	v_cmp_gt_u32_e64 s[6:7], 8, v63
	v_cmp_eq_u32_e64 s[4:5], v66, v65
	v_readlane_b32 s37, v254, 22
	v_readlane_b32 s40, v254, 25
	v_readlane_b32 s41, v254, 26
	v_readlane_b32 s42, v254, 27
	v_readlane_b32 s43, v254, 28
	v_readlane_b32 s50, v254, 35
	v_readlane_b32 s51, v254, 36
	s_cbranch_vccnz .LBB0_928
	s_lshl_b32 s8, s26, 3
	v_mov_b32_e32 v1, 0xff
	v_or_b32_e32 v174, s8, v65
	v_bitop3_b32 v1, s8, v1, v65 bitop3:0x36
	v_cndmask_b32_e64 v1, v1, v174, s[2:3]
	v_or_b32_e32 v1, v1, v175
	v_mov_b64_e32 v[56:57], s[38:39]
	v_mad_u64_u32 v[20:21], s[10:11], v1, s71, v[56:57]
	v_lshlrev_b32_e32 v2, 4, v23
	v_lshl_add_u64 v[4:5], v[20:21], 0, v[2:3]
	v_add_co_u32_e32 v24, vcc, 0x3000, v4
	v_or_b32_e32 v43, v62, v69
	s_nop 0
	v_addc_co_u32_e32 v25, vcc, 0, v5, vcc
	global_load_dwordx4 v[70:73], v[24:25], off offset:1568
	global_load_dwordx4 v[74:77], v[24:25], off offset:1632
	v_lshlrev_b32_e32 v4, 1, v68
	v_or_b32_e32 v109, v43, v67
	v_add3_u32 v98, 0, v2, v4
	v_lshlrev_b32_e32 v60, 1, v109
	s_mov_b64 s[10:11], 0x1e20
	v_mov_b32_e32 v61, v3
	v_mov_b32_e32 v59, v3
	v_add_u32_e32 v102, 0xe000, v98
	v_or_b32_e32 v58, 32, v60
	v_lshl_add_u64 v[22:23], v[20:21], 0, s[10:11]
	s_mov_b64 s[12:13], 0x2420
	s_mov_b64 s[14:15], 0x2a20
	ds_read_b128 v[78:81], v98 offset:57344
	ds_read_b128 v[36:39], v98 offset:57408
	ds_read_b128 v[8:11], v98 offset:59648
	ds_read_b128 v[4:7], v98 offset:59712
	ds_read_b128 v[32:35], v98 offset:61952
	ds_read_b128 v[28:31], v98 offset:62016
	ds_read_b128 v[82:85], v102 offset:9216
	ds_read_b128 v[86:89], v102 offset:9280
	ds_read_b128 v[16:19], v102 offset:11520
	ds_read_b128 v[12:15], v102 offset:11584
	v_lshl_add_u64 v[26:27], v[20:21], 0, s[12:13]
	v_lshl_add_u64 v[44:45], v[20:21], 0, s[14:15]
	v_lshl_add_u64 v[46:47], v[22:23], 0, v[60:61]
	v_lshl_add_u64 v[90:91], v[22:23], 0, v[58:59]
	global_load_dwordx4 v[20:23], v[24:25], off offset:1696
	v_lshl_add_u64 v[50:51], v[26:27], 0, v[60:61]
	v_lshl_add_u64 v[54:55], v[44:45], 0, v[60:61]
	v_lshl_add_u64 v[26:27], v[26:27], 0, v[58:59]
	v_lshl_add_u64 v[92:93], v[44:45], 0, v[58:59]
	global_load_dwordx2 v[48:49], v[46:47], off
	global_load_dwordx2 v[52:53], v[50:51], off
	s_nop 0
	global_load_dwordx2 v[50:51], v[54:55], off
	global_load_dwordx2 v[44:45], v[90:91], off
	s_nop 0
	global_load_dwordx2 v[54:55], v[26:27], off
	global_load_dwordx2 v[46:47], v[92:93], off
	s_nop 0
	global_load_dwordx4 v[24:27], v[24:25], off offset:1760
	v_bitop3_b32 v107, s8, v166, v65 bitop3:0x36
	v_or_b32_e32 v106, 32, v174
	v_add_u32_e32 v107, 0x100, v107
	v_cndmask_b32_e64 v106, v107, v106, s[2:3]
	v_or_b32_e32 v106, v106, v175
	v_mad_u64_u32 v[56:57], s[8:9], v106, s71, v[56:57]
	v_lshl_add_u64 v[106:107], v[56:57], 0, v[2:3]
	s_movk_i32 s8, 0x3000
	v_add_co_u32_e32 v106, vcc, s8, v106
	v_lshl_add_u64 v[112:113], v[56:57], 0, s[12:13]
	s_nop 0
	v_addc_co_u32_e32 v107, vcc, 0, v107, vcc
	v_lshlrev_b32_e32 v2, 2, v0
	v_lshl_add_u64 v[116:117], v[112:113], 0, v[60:61]
	v_cmp_lt_i32_e32 vcc, v155, v156
	v_lshl_or_b32 v176, v174, 6, v43
	v_bfe_u32 v246, v238, 1, 2
	v_lshlrev_b32_e32 v246, 2, v246
	v_xor_b32_e32 v176, v176, v246
	v_lshl_add_u32 v43, v176, 2, 0
	s_mov_b64 s[74:75], 0x2a20
	s_waitcnt vmcnt(7) lgkmcnt(3)
	v_mfma_f32_16x16x32_f16 v[82:85], v[82:85], v[20:23], 0
	v_cndmask_b32_e64 v70, v72, v70, s[6:7]
	v_cndmask_b32_e64 v71, v73, v71, s[6:7]
	v_cndmask_b32_e64 v72, v76, v74, s[6:7]
	v_cndmask_b32_e64 v73, v77, v75, s[6:7]
	v_cvt_f32_f16_e32 v74, v70
	v_cvt_f32_f16_sdwa v70, v70 dst_sel:DWORD dst_unused:UNUSED_PAD src0_sel:WORD_1
	v_cvt_f32_f16_e32 v75, v71
	v_cvt_f32_f16_sdwa v71, v71 dst_sel:DWORD dst_unused:UNUSED_PAD src0_sel:WORD_1
	v_cvt_f32_f16_e32 v77, v73
	v_cvt_f32_f16_sdwa v73, v73 dst_sel:DWORD dst_unused:UNUSED_PAD src0_sel:WORD_1
	v_cvt_f32_f16_e32 v76, v72
	v_cvt_f32_f16_sdwa v72, v72 dst_sel:DWORD dst_unused:UNUSED_PAD src0_sel:WORD_1
	v_add_f32_e32 v74, v74, v74
	v_add_f32_e32 v70, v70, v70
	v_add_f32_e32 v75, v75, v75
	v_add_f32_e32 v71, v71, v71
	v_add_f32_e32 v73, v73, v73
	v_mul_f32_e32 v74, 0x3fb8aa3b, v74
	v_mul_f32_e32 v70, 0x3fb8aa3b, v70
	v_mul_f32_e32 v75, 0x3fb8aa3b, v75
	v_mul_f32_e32 v71, 0x3fb8aa3b, v71
	v_mul_f32_e32 v90, 0x3fb8aa3b, v73
	v_exp_f32_e32 v73, v74
	v_exp_f32_e32 v70, v70
	v_exp_f32_e32 v74, v75
	v_exp_f32_e32 v71, v71
	v_add_f32_e32 v76, v76, v76
	v_add_f32_e32 v72, v72, v72
	v_mul_f32_e32 v76, 0x3fb8aa3b, v76
	v_mul_f32_e32 v72, 0x3fb8aa3b, v72
	v_exp_f32_e32 v75, v76
	v_exp_f32_e32 v76, v72
	v_add_f32_e32 v72, 1.0, v73
	v_add_f32_e32 v73, 1.0, v70
	v_add_f32_e32 v74, 1.0, v74
	v_add_f32_e32 v91, 1.0, v71
	v_rcp_f32_e32 v70, v72
	v_rcp_f32_e32 v71, v73
	v_add_f32_e32 v77, v77, v77
	v_rcp_f32_e32 v72, v74
	v_rcp_f32_e32 v73, v91
	v_mul_f32_e32 v77, 0x3fb8aa3b, v77
	v_exp_f32_e32 v77, v77
	v_exp_f32_e32 v90, v90
	v_add_f32_e32 v75, 1.0, v75
	v_pk_fma_f32 v[70:71], v[70:71], 2.0, 1.0 op_sel_hi:[1,0,0] neg_lo:[1,0,0] neg_hi:[1,0,0]
	v_rcp_f32_e32 v74, v75
	v_pk_fma_f32 v[72:73], v[72:73], 2.0, 1.0 op_sel_hi:[1,0,0] neg_lo:[1,0,0] neg_hi:[1,0,0]
	v_cvt_pk_f16_f32 v75, v70, v71
	v_add_f32_e32 v76, 1.0, v76
	v_cvt_pk_f16_f32 v73, v72, v73
	v_mov_b32_dpp v72, v75 row_ror:8 row_mask:0xf bank_mask:0xf bound_ctrl:1
	v_cndmask_b32_e64 v70, v72, v75, s[6:7]
	v_cndmask_b32_e64 v72, v75, v72, s[6:7]
	v_rcp_f32_e32 v75, v76
	v_add_f32_e32 v76, 1.0, v77
	v_add_f32_e32 v77, 1.0, v90
	v_rcp_f32_e32 v76, v76
	v_rcp_f32_e32 v77, v77
	v_mov_b32_dpp v91, v73 row_ror:8 row_mask:0xf bank_mask:0xf bound_ctrl:1
	v_pk_fma_f32 v[74:75], v[74:75], 2.0, 1.0 op_sel_hi:[1,0,0] neg_lo:[1,0,0] neg_hi:[1,0,0]
	v_cndmask_b32_e64 v71, v91, v73, s[6:7]
	v_cndmask_b32_e64 v73, v73, v91, s[6:7]
	v_cvt_pk_f16_f32 v90, v74, v75
	v_pk_fma_f32 v[74:75], v[76:77], 2.0, 1.0 op_sel_hi:[1,0,0] neg_lo:[1,0,0] neg_hi:[1,0,0]
	v_mfma_f32_16x16x32_f16 v[8:11], v[8:11], v[70:73], 0
	v_cvt_pk_f16_f32 v91, v74, v75
	s_waitcnt vmcnt(6)
	v_cvt_f32_f16_sdwa v122, v49 dst_sel:DWORD dst_unused:UNUSED_PAD src0_sel:WORD_1
	v_mfma_f32_16x16x32_f16 v[74:77], v[78:81], v[70:73], 0
	v_mov_b32_dpp v80, v90 row_ror:8 row_mask:0xf bank_mask:0xf bound_ctrl:1
	v_mov_b32_dpp v81, v91 row_ror:8 row_mask:0xf bank_mask:0xf bound_ctrl:1
	v_cndmask_b32_e64 v78, v80, v90, s[6:7]
	s_waitcnt lgkmcnt(1)
	v_mfma_f32_16x16x32_f16 v[16:19], v[16:19], v[20:23], 0
	v_cndmask_b32_e64 v79, v81, v91, s[6:7]
	v_cndmask_b32_e64 v80, v90, v80, s[6:7]
	v_cndmask_b32_e64 v81, v91, v81, s[6:7]
	v_mfma_f32_16x16x32_f16 v[32:35], v[32:35], v[70:73], 0
	s_nop 0
	v_mfma_f32_16x16x32_f16 v[36:39], v[36:39], v[78:81], v[74:77]
	s_nop 2
	ds_read_b128 v[74:77], v102 offset:13824
	ds_read_b128 v[90:93], v102 offset:13888
	ds_read_b128 v[94:97], v98 offset:64256
	ds_read_b128 v[98:101], v98 offset:64320
	s_waitcnt vmcnt(0)
	v_mfma_f32_16x16x32_f16 v[82:85], v[86:89], v[24:27], v[82:85]
	ds_read_b128 v[86:89], v102 offset:16128
	ds_read_b128 v[102:105], v102 offset:16192
	v_mfma_f32_16x16x32_f16 v[124:127], v[4:7], v[78:81], v[8:11]
	global_load_dwordx4 v[4:7], v[106:107], off offset:1568
	s_nop 1
	global_load_dwordx4 v[8:11], v[106:107], off offset:1632
	s_waitcnt lgkmcnt(6)
	v_mfma_f32_16x16x32_f16 v[128:131], v[12:15], v[24:27], v[16:19]
	s_nop 2
	global_load_dwordx4 v[16:19], v[106:107], off offset:1696
	global_load_dwordx4 v[12:15], v[106:107], off offset:1760
	v_lshl_add_u64 v[106:107], v[56:57], 0, s[10:11]
	v_lshl_add_u64 v[56:57], v[56:57], 0, s[14:15]
	v_readlane_b32 s8, v254, 53
	v_readlane_b32 s10, v254, 55
	v_readlane_b32 s11, v254, 56
	v_readlane_b32 s14, v254, 59
	v_readlane_b32 s15, v254, 60
	v_mfma_f32_16x16x32_f16 v[132:135], v[28:31], v[78:81], v[32:35]
	v_lshl_add_u64 v[110:111], v[106:107], 0, v[60:61]
	v_lshl_add_u64 v[28:29], v[112:113], 0, v[58:59]
	v_lshl_add_u64 v[60:61], v[56:57], 0, v[60:61]
	v_lshl_add_u64 v[32:33], s[10:11], 0, v[2:3]
	v_lshl_add_u64 v[34:35], s[14:15], 0, v[2:3]
	v_lshlrev_b32_e32 v2, 2, v109
	v_lshl_add_u64 v[32:33], v[32:33], 0, v[2:3]
	v_lshl_add_u64 v[106:107], v[106:107], 0, v[58:59]
	global_load_dwordx2 v[114:115], v[110:111], off
	global_load_dwordx2 v[118:119], v[116:117], off
	s_nop 0
	global_load_dwordx2 v[116:117], v[60:61], off
	global_load_dwordx2 v[110:111], v[106:107], off
	v_lshl_add_u64 v[30:31], v[56:57], 0, v[58:59]
	global_load_dwordx2 v[120:121], v[28:29], off
	global_load_dwordx2 v[112:113], v[30:31], off
	s_waitcnt lgkmcnt(0)
	s_barrier
	global_load_dwordx4 v[56:59], v[32:33], off
	v_lshl_add_u64 v[60:61], v[34:35], 0, v[2:3]
	v_mfma_f32_16x16x32_f16 v[28:31], v[94:97], v[70:73], 0
	global_load_dwordx4 v[70:73], v[60:61], off
	v_readlane_b32 s18, v254, 63
	v_readlane_b32 s19, v255, 0
	v_mfma_f32_16x16x32_f16 v[74:77], v[74:77], v[20:23], 0
	v_readlane_b32 s20, v255, 1
	v_readlane_b32 s21, v255, 2
	v_readlane_b32 s22, v255, 3
	v_mfma_f32_16x16x32_f16 v[20:23], v[86:89], v[20:23], 0
	global_load_dwordx4 v[86:89], v[32:33], off offset:64
	v_readlane_b32 s23, v255, 4
	v_cndmask_b32_e64 v36, v132, v36, s[6:7]
	v_mfma_f32_16x16x32_f16 v[74:77], v[90:93], v[24:27], v[74:77]
	v_cndmask_b32_e64 v37, v133, v37, s[6:7]
	v_cndmask_b32_e64 v38, v134, v38, s[6:7]
	v_cvt_f32_f16_e32 v106, v48
	v_mfma_f32_16x16x32_f16 v[78:81], v[98:101], v[78:81], v[28:31]
	v_cvt_f32_f16_sdwa v107, v48 dst_sel:DWORD dst_unused:UNUSED_PAD src0_sel:WORD_1
	v_cvt_f32_f16_e32 v109, v49
	v_readlane_b32 s9, v254, 54
	v_mfma_f32_16x16x32_f16 v[90:93], v[102:105], v[24:27], v[20:23]
	global_load_dwordx4 v[94:97], v2, s[18:19] offset:3072
	global_load_dwordx4 v[32:35], v2, s[20:21] offset:3072
	global_load_dwordx4 v[98:101], v[60:61], off offset:64
	global_load_dwordx4 v[28:31], v2, s[22:23] offset:3072
	global_load_dwordx4 v[102:105], v2, s[18:19] offset:3136
	global_load_dwordx4 v[24:27], v2, s[20:21] offset:3136
	global_load_dwordx4 v[20:23], v2, s[22:23] offset:3136
	v_cndmask_b32_e64 v2, v135, v39, s[6:7]
	v_cndmask_b32_e64 v39, v77, v85, s[6:7]
	v_cndmask_b32_e64 v60, v74, v82, s[6:7]
	v_cndmask_b32_e64 v61, v75, v83, s[6:7]
	v_cvt_f32_f16_e32 v74, v54
	v_cvt_f32_f16_sdwa v75, v54 dst_sel:DWORD dst_unused:UNUSED_PAD src0_sel:WORD_1
	v_readlane_b32 s12, v254, 57
	v_readlane_b32 s13, v254, 58
	v_readlane_b32 s16, v254, 61
	v_readlane_b32 s17, v254, 62
	s_waitcnt vmcnt(9)
	v_add_f32_e32 v2, v2, v59
	v_add_f32_e32 v36, v36, v56
	v_cndmask_b32_e64 v56, v76, v84, s[6:7]
	v_mul_f32_e32 v2, 0xbfb8aa3b, v2
	s_waitcnt vmcnt(8)
	v_add_f32_e32 v56, v56, v72
	v_exp_f32_e32 v2, v2
	v_mul_f32_e32 v56, 0xbfb8aa3b, v56
	v_exp_f32_e32 v56, v56
	v_add_f32_e32 v60, v60, v70
	v_add_f32_e32 v2, 1.0, v2
	v_rcp_f32_e32 v2, v2
	v_add_f32_e32 v39, v39, v73
	v_mul_f32_e32 v60, 0xbfb8aa3b, v60
	v_add_f32_e32 v56, 1.0, v56
	v_mul_f32_e32 v39, 0xbfb8aa3b, v39
	v_exp_f32_e32 v60, v60
	v_rcp_f32_e32 v70, v56
	v_exp_f32_e32 v56, v39
	v_mul_f32_e32 v2, 0xbf1b4598, v2
	v_mul_f32_e32 v2, 0x3fb8aa3b, v2
	v_add_f32_e32 v37, v37, v57
	v_add_f32_e32 v57, 1.0, v60
	v_exp_f32_e32 v39, v2
	v_add_f32_e32 v2, 1.0, v56
	v_rcp_f32_e32 v60, v57
	v_add_f32_e32 v57, v61, v71
	v_rcp_f32_e32 v71, v2
	v_cndmask_b32_e64 v2, v81, v127, s[6:7]
	v_add_f32_e32 v38, v38, v58
	v_cndmask_b32_e64 v58, v80, v126, s[6:7]
	s_waitcnt vmcnt(7)
	v_add_f32_e32 v2, v2, v89
	v_add_f32_e32 v58, v58, v88
	v_mul_f32_e32 v2, 0xbfb8aa3b, v2
	v_mul_f32_e32 v57, 0xbfb8aa3b, v57
	v_mul_f32_e32 v58, 0xbfb8aa3b, v58
	v_exp_f32_e32 v2, v2
	v_exp_f32_e32 v57, v57
	v_exp_f32_e32 v58, v58
	v_cndmask_b32_e64 v59, v93, v131, s[6:7]
	v_add_f32_e32 v2, 1.0, v2
	v_add_f32_e32 v57, 1.0, v57
	v_cndmask_b32_e64 v80, v92, v130, s[6:7]
	v_add_f32_e32 v54, 1.0, v58
	v_rcp_f32_e32 v2, v2
	s_waitcnt vmcnt(4)
	v_add_f32_e32 v59, v59, v101
	v_rcp_f32_e32 v61, v57
	v_cndmask_b32_e64 v56, v78, v124, s[6:7]
	v_cndmask_b32_e64 v57, v79, v125, s[6:7]
	v_rcp_f32_e32 v54, v54
	v_add_f32_e32 v58, v80, v100
	v_mul_f32_e32 v59, 0xbfb8aa3b, v59
	v_add_f32_e32 v56, v56, v86
	v_add_f32_e32 v57, v57, v87
	v_mul_f32_e32 v58, 0xbfb8aa3b, v58
	v_exp_f32_e32 v82, v59
	v_cvt_f32_f16_e32 v86, v52
	v_cvt_f32_f16_sdwa v87, v52 dst_sel:DWORD dst_unused:UNUSED_PAD src0_sel:WORD_1
	v_exp_f32_e32 v80, v58
	v_cvt_f32_f16_e32 v52, v53
	v_cvt_f32_f16_sdwa v53, v53 dst_sel:DWORD dst_unused:UNUSED_PAD src0_sel:WORD_1
	v_mul_f32_e32 v2, 0xbf1b4598, v2
	v_mul_f32_e32 v54, 0xbf1b4598, v54
	v_mul_f32_e32 v2, 0x3fb8aa3b, v2
	v_mul_f32_e32 v54, 0x3fb8aa3b, v54
	v_exp_f32_e32 v59, v2
	v_add_f32_e32 v2, 1.0, v82
	v_pk_mul_f32 v[88:89], v[94:95], v[86:87]
	v_cndmask_b32_e64 v73, v91, v129, s[6:7]
	v_cndmask_b32_e64 v72, v90, v128, s[6:7]
	v_exp_f32_e32 v58, v54
	v_add_f32_e32 v54, 1.0, v80
	v_cvt_f32_f16_e32 v80, v55
	v_cvt_f32_f16_sdwa v81, v55 dst_sel:DWORD dst_unused:UNUSED_PAD src0_sel:WORD_1
	v_rcp_f32_e32 v55, v2
	v_cndmask_b32_e32 v2, v154, v155, vcc
	v_pk_mul_f32 v[90:91], v[88:89], v[88:89]
	v_pk_mul_f32 v[92:93], v[96:97], v[52:53]
	s_waitcnt vmcnt(2)
	v_pk_mul_f32 v[76:77], v[102:103], v[74:75]
	v_lshlrev_b32_e32 v102, 2, v2
	v_pk_mul_f32 v[94:95], v[92:93], v[92:93]
	v_add_f32_e32 v2, v90, v91
	v_add_f32_e32 v2, v94, v2
	v_pk_mul_f32 v[78:79], v[76:77], v[76:77]
	v_add_f32_e32 v2, v95, v2
	v_pk_mul_f32 v[82:83], v[104:105], v[80:81]
	v_add_f32_e32 v2, v2, v78
	v_pk_mul_f32 v[84:85], v[82:83], v[82:83]
	v_add_f32_e32 v2, v79, v2
	v_add_f32_e32 v2, v84, v2
	v_add_f32_e32 v2, v85, v2
	v_cmp_lt_i32_e32 vcc, v157, v156
	v_mul_f32_e32 v36, 0xbfb8aa3b, v36
	v_add_f32_dpp v2, v2, v2 row_ror:8 row_mask:0xf bank_mask:0xf bound_ctrl:1
	ds_bpermute_b32 v84, v102, v2
	v_cndmask_b32_e32 v78, v154, v157, vcc
	v_lshlrev_b32_e32 v90, 2, v78
	v_mul_f32_e32 v37, 0xbfb8aa3b, v37
	v_mul_f32_e32 v38, 0xbfb8aa3b, v38
	s_waitcnt lgkmcnt(0)
	v_add_f32_e32 v2, v2, v84
	ds_bpermute_b32 v84, v90, v2
	v_exp_f32_e32 v36, v36
	v_exp_f32_e32 v37, v37
	v_exp_f32_e32 v38, v38
	v_add_f32_e32 v72, v72, v98
	s_waitcnt lgkmcnt(0)
	v_add_f32_e32 v2, v2, v84
	v_add_f32_e32 v36, 1.0, v36
	v_add_f32_e32 v37, 1.0, v37
	v_add_f32_e32 v38, 1.0, v38
	v_add_f32_e32 v73, v73, v99
	v_max_f32_e32 v2, 0x179abe15, v2
	v_rcp_f32_e32 v36, v36
	v_rcp_f32_e32 v37, v37
	v_rcp_f32_e32 v38, v38
	v_mul_f32_e32 v72, 0xbfb8aa3b, v72
	v_mul_f32_e32 v73, 0xbfb8aa3b, v73
	v_pk_add_f32 v[78:79], v[60:61], -1.0 op_sel_hi:[1,0]
	v_rsq_f32_e32 v2, v2
	v_exp_f32_e32 v72, v72
	v_exp_f32_e32 v73, v73
	v_pk_fma_f32 v[32:33], v[32:33], v[78:79], 1.0 op_sel_hi:[1,1,0]
	v_mul_f32_e32 v36, 0xbf1b4598, v36
	v_pk_mul_f32 v[32:33], v[32:33], v[86:87]
	v_mul_f32_e32 v37, 0xbf1b4598, v37
	v_mul_f32_e32 v78, v32, v106
	v_mul_f32_e32 v38, 0xbf1b4598, v38
	v_fma_f32 v86, v28, v78, 0
	v_pk_mul_f32 v[78:79], v[92:93], v[2:3] op_sel_hi:[1,0]
	v_mul_f32_e32 v36, 0x3fb8aa3b, v36
	v_mul_f32_e32 v37, 0x3fb8aa3b, v37
	v_mul_f32_e32 v38, 0x3fb8aa3b, v38
	v_add_f32_e32 v72, 1.0, v72
	v_add_f32_e32 v73, 1.0, v73
	v_pk_mul_f32 v[84:85], v[70:71], v[78:79]
	v_pk_add_f32 v[70:71], v[70:71], -1.0 op_sel_hi:[1,0]
	v_exp_f32_e32 v36, v36
	v_exp_f32_e32 v37, v37
	v_exp_f32_e32 v38, v38
	v_rcp_f32_e32 v72, v72
	v_rcp_f32_e32 v73, v73
	v_pk_fma_f32 v[34:35], v[34:35], v[70:71], 1.0 op_sel_hi:[1,1,0]
	v_mul_f32_e32 v28, v33, v107
	v_pk_mul_f32 v[34:35], v[34:35], v[52:53]
	v_fmac_f32_e32 v86, v29, v28
	v_cvt_pk_f16_f32 v28, v32, v33
	v_pk_mul_f32 v[32:33], v[88:89], v[2:3] op_sel_hi:[1,0]
	v_mul_f32_e32 v29, v34, v109
	v_cvt_f32_f16_e32 v98, v44
	v_pk_mul_f32 v[60:61], v[60:61], v[32:33]
	v_mul_f32_e32 v52, v35, v122
	v_fmac_f32_e32 v86, v30, v29
	v_cvt_pk_f16_f32 v30, -v32, -v33
	v_lshlrev_b32_e32 v32, 1, v176
	v_cvt_f32_f16_sdwa v99, v44 dst_sel:DWORD dst_unused:UNUSED_PAD src0_sel:WORD_1
	v_fmac_f32_e32 v86, v31, v52
	v_cvt_pk_f16_f32 v29, v34, v35
	v_cvt_pk_f16_f32 v31, -v78, -v79
	ds_write_b128 v43, v[36:39]
	v_sub_u32_e32 v36, v43, v32
	v_pk_add_f32 v[34:35], v[72:73], -1.0 op_sel_hi:[1,0]
	v_rcp_f32_e32 v54, v54
	v_cvt_pk_f16_f32 v60, v60, v61
	v_cvt_pk_f16_f32 v61, v84, v85
	ds_write_b64 v36, v[30:31] offset:20480
	ds_write_b64 v36, v[60:61] offset:24576
	ds_write_b64 v36, v[48:49] offset:28672
	ds_write_b64 v36, v[50:51] offset:32768
	v_pk_mul_f32 v[30:31], v[76:77], v[2:3] op_sel_hi:[1,0]
	s_waitcnt vmcnt(1)
	v_pk_fma_f32 v[24:25], v[24:25], v[34:35], 1.0 op_sel_hi:[1,1,0]
	v_pk_mul_f32 v[32:33], v[72:73], v[30:31]
	v_pk_mul_f32 v[24:25], v[24:25], v[74:75]
	v_cvt_pk_f16_f32 v32, v32, v33
	v_mul_f32_e32 v33, v24, v98
	v_cvt_f32_f16_e32 v100, v45
	v_mul_f32_e32 v34, v25, v99
	s_waitcnt vmcnt(0)
	v_fmac_f32_e32 v86, v20, v33
	v_cvt_f32_f16_sdwa v101, v45 dst_sel:DWORD dst_unused:UNUSED_PAD src0_sel:WORD_1
	v_fmac_f32_e32 v86, v21, v34
	v_pk_add_f32 v[20:21], v[54:55], -1.0 op_sel_hi:[1,0]
	v_mul_f32_e32 v56, 0xbfb8aa3b, v56
	v_pk_fma_f32 v[20:21], v[26:27], v[20:21], 1.0 op_sel_hi:[1,1,0]
	v_mul_f32_e32 v57, 0xbfb8aa3b, v57
	v_pk_mul_f32 v[26:27], v[20:21], v[80:81]
	v_exp_f32_e32 v56, v56
	v_exp_f32_e32 v57, v57
	v_mul_f32_e32 v20, v26, v100
	v_mul_f32_e32 v21, v27, v101
	v_fmac_f32_e32 v86, v22, v20
	v_fmac_f32_e32 v86, v23, v21
	v_add_f32_e32 v56, 1.0, v56
	v_add_f32_e32 v57, 1.0, v57
	v_add_f32_dpp v23, v86, v86 row_ror:8 row_mask:0xf bank_mask:0xf bound_ctrl:1
	ds_bpermute_b32 v34, v102, v23
	v_rcp_f32_e32 v56, v56
	v_rcp_f32_e32 v57, v57
	v_cvt_pk_f16_f32 v22, v24, v25
	v_pk_mul_f32 v[24:25], v[82:83], v[2:3] op_sel_hi:[1,0]
	v_mul_f32_e32 v56, 0xbf1b4598, v56
	v_mul_f32_e32 v57, 0xbf1b4598, v57
	v_pk_mul_f32 v[20:21], v[54:55], v[24:25]
	s_waitcnt lgkmcnt(0)
	v_add_f32_e32 v2, v23, v34
	v_mul_f32_e32 v56, 0x3fb8aa3b, v56
	v_mul_f32_e32 v57, 0x3fb8aa3b, v57
	v_cvt_pk_f16_f32 v33, v20, v21
	ds_bpermute_b32 v20, v90, v2
	v_exp_f32_e32 v56, v56
	v_exp_f32_e32 v57, v57
	v_cvt_pk_f16_f32 v23, v26, v27
	v_add_u32_e32 v21, 0x4000, v36
	v_cvt_pk_f16_f32 v25, -v24, -v25
	v_cvt_pk_f16_f32 v24, -v30, -v31
	ds_write_b128 v43, v[56:59] offset:64
	ds_write2_b64 v21, v[28:29], v[22:23] offset1:4
	ds_write_b64 v36, v[24:25] offset:20512
	ds_write_b64 v36, v[32:33] offset:24608
	ds_write_b64 v36, v[44:45] offset:28704
	ds_write_b64 v36, v[46:47] offset:32800
	s_and_saveexec_b64 s[6:7], s[4:5]
	s_cbranch_execz .LBB0_927
	s_waitcnt lgkmcnt(6)
	v_add_f32_e32 v22, v2, v20
	v_mad_u64_u32 v[20:21], s[4:5], v1, 48, v[40:41]
	v_lshlrev_b32_e32 v2, 2, v108
	v_lshl_add_u64 v[20:21], v[20:21], 0, v[2:3]
	global_store_dword v[20:21], v22, off

.LBB0_928:
	v_mov_b32_e32 v23, s47
	v_mov_b32_e32 v24, s45
	v_cndmask_b32_e64 v25, v23, v24, s[2:3]
	v_mov_b32_e32 v23, s46
	v_mov_b32_e32 v24, s44
	v_cndmask_b32_e64 v24, v23, v24, s[2:3]
	v_lshlrev_b32_e32 v23, 1, v64
	v_bfe_u32 v28, v64, 5, 1
	v_and_b32_e32 v29, 62, v23
	v_lshl_or_b32 v23, v28, 6, v29
	v_readlane_b32 s6, v255, 38
	v_lshlrev_b32_e32 v30, 2, v29
	v_readlane_b32 s7, v255, 39
	v_mad_u32_u24 v180, v23, 40, s6
	v_lshlrev_b32_e32 v23, 8, v28
	v_lshlrev_b32_e32 v31, 1, v122
	v_add3_u32 v181, s7, v23, v30
	v_lshl_add_u32 v182, v122, 2, s7
	v_add_u32_e32 v32, s6, v31
	v_readlane_b32 s6, v255, 28
	v_readlane_b32 s7, v255, 29
	v_lshl_add_u64 v[24:25], v[2:3], 1, v[24:25]
	s_lshl_b32 s6, s26, 5
	s_mov_b32 s9, s7
	v_writelane_b32 v255, s8, 28
	v_lshl_add_u64 v[24:25], v[24:25], 0, s[6:7]
	v_lshlrev_b32_e32 v26, 1, v63
	v_mov_b32_e32 v27, v3
	v_writelane_b32 v255, s9, 29
	v_lshl_add_u64 v[126:127], v[24:25], 0, v[26:27]
	v_lshlrev_b32_e32 v23, 1, v124
	v_lshlrev_b32_e32 v26, 1, v22
	v_add3_u32 v183, 0, v23, v26
	v_or3_b32 v2, v2, v21, v122
	v_lshlrev_b32_e32 v22, 2, v108
	v_mov_b32_e32 v23, v3
	v_mul_u32_u24_e32 v21, 0x900, v28
	v_lshlrev_b32_e32 v27, 1, v29
	v_readlane_b32 s27, v255, 40
	v_lshl_add_u64 v[128:129], v[40:41], 0, v[22:23]
	v_cmp_eq_u32_e32 vcc, v122, v63
	v_add3_u32 v185, s27, v21, v27
	v_lshl_or_b32 v21, v28, 4, 1
	v_or_b32_e32 v22, 1, v122
	v_lshlrev_b32_e32 v186, 6, v21
	v_mul_u32_u24_e32 v21, 0x90, v21
	v_cndmask_b32_e64 v217, 0, 1.0, vcc
	v_cmp_lt_u32_e64 s[14:15], v22, v63
	v_cmp_eq_u32_e32 vcc, v22, v63
	v_or_b32_e32 v22, 2, v122
	v_add3_u32 v187, s27, v21, v27
	v_add_u32_e32 v21, s27, v26
	v_lshlrev_b32_e32 v20, 1, v20
	v_cndmask_b32_e64 v219, 0, 1.0, vcc
	v_cmp_lt_u32_e64 s[16:17], v22, v63
	v_cmp_lt_u32_e64 s[18:19], v63, v22
	v_cmp_eq_u32_e32 vcc, v22, v63
	v_or_b32_e32 v22, 3, v122
	v_add_u32_e32 v216, v21, v20
	v_cndmask_b32_e64 v220, 0, 1.0, vcc
	v_cmp_lt_u32_e64 s[20:21], v22, v63
	v_cmp_lt_u32_e64 s[22:23], v63, v22
	v_cmp_eq_u32_e32 vcc, v22, v63
	v_add_u32_e32 v222, v21, v31
	v_or_b32_e32 v21, 16, v63
	v_mov_b32_e32 v22, s27
	v_mad_u32_u24 v21, v21, s89, v22
	v_readlane_b32 s36, v254, 53
	v_add_u32_e32 v228, v21, v20
	v_lshlrev_b32_e32 v20, 12, v28
	v_lshlrev_b64 v[0:1], 2, v[0:1]
	v_readlane_b32 s38, v254, 55
	v_readlane_b32 s39, v254, 56
	v_readlane_b32 s42, v254, 59
	v_readlane_b32 s43, v254, 60
	v_add_u32_e32 v229, v21, v31
	v_add3_u32 v234, 0, v30, v20
	v_readlane_b32 s37, v254, 54
	v_readlane_b32 s40, v254, 57
	v_readlane_b32 s41, v254, 58
	v_readlane_b32 s44, v254, 61
	v_readlane_b32 s45, v254, 62
	v_readlane_b32 s46, v254, 63
	v_readlane_b32 s47, v255, 0
	v_readlane_b32 s48, v255, 1
	v_readlane_b32 s49, v255, 2
	v_readlane_b32 s50, v255, 3
	v_readlane_b32 s51, v255, 4
	v_lshl_add_u64 v[20:21], s[38:39], 0, v[0:1]
	v_lshl_add_u64 v[0:1], s[42:43], 0, v[0:1]
	v_lshlrev_b64 v[22:23], 2, v[2:3]
	v_or_b32_e32 v24, 16, v2
	v_mov_b32_e32 v25, v3
	v_lshl_or_b32 v218, s26, 4, v63
	v_mul_u32_u24_e32 v26, 40, v63
	v_lshl_add_u64 v[130:131], v[20:21], 0, v[22:23]
	v_lshl_add_u64 v[132:133], v[0:1], 0, v[22:23]
	v_lshl_add_u64 v[134:135], s[46:47], 0, v[22:23]
	v_lshl_add_u64 v[136:137], s[48:49], 0, v[22:23]
	v_lshl_add_u64 v[138:139], s[50:51], 0, v[22:23]
	v_mov_b32_e32 v22, v3
	v_mov_b32_e32 v23, v3
	v_readlane_b32 s36, v255, 5
	v_bfe_u32 v178, v64, 6, 2
	v_lshlrev_b32_e32 v179, 10, v28
	v_mad_u32_u24 v223, v218, 40, v32
	v_mad_u32_u24 v224, v63, 40, v32
	v_add_u32_e32 v235, 0, v27
	v_mov_b32_e32 v20, v3
	v_mov_b32_e32 v21, v3
	v_add_u32_e32 v240, v32, v26
	v_lshlrev_b64 v[142:143], 1, v[24:25]
	v_mov_b64_e32 v[34:35], v[22:23]
	v_mov_b64_e32 v[30:31], v[22:23]
	v_mov_b64_e32 v[26:27], v[22:23]
	v_readlane_b32 s48, v255, 17
	s_mov_b32 s76, 0
	v_cmp_eq_u32_e64 s[4:5], 0, v178
	v_add_u32_e32 v184, 0xe000, v183
	v_cmp_gt_u32_e64 s[6:7], 8, v63
	v_cmp_eq_u32_e64 s[8:9], v66, v65
	v_mov_b32_e32 v109, v3
	v_or_b32_e32 v188, 0x80, v179
	v_add_u32_e32 v189, 0x90, v187
	v_or_b32_e32 v190, 0xc0, v179
	v_add_u32_e32 v191, 0x120, v187
	v_or_b32_e32 v192, 0x100, v179
	v_add_u32_e32 v193, 0x1b0, v187
	v_or_b32_e32 v194, 0x140, v179
	v_add_u32_e32 v195, 0x240, v187
	v_or_b32_e32 v196, 0x180, v179
	v_add_u32_e32 v197, 0x2d0, v187
	v_or_b32_e32 v198, 0x1c0, v179
	v_add_u32_e32 v199, 0x360, v187
	v_or_b32_e32 v200, 0x200, v179
	v_add_u32_e32 v201, 0x3f0, v187
	v_or_b32_e32 v202, 0x240, v179
	v_add_u32_e32 v203, 0x480, v187
	v_or_b32_e32 v204, 0x280, v179
	v_add_u32_e32 v205, 0x510, v187
	v_or_b32_e32 v206, 0x2c0, v179
	v_add_u32_e32 v207, 0x5a0, v187
	v_or_b32_e32 v208, 0x300, v179
	v_add_u32_e32 v209, 0x630, v187
	v_or_b32_e32 v210, 0x340, v179
	v_add_u32_e32 v211, 0x6c0, v187
	v_or_b32_e32 v212, 0x380, v179
	v_add_u32_e32 v213, 0x750, v187
	v_or_b32_e32 v214, 0x3c0, v179
	v_add_u32_e32 v215, 0x7e0, v187
	v_and_b32_e32 v244, 31, v238
	v_lshlrev_b32_e32 v244, 1, v244
	v_xor_b32_e32 v245, 4, v244
	v_sub_u32_e32 v245, v245, v244
	v_xor_b32_e32 v246, 8, v244
	v_sub_u32_e32 v246, v246, v244
	v_xor_b32_e32 v247, 12, v244
	v_sub_u32_e32 v247, v247, v244
	v_add_u32_e32 v188, v188, v245
	v_add_u32_e32 v190, v190, v245
	v_add_u32_e32 v192, v192, v246
	v_add_u32_e32 v194, v194, v246
	v_add_u32_e32 v196, v196, v247
	v_add_u32_e32 v198, v198, v247
	v_add_u32_e32 v204, v204, v245
	v_add_u32_e32 v206, v206, v245
	v_add_u32_e32 v208, v208, v246
	v_add_u32_e32 v210, v210, v246
	v_add_u32_e32 v212, v212, v247
	v_add_u32_e32 v214, v214, v247
	v_cmp_lt_u32_e64 s[10:11], v122, v63
	v_cmp_lt_u32_e64 s[12:13], v63, v122
	v_cndmask_b32_e64 v221, 0, 1.0, vcc
	v_add_u32_e32 v225, 0x280, v224
	v_add_u32_e32 v226, 0x500, v224
	v_add_u32_e32 v227, 0x780, v224
	v_add_u32_e32 v230, 0xa00, v224
	v_add_u32_e32 v231, 0xc80, v224
	v_add_u32_e32 v232, 0xf00, v224
	v_add_u32_e32 v233, 0x1180, v224
	v_sub_u32_e32 v236, 0xdf, v174
	v_sub_u32_e32 v237, 0, v62
	s_mov_b32 s77, 64
	v_lshlrev_b64 v[140:141], 1, v[2:3]
	s_mov_b32 s26, 0
	v_mov_b64_e32 v[32:33], v[20:21]
	v_mov_b64_e32 v[28:29], v[20:21]
	v_mov_b64_e32 v[24:25], v[20:21]
	v_readlane_b32 s37, v255, 6
	v_readlane_b32 s38, v255, 7
	v_readlane_b32 s39, v255, 8
	v_readlane_b32 s40, v255, 9
	v_readlane_b32 s41, v255, 10
	v_readlane_b32 s42, v255, 11
	v_readlane_b32 s43, v255, 12
	v_readlane_b32 s44, v255, 13
	v_readlane_b32 s45, v255, 14
	v_readlane_b32 s46, v255, 15
	v_readlane_b32 s47, v255, 16
	v_readlane_b32 s50, v255, 19
	v_readlane_b32 s51, v255, 20
	s_movk_i32 s48, 0x110
	s_waitcnt lgkmcnt(0)
	s_barrier
	v_readlane_b32 s49, v255, 18
	s_andn2_b64 vcc, exec, s[24:25]
	s_mov_b64 s[28:29], -1
	s_cbranch_vccnz .LBB0_936
.LBB0_929:
	s_and_b32 s27, s26, 1
	v_lshl_add_u32 v0, s27, 13, v234
	ds_read2_b64 v[36:39], v0 offset1:32
	v_mad_u32_u24 v2, s27, v167, v235
	s_waitcnt lgkmcnt(0)
	v_pk_mul_f32 v[66:67], v[36:37], v[38:39]
	v_xor_b32_e32 v90, 16, v0
	ds_read2_b64 v[38:41], v90 offset0:64 offset1:96
	s_waitcnt lgkmcnt(0)
	v_pk_mul_f32 v[64:65], v[66:67], v[38:39]
	s_nop 0
	v_pk_mul_f32 v[60:61], v[64:65], v[40:41]
	v_xor_b32_e32 v91, 32, v0
	ds_read2_b64 v[38:41], v91 offset0:128 offset1:160
	s_waitcnt lgkmcnt(0)
	v_pk_mul_f32 v[54:55], v[60:61], v[38:39]
	s_nop 0
	v_pk_mul_f32 v[48:49], v[54:55], v[40:41]
	v_xor_b32_e32 v92, 48, v0
	ds_read2_b64 v[38:41], v92 offset0:192 offset1:224
	v_add_u32_e32 v0, 0x800, v0
	v_xor_b32_e32 v91, 32, v0
	ds_read2_b64 v[68:71], v91 offset0:128 offset1:160
	s_waitcnt lgkmcnt(1)
	v_pk_mul_f32 v[44:45], v[48:49], v[38:39]
	s_nop 0
	v_pk_mul_f32 v[38:39], v[44:45], v[40:41]
	ds_read2_b64 v[40:43], v0 offset1:32
	s_waitcnt lgkmcnt(0)
	v_pk_mul_f32 v[58:59], v[38:39], v[40:41]
	s_nop 0
	v_pk_mul_f32 v[50:51], v[58:59], v[42:43]
	v_xor_b32_e32 v90, 16, v0
	ds_read2_b64 v[40:43], v90 offset0:64 offset1:96
	s_waitcnt lgkmcnt(0)
	v_pk_mul_f32 v[46:47], v[50:51], v[40:41]
	s_nop 0
	v_pk_mul_f32 v[42:43], v[46:47], v[42:43]
	v_rcp_f32_e32 v40, v38
	v_pk_mul_f32 v[62:63], v[42:43], v[68:69]
	v_rcp_f32_e32 v41, v39
	v_pk_mul_f32 v[56:57], v[62:63], v[70:71]
	v_xor_b32_e32 v92, 48, v0
	ds_read2_b64 v[68:71], v92 offset0:192 offset1:224
	s_waitcnt lgkmcnt(0)
	v_pk_mul_f32 v[52:53], v[56:57], v[68:69]
	s_nop 0
	v_pk_mul_f32 v[0:1], v[52:53], v[70:71]
	s_and_saveexec_b64 s[28:29], s[4:5]
	s_cbranch_execz .LBB0_931
	v_lshl_add_u32 v251, v179, 1, v2
	ds_read2st64_b32 v[72:73], v251 offset0:96 offset1:112
	ds_read2st64_b32 v[68:69], v251 offset0:64 offset1:80
	v_lshl_add_u32 v74, v179, 1, v2
	s_nop 0
	ds_read_b32 v84, v74 offset:32768
	s_nop 0
	v_rcp_f32_e32 v70, v36
	v_rcp_f32_e32 v71, v37
	s_nop 0
	s_nop 0
	s_waitcnt lgkmcnt(2)
	v_cvt_f32_f16_e32 v78, v73
	v_cvt_f32_f16_sdwa v79, v73 dst_sel:DWORD dst_unused:UNUSED_PAD src0_sel:WORD_1
	v_lshl_add_u32 v251, v186, 1, v2
	ds_read2st64_b32 v[148:149], v251 offset0:64 offset1:80
	s_waitcnt lgkmcnt(2)
	v_cvt_f32_f16_e32 v74, v68
	v_cvt_f32_f16_sdwa v75, v68 dst_sel:DWORD dst_unused:UNUSED_PAD src0_sel:WORD_1
	v_cvt_f32_f16_e32 v76, v72
	ds_read2st64_b32 v[162:163], v251 offset0:96 offset1:112
	v_cvt_f32_f16_sdwa v77, v72 dst_sel:DWORD dst_unused:UNUSED_PAD src0_sel:WORD_1
	v_cvt_f32_f16_e32 v72, v69
	v_cvt_f32_f16_sdwa v73, v69 dst_sel:DWORD dst_unused:UNUSED_PAD src0_sel:WORD_1
	v_pk_mul_f32 v[78:79], v[36:37], v[78:79]
	v_pk_mul_f32 v[76:77], v[70:71], v[76:77]
	v_pk_mul_f32 v[70:71], v[70:71], v[74:75]
	v_pk_mul_f32 v[72:73], v[40:41], v[72:73]
	v_pk_mul_f32 v[74:75], v[40:41], v[78:79]
	v_cvt_pk_f16_f32 v68, v78, v79
	v_pk_mul_f32 v[80:81], v[38:39], v[76:77]
	v_pk_mul_f32 v[82:83], v[38:39], v[70:71]
	ds_write2st64_b32 v185, v69, v68 offset1:18
	v_cvt_pk_f16_f32 v68, v72, v73
	v_cvt_pk_f16_f32 v69, v74, v75
	v_pk_mul_f32 v[76:77], v[0:1], v[76:77]
	ds_write2st64_b32 v185, v68, v69 offset0:36 offset1:54
	v_cvt_pk_f16_f32 v68, v80, v81
	v_cvt_pk_f16_f32 v69, v82, v83
	ds_write2st64_b32 v185, v68, v69 offset0:72 offset1:90
	v_cvt_f16_f32_e32 v68, v76
	v_pk_mul_f32 v[70:71], v[0:1], v[70:71]
	v_cvt_f16_f32_e32 v69, v77
	v_cvt_f16_f32_e32 v70, v70
	v_cvt_f16_f32_e32 v71, v71
	ds_write_b16 v180, v68
	ds_write_b16 v180, v69 offset:40
	ds_write_b16 v180, v70 offset:5120
	ds_write_b16 v180, v71 offset:5160
	s_waitcnt lgkmcnt(9)
	ds_write_b16 v180, v84 offset:10240
	v_lshl_add_u32 v74, v186, 1, v2
	s_nop 0
	s_nop 0
	ds_read_b32 v82, v74 offset:32768
	v_rcp_f32_e32 v70, v66
	v_rcp_f32_e32 v71, v67
	s_waitcnt lgkmcnt(10)
	v_cvt_f32_f16_e32 v76, v149
	v_cvt_f32_f16_sdwa v77, v149 dst_sel:DWORD dst_unused:UNUSED_PAD src0_sel:WORD_1
	s_waitcnt lgkmcnt(9)
	v_cvt_f32_f16_e32 v80, v163
	v_cvt_f32_f16_sdwa v81, v163 dst_sel:DWORD dst_unused:UNUSED_PAD src0_sel:WORD_1
	v_lshl_add_u32 v251, v188, 1, v2
	ds_read2st64_b32 v[164:165], v251 offset0:64 offset1:80
	v_cvt_f32_f16_e32 v74, v148
	v_cvt_f32_f16_e32 v78, v162
	v_cvt_f32_f16_sdwa v79, v162 dst_sel:DWORD dst_unused:UNUSED_PAD src0_sel:WORD_1
	ds_read2st64_b32 v[162:163], v251 offset0:96 offset1:112
	v_cvt_f32_f16_sdwa v75, v148 dst_sel:DWORD dst_unused:UNUSED_PAD src0_sel:WORD_1
	v_pk_mul_f32 v[36:37], v[36:37], v[76:77]
	v_pk_mul_f32 v[68:69], v[66:67], v[80:81]
	v_pk_mul_f32 v[72:73], v[70:71], v[78:79]
	v_pk_mul_f32 v[70:71], v[70:71], v[74:75]
	v_pk_mul_f32 v[74:75], v[40:41], v[36:37]
	v_pk_mul_f32 v[76:77], v[40:41], v[68:69]
	v_cvt_pk_f16_f32 v36, v36, v37
	v_cvt_pk_f16_f32 v37, v68, v69
	v_pk_mul_f32 v[78:79], v[38:39], v[72:73]
	v_pk_mul_f32 v[80:81], v[38:39], v[70:71]
	ds_write2st64_b32 v187, v36, v37 offset1:18
	v_cvt_pk_f16_f32 v36, v74, v75
	v_cvt_pk_f16_f32 v37, v76, v77
	v_pk_mul_f32 v[72:73], v[0:1], v[72:73]
	ds_write2st64_b32 v187, v36, v37 offset0:36 offset1:54
	v_cvt_pk_f16_f32 v36, v78, v79
	v_cvt_pk_f16_f32 v37, v80, v81
	ds_write2st64_b32 v187, v36, v37 offset0:72 offset1:90
	v_cvt_f16_f32_e32 v36, v72
	v_pk_mul_f32 v[70:71], v[0:1], v[70:71]
	v_cvt_f16_f32_e32 v37, v73
	v_cvt_f16_f32_e32 v68, v70
	v_cvt_f16_f32_e32 v69, v71
	ds_write_b16 v180, v36 offset:2
	s_waitcnt lgkmcnt(14)
	ds_write_b16 v180, v37 offset:42
	s_waitcnt lgkmcnt(14)
	ds_write_b16 v180, v68 offset:5122
	s_waitcnt lgkmcnt(14)
	ds_write_b16 v180, v69 offset:5162
	s_waitcnt lgkmcnt(9)
	ds_write_b16 v180, v82 offset:10242
	v_lshl_add_u32 v72, v188, 1, v2
	s_nop 0
	s_nop 0
	ds_read_b32 v80, v72 offset:32768
	v_rcp_f32_e32 v68, v64
	v_rcp_f32_e32 v69, v65
	s_waitcnt lgkmcnt(10)
	v_cvt_f32_f16_e32 v74, v165
	v_cvt_f32_f16_sdwa v75, v165 dst_sel:DWORD dst_unused:UNUSED_PAD src0_sel:WORD_1
	s_waitcnt lgkmcnt(9)
	v_cvt_f32_f16_e32 v78, v163
	v_cvt_f32_f16_sdwa v79, v163 dst_sel:DWORD dst_unused:UNUSED_PAD src0_sel:WORD_1
	v_lshl_add_u32 v251, v190, 1, v2
	ds_read2st64_b32 v[148:149], v251 offset0:64 offset1:80
	v_cvt_f32_f16_e32 v72, v164
	v_cvt_f32_f16_e32 v76, v162
	v_cvt_f32_f16_sdwa v77, v162 dst_sel:DWORD dst_unused:UNUSED_PAD src0_sel:WORD_1
	ds_read2st64_b32 v[162:163], v251 offset0:96 offset1:112
	v_cvt_f32_f16_sdwa v73, v164 dst_sel:DWORD dst_unused:UNUSED_PAD src0_sel:WORD_1
	v_pk_mul_f32 v[36:37], v[66:67], v[74:75]
	v_pk_mul_f32 v[66:67], v[64:65], v[78:79]
	v_pk_mul_f32 v[70:71], v[68:69], v[76:77]
	v_pk_mul_f32 v[68:69], v[68:69], v[72:73]
	v_pk_mul_f32 v[72:73], v[40:41], v[36:37]
	v_pk_mul_f32 v[74:75], v[40:41], v[66:67]
	v_cvt_pk_f16_f32 v36, v36, v37
	v_cvt_pk_f16_f32 v37, v66, v67
	v_pk_mul_f32 v[76:77], v[38:39], v[70:71]
	v_pk_mul_f32 v[78:79], v[38:39], v[68:69]
	ds_write2st64_b32 v189, v36, v37 offset1:18
	v_cvt_pk_f16_f32 v36, v72, v73
	v_cvt_pk_f16_f32 v37, v74, v75
	v_pk_mul_f32 v[70:71], v[0:1], v[70:71]
	ds_write2st64_b32 v189, v36, v37 offset0:36 offset1:54
	v_cvt_pk_f16_f32 v36, v76, v77
	v_cvt_pk_f16_f32 v37, v78, v79
	ds_write2st64_b32 v189, v36, v37 offset0:72 offset1:90
	v_cvt_f16_f32_e32 v36, v70
	v_pk_mul_f32 v[68:69], v[0:1], v[68:69]
	v_cvt_f16_f32_e32 v37, v71
	v_cvt_f16_f32_e32 v66, v68
	v_cvt_f16_f32_e32 v67, v69
	ds_write_b16 v180, v36 offset:4
	s_waitcnt lgkmcnt(14)
	ds_write_b16 v180, v37 offset:44
	s_waitcnt lgkmcnt(14)
	ds_write_b16 v180, v66 offset:5124
	s_waitcnt lgkmcnt(14)
	ds_write_b16 v180, v67 offset:5164
	s_waitcnt lgkmcnt(9)
	ds_write_b16 v180, v80 offset:10244
	v_lshl_add_u32 v70, v190, 1, v2
	s_nop 0
	s_nop 0
	ds_read_b32 v78, v70 offset:32768
	v_rcp_f32_e32 v66, v60
	v_rcp_f32_e32 v67, v61
	s_waitcnt lgkmcnt(10)
	v_cvt_f32_f16_e32 v72, v149
	v_cvt_f32_f16_sdwa v73, v149 dst_sel:DWORD dst_unused:UNUSED_PAD src0_sel:WORD_1
	s_waitcnt lgkmcnt(9)
	v_cvt_f32_f16_e32 v76, v163
	v_cvt_f32_f16_sdwa v77, v163 dst_sel:DWORD dst_unused:UNUSED_PAD src0_sel:WORD_1
	v_cvt_f32_f16_e32 v70, v148
	v_cvt_f32_f16_e32 v74, v162
	v_cvt_f32_f16_sdwa v75, v162 dst_sel:DWORD dst_unused:UNUSED_PAD src0_sel:WORD_1
	v_cvt_f32_f16_sdwa v71, v148 dst_sel:DWORD dst_unused:UNUSED_PAD src0_sel:WORD_1
	v_pk_mul_f32 v[36:37], v[64:65], v[72:73]
	v_pk_mul_f32 v[64:65], v[60:61], v[76:77]
	v_pk_mul_f32 v[68:69], v[66:67], v[74:75]
	v_pk_mul_f32 v[66:67], v[66:67], v[70:71]
	v_pk_mul_f32 v[70:71], v[40:41], v[36:37]
	v_pk_mul_f32 v[72:73], v[40:41], v[64:65]
	v_cvt_pk_f16_f32 v36, v36, v37
	v_cvt_pk_f16_f32 v37, v64, v65
	v_pk_mul_f32 v[74:75], v[38:39], v[68:69]
	v_pk_mul_f32 v[76:77], v[38:39], v[66:67]
	ds_write2st64_b32 v191, v36, v37 offset1:18
	v_cvt_pk_f16_f32 v36, v70, v71
	v_cvt_pk_f16_f32 v37, v72, v73
	v_pk_mul_f32 v[68:69], v[0:1], v[68:69]
	ds_write2st64_b32 v191, v36, v37 offset0:36 offset1:54
	v_cvt_pk_f16_f32 v36, v74, v75
	v_cvt_pk_f16_f32 v37, v76, v77
	ds_write2st64_b32 v191, v36, v37 offset0:72 offset1:90
	v_cvt_f16_f32_e32 v36, v68
	v_pk_mul_f32 v[66:67], v[0:1], v[66:67]
	v_cvt_f16_f32_e32 v37, v69
	v_cvt_f16_f32_e32 v64, v66
	v_cvt_f16_f32_e32 v65, v67
	ds_write_b16 v180, v36 offset:6
	ds_write_b16 v180, v37 offset:46
	ds_write_b16 v180, v64 offset:5126
	s_waitcnt lgkmcnt(14)
	ds_write_b16 v180, v65 offset:5166
	s_nop 0
	s_waitcnt lgkmcnt(7)
	ds_write_b16 v180, v78 offset:10246
	v_perm_b32 v36, v82, v84, s35
	v_perm_b32 v37, v78, v80, s35
	ds_write_b64 v180, v[36:37] offset:10280

.LBB0_1021:
	s_mov_b64 s[62:63], s[46:47]
	s_mov_b64 s[60:61], s[44:45]
	s_mov_b64 s[58:59], s[42:43]
	s_mov_b64 s[56:57], s[40:41]
	s_mov_b64 s[54:55], s[38:39]
	s_mov_b64 s[52:53], s[36:37]
	s_mov_b64 s[66:67], s[50:51]
	v_readlane_b32 s36, v254, 21
	v_readlane_b32 s48, v254, 33
	v_readlane_b32 s49, v254, 34
	s_waitcnt vmcnt(1)
	v_lshl_add_u32 v151, v20, 11, v170
	s_mov_b32 s6, 0xc0000
	v_mov_b64_e32 v[20:21], s[48:49]
	v_mad_u64_u32 v[58:59], s[6:7], v1, s6, v[20:21]
	v_readlane_b32 s38, v254, 23
	v_readlane_b32 s39, v254, 24
	v_readlane_b32 s44, v254, 29
	v_readlane_b32 s45, v254, 30
	v_readlane_b32 s46, v254, 31
	v_readlane_b32 s47, v254, 32
	s_andn2_b64 vcc, exec, s[4:5]
	v_cmp_gt_u32_e64 s[6:7], 8, v74
	v_cmp_eq_u32_e64 s[4:5], v78, v79
	v_readlane_b32 s37, v254, 22
	v_readlane_b32 s40, v254, 25
	v_readlane_b32 s41, v254, 26
	v_readlane_b32 s42, v254, 27
	v_readlane_b32 s43, v254, 28
	v_readlane_b32 s50, v254, 35
	v_readlane_b32 s51, v254, 36
	s_cbranch_vccnz .LBB0_1025
	s_lshl_b32 s9, s9, 3
	v_or_b32_e32 v150, s9, v79
	v_bitop3_b32 v1, s9, v171, v79 bitop3:0x36
	v_cndmask_b32_e64 v1, v1, v150, s[2:3]
	v_or_b32_e32 v57, v1, v151
	v_mov_b64_e32 v[20:21], s[38:39]
	v_mad_i64_i32 v[34:35], s[10:11], v57, s71, v[20:21]
	v_mov_b32_e32 v45, v3
	v_lshl_add_u64 v[22:23], v[34:35], 0, v[44:45]
	v_add_co_u32_e32 v36, vcc, 0x3000, v22
	v_lshlrev_b32_e32 v2, 1, v81
	s_nop 0
	v_addc_co_u32_e32 v37, vcc, 0, v23, vcc
	global_load_dwordx4 v[22:25], v[36:37], off offset:1568
	global_load_dwordx4 v[26:29], v[36:37], off offset:1632
	v_or_b32_e32 v1, v77, v82
	v_add3_u32 v2, 0, v44, v2
	v_or_b32_e32 v46, v1, v80
	v_add_u32_e32 v61, 0xe000, v2
	v_or_b32_e32 v38, 16, v46
	ds_read_b128 v[30:33], v2 offset:57344
	ds_read_b128 v[52:55], v2 offset:57408
	ds_read_b128 v[84:87], v2 offset:59648
	ds_read_b128 v[88:91], v2 offset:59712
	ds_read_b128 v[92:95], v61 offset:9216
	ds_read_b128 v[96:99], v61 offset:9280
	global_load_dwordx4 v[40:43], v[36:37], off offset:1696
	v_ashrrev_i32_e32 v47, 31, v46
	v_ashrrev_i32_e32 v39, 31, v38
	s_mov_b64 s[12:13], 0x1e20
	s_mov_b64 s[14:15], 0x2420
	s_mov_b64 s[16:17], 0x2a20
	v_lshlrev_b64 v[50:51], 1, v[46:47]
	v_lshlrev_b64 v[48:49], 1, v[38:39]
	v_lshl_add_u64 v[38:39], v[34:35], 0, s[12:13]
	v_lshl_add_u64 v[62:63], v[34:35], 0, s[14:15]
	v_lshl_add_u64 v[34:35], v[34:35], 0, s[16:17]
	v_lshl_add_u64 v[64:65], v[38:39], 0, v[50:51]
	v_lshl_add_u64 v[68:69], v[62:63], 0, v[50:51]
	v_lshl_add_u64 v[72:73], v[34:35], 0, v[50:51]
	v_lshl_add_u64 v[38:39], v[38:39], 0, v[48:49]
	v_lshl_add_u64 v[100:101], v[62:63], 0, v[48:49]
	v_lshl_add_u64 v[34:35], v[34:35], 0, v[48:49]
	global_load_dwordx2 v[66:67], v[64:65], off
	global_load_dwordx2 v[70:71], v[68:69], off
	s_nop 0
	global_load_dwordx2 v[68:69], v[72:73], off
	global_load_dwordx2 v[62:63], v[38:39], off
	s_nop 0
	global_load_dwordx2 v[72:73], v[100:101], off
	global_load_dwordx2 v[64:65], v[34:35], off
	s_nop 0
	global_load_dwordx4 v[36:39], v[36:37], off offset:1760
	v_readlane_b32 s36, v254, 53
	v_readlane_b32 s37, v254, 54
	v_readlane_b32 s38, v254, 55
	v_readlane_b32 s39, v254, 56
	v_lshlrev_b64 v[46:47], 2, v[46:47]
	v_readlane_b32 s42, v254, 59
	v_readlane_b32 s43, v254, 60
	s_mov_b64 s[22:23], s[42:43]
	v_readlane_b32 s46, v254, 63
	v_readlane_b32 s47, v255, 0
	v_readlane_b32 s48, v255, 1
	v_readlane_b32 s49, v255, 2
	v_readlane_b32 s50, v255, 3
	v_readlane_b32 s51, v255, 4
	s_mov_b64 s[28:29], s[48:49]
	s_mov_b64 s[26:27], s[46:47]
	s_mov_b64 s[30:31], s[50:51]
	v_lshl_add_u64 v[148:149], s[30:31], 0, v[46:47]
	s_waitcnt vmcnt(10)
	v_lshl_or_b32 v152, v150, 6, v1
	v_bfe_u32 v246, v238, 1, 2
	v_lshlrev_b32_e32 v246, 2, v246
	v_xor_b32_e32 v152, v152, v246
	v_lshlrev_b32_e32 v1, 1, v152
	s_mov_b64 s[74:75], 0x2a20
	v_readlane_b32 s40, v254, 57
	v_readlane_b32 s41, v254, 58
	v_readlane_b32 s44, v254, 61
	v_readlane_b32 s45, v254, 62
	s_waitcnt vmcnt(9)
	v_cndmask_b32_e64 v22, v24, v22, s[6:7]
	v_cndmask_b32_e64 v23, v25, v23, s[6:7]
	s_waitcnt vmcnt(8)
	v_cndmask_b32_e64 v24, v28, v26, s[6:7]
	v_cvt_f32_f16_e32 v26, v22
	v_cvt_f32_f16_sdwa v22, v22 dst_sel:DWORD dst_unused:UNUSED_PAD src0_sel:WORD_1
	v_cndmask_b32_e64 v25, v29, v27, s[6:7]
	v_cvt_f32_f16_e32 v27, v23
	v_cvt_f32_f16_sdwa v23, v23 dst_sel:DWORD dst_unused:UNUSED_PAD src0_sel:WORD_1
	v_cvt_f32_f16_e32 v29, v25
	v_cvt_f32_f16_sdwa v25, v25 dst_sel:DWORD dst_unused:UNUSED_PAD src0_sel:WORD_1
	v_add_f32_e32 v26, v26, v26
	v_add_f32_e32 v22, v22, v22
	v_add_f32_e32 v23, v23, v23
	v_mul_f32_e32 v26, 0x3fb8aa3b, v26
	v_mul_f32_e32 v22, 0x3fb8aa3b, v22
	v_cvt_f32_f16_e32 v28, v24
	v_cvt_f32_f16_sdwa v24, v24 dst_sel:DWORD dst_unused:UNUSED_PAD src0_sel:WORD_1
	v_mul_f32_e32 v23, 0x3fb8aa3b, v23
	v_exp_f32_e32 v26, v26
	v_exp_f32_e32 v22, v22
	v_exp_f32_e32 v23, v23
	v_add_f32_e32 v25, v25, v25
	v_add_f32_e32 v27, v27, v27
	v_mul_f32_e32 v25, 0x3fb8aa3b, v25
	v_add_f32_e32 v24, v24, v24
	v_mul_f32_e32 v27, 0x3fb8aa3b, v27
	v_exp_f32_e32 v34, v25
	v_add_f32_e32 v25, 1.0, v26
	v_add_f32_e32 v26, 1.0, v22
	v_mul_f32_e32 v24, 0x3fb8aa3b, v24
	v_exp_f32_e32 v27, v27
	v_add_f32_e32 v35, 1.0, v23
	v_rcp_f32_e32 v22, v25
	v_rcp_f32_e32 v23, v26
	v_add_f32_e32 v28, v28, v28
	v_add_f32_e32 v29, v29, v29
	v_exp_f32_e32 v24, v24
	v_mul_f32_e32 v28, 0x3fb8aa3b, v28
	v_mul_f32_e32 v29, 0x3fb8aa3b, v29
	v_exp_f32_e32 v28, v28
	v_exp_f32_e32 v29, v29
	v_add_f32_e32 v27, 1.0, v27
	v_pk_fma_f32 v[22:23], v[22:23], 2.0, 1.0 op_sel_hi:[1,0,0] neg_lo:[1,0,0] neg_hi:[1,0,0]
	v_add_f32_e32 v83, 1.0, v24
	v_rcp_f32_e32 v24, v27
	v_rcp_f32_e32 v25, v35
	v_cvt_pk_f16_f32 v22, v22, v23
	v_add_f32_e32 v28, 1.0, v28
	v_add_f32_e32 v29, 1.0, v29
	v_mov_b32_dpp v23, v22 row_ror:8 row_mask:0xf bank_mask:0xf bound_ctrl:1
	v_cndmask_b32_e64 v100, v23, v22, s[6:7]
	v_cndmask_b32_e64 v102, v22, v23, s[6:7]
	v_add_f32_e32 v23, 1.0, v34
	v_rcp_f32_e32 v26, v28
	v_rcp_f32_e32 v27, v83
	v_rcp_f32_e32 v22, v29
	v_rcp_f32_e32 v23, v23
	v_pk_fma_f32 v[24:25], v[24:25], 2.0, 1.0 op_sel_hi:[1,0,0] neg_lo:[1,0,0] neg_hi:[1,0,0]
	v_pk_fma_f32 v[22:23], v[22:23], 2.0, 1.0 op_sel_hi:[1,0,0] neg_lo:[1,0,0] neg_hi:[1,0,0]
	v_cvt_pk_f16_f32 v24, v24, v25
	v_cvt_pk_f16_f32 v35, v22, v23
	s_nop 0
	v_mov_b32_dpp v25, v24 row_ror:8 row_mask:0xf bank_mask:0xf bound_ctrl:1
	v_cndmask_b32_e64 v101, v25, v24, s[6:7]
	v_cndmask_b32_e64 v103, v24, v25, s[6:7]
	v_pk_fma_f32 v[24:25], v[26:27], 2.0, 1.0 op_sel_hi:[1,0,0] neg_lo:[1,0,0] neg_hi:[1,0,0]
	s_waitcnt vmcnt(7) lgkmcnt(1)
	v_mfma_f32_16x16x32_f16 v[26:29], v[92:95], v[40:43], 0
	v_cvt_pk_f16_f32 v34, v24, v25
	v_mfma_f32_16x16x32_f16 v[22:25], v[30:33], v[100:103], 0
	s_nop 0
	v_mov_b32_dpp v30, v34 row_ror:8 row_mask:0xf bank_mask:0xf bound_ctrl:1
	v_mov_b32_dpp v31, v35 row_ror:8 row_mask:0xf bank_mask:0xf bound_ctrl:1
	v_cndmask_b32_e64 v104, v30, v34, s[6:7]
	v_cndmask_b32_e64 v105, v31, v35, s[6:7]
	v_cndmask_b32_e64 v106, v34, v30, s[6:7]
	v_cndmask_b32_e64 v107, v35, v31, s[6:7]
	v_bitop3_b32 v34, s9, v166, v79 bitop3:0x36
	v_add_u32_e32 v34, 0x800, v34
	v_mfma_f32_16x16x32_f16 v[52:55], v[52:55], v[104:107], v[22:25]
	s_nop 2
	ds_read_b128 v[22:25], v61 offset:11520
	ds_read_b128 v[30:33], v61 offset:11584
	ds_read_b128 v[92:95], v2 offset:61952
	ds_read_b128 v[108:111], v2 offset:62016
	ds_read_b128 v[112:115], v61 offset:13824
	ds_read_b128 v[116:119], v61 offset:13888
	ds_read_b128 v[120:123], v2 offset:64256
	ds_read_b128 v[124:127], v2 offset:64320
	v_or_b32_e32 v2, 32, v150
	s_waitcnt vmcnt(0) lgkmcnt(8)
	v_mfma_f32_16x16x32_f16 v[96:99], v[96:99], v[36:39], v[26:29]
	v_cndmask_b32_e64 v2, v34, v2, s[2:3]
	v_or_b32_e32 v2, v2, v151
	v_mad_i64_i32 v[136:137], s[10:11], v2, s71, v[20:21]
	v_mfma_f32_16x16x32_f16 v[26:29], v[84:87], v[100:103], 0
	v_lshl_add_u64 v[20:21], v[136:137], 0, v[44:45]
	s_movk_i32 s9, 0x3000
	v_lshl_add_u64 v[44:45], v[136:137], 0, s[12:13]
	s_waitcnt lgkmcnt(5)
	v_mfma_f32_16x16x32_f16 v[92:95], v[92:95], v[100:103], 0
	v_lshl_add_u64 v[140:141], v[136:137], 0, s[14:15]
	ds_read_b128 v[84:87], v61 offset:16128
	ds_read_b128 v[128:131], v61 offset:16192
	v_lshl_add_u64 v[142:143], v[136:137], 0, s[16:17]
	v_mfma_f32_16x16x32_f16 v[22:25], v[22:25], v[40:43], 0
	v_lshl_add_u64 v[144:145], v[44:45], 0, v[50:51]
	v_lshl_add_u64 v[44:45], v[44:45], 0, v[48:49]
	s_mov_b64 s[16:17], s[36:37]
	s_waitcnt lgkmcnt(5)
	v_mfma_f32_16x16x32_f16 v[112:115], v[112:115], v[40:43], 0
	v_lshlrev_b32_e32 v2, 2, v56
	s_mov_b64 s[18:19], s[38:39]
	v_mfma_f32_16x16x32_f16 v[88:91], v[88:91], v[104:107], v[26:29]
	s_nop 2
	v_add_co_u32_e32 v28, vcc, s9, v20
	v_mfma_f32_16x16x32_f16 v[92:95], v[108:111], v[104:107], v[92:95]
	s_nop 0
	v_addc_co_u32_e32 v29, vcc, 0, v21, vcc
	v_lshl_add_u64 v[108:109], v[140:141], 0, v[50:51]
	v_mfma_f32_16x16x32_f16 v[132:135], v[30:33], v[36:39], v[22:25]
	s_nop 2
	global_load_dwordx4 v[20:23], v[28:29], off offset:1568
	global_load_dwordx4 v[24:27], v[28:29], off offset:1632
	global_load_dwordx4 v[32:35], v[28:29], off offset:1696
	s_nop 0
	global_load_dwordx4 v[28:31], v[28:29], off offset:1760
	v_lshl_add_u64 v[50:51], v[142:143], 0, v[50:51]
	s_waitcnt lgkmcnt(4)
	v_mfma_f32_16x16x32_f16 v[136:139], v[116:119], v[36:39], v[112:115]
	s_nop 2
	global_load_dwordx2 v[112:113], v[144:145], off
	global_load_dwordx2 v[116:117], v[108:109], off
	global_load_dwordx2 v[114:115], v[50:51], off
	s_nop 0
	global_load_dwordx2 v[108:109], v[44:45], off
	v_lshl_add_u64 v[44:45], v[140:141], 0, v[48:49]
	v_lshl_add_u64 v[48:49], v[142:143], 0, v[48:49]
	global_load_dwordx2 v[118:119], v[44:45], off
	global_load_dwordx2 v[110:111], v[48:49], off
	v_lshl_add_u64 v[44:45], s[18:19], 0, v[2:3]
	s_waitcnt lgkmcnt(3)
	v_mfma_f32_16x16x32_f16 v[100:103], v[120:123], v[100:103], 0
	v_lshl_add_u64 v[44:45], v[44:45], 0, v[46:47]
	s_waitcnt lgkmcnt(0)
	s_barrier
	v_mfma_f32_16x16x32_f16 v[40:43], v[84:87], v[40:43], 0
	global_load_dwordx4 v[84:87], v[44:45], off
	v_lshl_add_u64 v[48:49], s[22:23], 0, v[2:3]
	v_lshl_add_u64 v[48:49], v[48:49], 0, v[46:47]
	v_mfma_f32_16x16x32_f16 v[100:103], v[124:127], v[104:107], v[100:103]
	global_load_dwordx4 v[104:107], v[48:49], off
	global_load_dwordx4 v[120:123], v[44:45], off offset:64
	v_cndmask_b32_e64 v2, v95, v55, s[6:7]
	v_cndmask_b32_e64 v52, v92, v52, s[6:7]
	v_mfma_f32_16x16x32_f16 v[124:127], v[128:131], v[36:39], v[40:43]
	v_lshl_add_u64 v[36:37], s[26:27], 0, v[46:47]
	v_lshl_add_u64 v[38:39], s[28:29], 0, v[46:47]
	global_load_dwordx4 v[128:131], v[48:49], off offset:64
	global_load_dwordx4 v[140:143], v[36:37], off offset:3072
	global_load_dwordx4 v[144:147], v[36:37], off offset:3136
	s_nop 0
	global_load_dwordx4 v[48:51], v[38:39], off offset:3072
	global_load_dwordx4 v[40:43], v[38:39], off offset:3136
	global_load_dwordx4 v[44:47], v[148:149], off offset:3072
	s_nop 0
	global_load_dwordx4 v[36:39], v[148:149], off offset:3136
	v_cndmask_b32_e64 v55, v139, v99, s[6:7]
	v_cndmask_b32_e64 v54, v94, v54, s[6:7]
	v_cndmask_b32_e64 v61, v138, v98, s[6:7]
	v_cndmask_b32_e64 v53, v93, v53, s[6:7]
	v_cmp_lt_i32_e32 vcc, v155, v156
	v_cndmask_b32_e64 v83, v137, v97, s[6:7]
	v_cvt_f32_f16_sdwa v137, v67 dst_sel:DWORD dst_unused:UNUSED_PAD src0_sel:WORD_1
	s_waitcnt vmcnt(9)
	v_add_f32_e32 v2, v2, v87
	v_add_f32_e32 v52, v52, v84
	v_cndmask_b32_e64 v84, v136, v96, s[6:7]
	v_mul_f32_e32 v2, 0xbfb8aa3b, v2
	s_waitcnt vmcnt(8)
	v_add_f32_e32 v84, v84, v104
	v_exp_f32_e32 v2, v2
	v_mul_f32_e32 v84, 0xbfb8aa3b, v84
	v_exp_f32_e32 v84, v84
	v_add_f32_e32 v55, v55, v107
	v_add_f32_e32 v2, 1.0, v2
	v_rcp_f32_e32 v2, v2
	v_add_f32_e32 v84, 1.0, v84
	v_mul_f32_e32 v55, 0xbfb8aa3b, v55
	v_rcp_f32_e32 v92, v84
	v_exp_f32_e32 v84, v55
	v_mul_f32_e32 v2, 0xbf1b4598, v2
	v_mul_f32_e32 v2, 0x3fb8aa3b, v2
	v_exp_f32_e32 v55, v2
	v_add_f32_e32 v2, 1.0, v84
	v_rcp_f32_e32 v95, v2
	v_cndmask_b32_e64 v2, v103, v91, s[6:7]
	v_add_f32_e32 v54, v54, v86
	v_cndmask_b32_e64 v86, v102, v90, s[6:7]
	s_waitcnt vmcnt(7)
	v_add_f32_e32 v2, v2, v123
	v_add_f32_e32 v86, v86, v122
	v_mul_f32_e32 v2, 0xbfb8aa3b, v2
	v_mul_f32_e32 v86, 0xbfb8aa3b, v86
	v_exp_f32_e32 v2, v2
	v_exp_f32_e32 v86, v86
	v_cndmask_b32_e64 v87, v127, v135, s[6:7]
	v_cndmask_b32_e64 v84, v100, v88, s[6:7]
	v_add_f32_e32 v2, 1.0, v2
	v_cndmask_b32_e64 v100, v126, v134, s[6:7]
	v_cvt_f32_f16_e32 v90, v72
	v_cvt_f32_f16_sdwa v91, v72 dst_sel:DWORD dst_unused:UNUSED_PAD src0_sel:WORD_1
	v_add_f32_e32 v72, 1.0, v86
	v_rcp_f32_e32 v2, v2
	s_waitcnt vmcnt(6)
	v_add_f32_e32 v87, v87, v131
	v_rcp_f32_e32 v72, v72
	v_add_f32_e32 v86, v100, v130
	v_mul_f32_e32 v87, 0xbfb8aa3b, v87
	v_add_f32_e32 v61, v61, v106
	v_mul_f32_e32 v86, 0xbfb8aa3b, v86
	v_exp_f32_e32 v102, v87
	v_cvt_f32_f16_e32 v106, v70
	v_cvt_f32_f16_sdwa v107, v70 dst_sel:DWORD dst_unused:UNUSED_PAD src0_sel:WORD_1
	v_exp_f32_e32 v100, v86
	v_cvt_f32_f16_e32 v70, v71
	v_cvt_f32_f16_sdwa v71, v71 dst_sel:DWORD dst_unused:UNUSED_PAD src0_sel:WORD_1
	v_mul_f32_e32 v2, 0xbf1b4598, v2
	v_add_f32_e32 v53, v53, v85
	v_cndmask_b32_e64 v85, v101, v89, s[6:7]
	v_mul_f32_e32 v72, 0xbf1b4598, v72
	v_mul_f32_e32 v2, 0x3fb8aa3b, v2
	v_add_f32_e32 v84, v84, v120
	v_add_f32_e32 v85, v85, v121
	v_mul_f32_e32 v72, 0x3fb8aa3b, v72
	v_exp_f32_e32 v87, v2
	v_add_f32_e32 v2, 1.0, v102
	s_waitcnt vmcnt(5)
	v_pk_mul_f32 v[120:121], v[140:141], v[106:107]
	v_cndmask_b32_e64 v89, v125, v133, s[6:7]
	v_cndmask_b32_e64 v88, v124, v132, s[6:7]
	v_exp_f32_e32 v86, v72
	v_add_f32_e32 v72, 1.0, v100
	v_cvt_f32_f16_e32 v100, v73
	v_cvt_f32_f16_sdwa v101, v73 dst_sel:DWORD dst_unused:UNUSED_PAD src0_sel:WORD_1
	v_rcp_f32_e32 v73, v2
	v_cndmask_b32_e32 v2, v154, v155, vcc
	v_pk_mul_f32 v[122:123], v[120:121], v[120:121]
	v_pk_mul_f32 v[124:125], v[142:143], v[70:71]
	v_lshlrev_b32_e32 v132, 2, v2
	v_pk_mul_f32 v[126:127], v[124:125], v[124:125]
	v_add_f32_e32 v2, v122, v123
	s_waitcnt vmcnt(4)
	v_pk_mul_f32 v[96:97], v[144:145], v[90:91]
	v_add_f32_e32 v2, v126, v2
	v_pk_mul_f32 v[98:99], v[96:97], v[96:97]
	v_add_f32_e32 v2, v127, v2
	v_pk_mul_f32 v[102:103], v[146:147], v[100:101]
	v_add_f32_e32 v2, v2, v98
	v_add_f32_e32 v83, v83, v105
	v_pk_mul_f32 v[104:105], v[102:103], v[102:103]
	v_add_f32_e32 v2, v99, v2
	v_add_f32_e32 v2, v104, v2
	v_add_f32_e32 v2, v105, v2
	v_mul_f32_e32 v83, 0xbfb8aa3b, v83
	v_cmp_lt_i32_e32 vcc, v157, v156
	v_add_f32_dpp v2, v2, v2 row_ror:8 row_mask:0xf bank_mask:0xf bound_ctrl:1
	ds_bpermute_b32 v104, v132, v2
	v_exp_f32_e32 v83, v83
	v_cndmask_b32_e32 v98, v154, v157, vcc
	v_lshlrev_b32_e32 v122, 2, v98
	v_mul_f32_e32 v52, 0xbfb8aa3b, v52
	s_waitcnt lgkmcnt(0)
	v_add_f32_e32 v2, v2, v104
	ds_bpermute_b32 v104, v122, v2
	v_mul_f32_e32 v53, 0xbfb8aa3b, v53
	v_mul_f32_e32 v54, 0xbfb8aa3b, v54
	v_add_f32_e32 v83, 1.0, v83
	v_mul_f32_e32 v61, 0xbfb8aa3b, v61
	v_exp_f32_e32 v52, v52
	v_exp_f32_e32 v53, v53
	v_exp_f32_e32 v54, v54
	v_rcp_f32_e32 v93, v83
	v_exp_f32_e32 v61, v61
	s_waitcnt lgkmcnt(0)
	v_add_f32_e32 v2, v2, v104
	v_cvt_f32_f16_e32 v136, v66
	v_add_f32_e32 v88, v88, v128
	v_add_f32_e32 v89, v89, v129
	v_max_f32_e32 v2, 0x179abe15, v2
	v_add_f32_e32 v52, 1.0, v52
	v_add_f32_e32 v53, 1.0, v53
	v_add_f32_e32 v54, 1.0, v54
	v_add_f32_e32 v61, 1.0, v61
	v_mul_f32_e32 v88, 0xbfb8aa3b, v88
	v_mul_f32_e32 v89, 0xbfb8aa3b, v89
	v_pk_add_f32 v[98:99], v[92:93], -1.0 op_sel_hi:[1,0]
	v_rsq_f32_e32 v2, v2
	v_rcp_f32_e32 v52, v52
	v_rcp_f32_e32 v53, v53
	v_rcp_f32_e32 v54, v54
	v_rcp_f32_e32 v94, v61
	v_exp_f32_e32 v88, v88
	v_exp_f32_e32 v89, v89
	s_waitcnt vmcnt(3)
	v_pk_fma_f32 v[48:49], v[48:49], v[98:99], 1.0 op_sel_hi:[1,1,0]
	v_cvt_f32_f16_sdwa v83, v66 dst_sel:DWORD dst_unused:UNUSED_PAD src0_sel:WORD_1
	v_pk_mul_f32 v[48:49], v[48:49], v[106:107]
	v_cvt_f32_f16_e32 v61, v67
	v_mul_f32_e32 v98, v48, v136
	s_waitcnt vmcnt(1)
	v_fma_f32 v106, v44, v98, 0
	v_pk_mul_f32 v[98:99], v[124:125], v[2:3] op_sel_hi:[1,0]
	v_mul_f32_e32 v52, 0xbf1b4598, v52
	v_mul_f32_e32 v53, 0xbf1b4598, v53
	v_mul_f32_e32 v54, 0xbf1b4598, v54
	v_add_f32_e32 v88, 1.0, v88
	v_add_f32_e32 v89, 1.0, v89
	v_pk_mul_f32 v[104:105], v[94:95], v[98:99]
	v_pk_add_f32 v[94:95], v[94:95], -1.0 op_sel_hi:[1,0]
	v_mul_f32_e32 v52, 0x3fb8aa3b, v52
	v_mul_f32_e32 v53, 0x3fb8aa3b, v53
	v_mul_f32_e32 v54, 0x3fb8aa3b, v54
	v_rcp_f32_e32 v88, v88
	v_rcp_f32_e32 v89, v89
	v_pk_fma_f32 v[50:51], v[50:51], v[94:95], 1.0 op_sel_hi:[1,1,0]
	v_exp_f32_e32 v52, v52
	v_exp_f32_e32 v53, v53
	v_exp_f32_e32 v54, v54
	v_mul_f32_e32 v44, v49, v83
	v_pk_mul_f32 v[50:51], v[50:51], v[70:71]
	v_fmac_f32_e32 v106, v45, v44
	v_mul_f32_e32 v45, v50, v61
	v_cvt_f32_f16_e32 v128, v62
	v_mul_f32_e32 v61, v51, v137
	v_fmac_f32_e32 v106, v46, v45
	v_cvt_f32_f16_sdwa v129, v62 dst_sel:DWORD dst_unused:UNUSED_PAD src0_sel:WORD_1
	v_cvt_pk_f16_f32 v44, v48, v49
	v_pk_mul_f32 v[48:49], v[120:121], v[2:3] op_sel_hi:[1,0]
	v_fmac_f32_e32 v106, v47, v61
	v_cvt_pk_f16_f32 v45, v50, v51
	v_lshl_add_u32 v61, v152, 2, 0
	v_pk_add_f32 v[50:51], v[88:89], -1.0 op_sel_hi:[1,0]
	v_rcp_f32_e32 v72, v72
	v_pk_mul_f32 v[92:93], v[92:93], v[48:49]
	v_cvt_pk_f16_f32 v47, -v98, -v99
	v_cvt_pk_f16_f32 v46, -v48, -v49
	ds_write_b128 v61, v[52:55]
	v_sub_u32_e32 v52, v61, v1
	v_pk_fma_f32 v[40:41], v[40:41], v[50:51], 1.0 op_sel_hi:[1,1,0]
	v_cvt_pk_f16_f32 v92, v92, v93
	v_cvt_pk_f16_f32 v93, v104, v105
	ds_write_b64 v52, v[46:47] offset:20480
	ds_write_b64 v52, v[92:93] offset:24576
	ds_write_b64 v52, v[66:67] offset:28672
	ds_write_b64 v52, v[68:69] offset:32768
	v_pk_mul_f32 v[46:47], v[96:97], v[2:3] op_sel_hi:[1,0]
	v_pk_mul_f32 v[40:41], v[40:41], v[90:91]
	v_pk_mul_f32 v[48:49], v[88:89], v[46:47]
	v_mul_f32_e32 v1, v40, v128
	v_cvt_f32_f16_e32 v130, v63
	v_cvt_pk_f16_f32 v48, v48, v49
	v_mul_f32_e32 v49, v41, v129
	s_waitcnt vmcnt(0)
	v_fmac_f32_e32 v106, v36, v1
	v_cvt_f32_f16_sdwa v131, v63 dst_sel:DWORD dst_unused:UNUSED_PAD src0_sel:WORD_1
	v_fmac_f32_e32 v106, v37, v49
	v_pk_add_f32 v[36:37], v[72:73], -1.0 op_sel_hi:[1,0]
	v_mul_f32_e32 v84, 0xbfb8aa3b, v84
	v_pk_fma_f32 v[36:37], v[42:43], v[36:37], 1.0 op_sel_hi:[1,1,0]
	v_mul_f32_e32 v85, 0xbfb8aa3b, v85
	v_pk_mul_f32 v[36:37], v[36:37], v[100:101]
	v_exp_f32_e32 v84, v84
	v_exp_f32_e32 v85, v85
	v_mul_f32_e32 v1, v36, v130
	v_mul_f32_e32 v42, v37, v131
	v_fmac_f32_e32 v106, v38, v1
	v_fmac_f32_e32 v106, v39, v42
	v_add_f32_e32 v84, 1.0, v84
	v_add_f32_e32 v85, 1.0, v85
	v_add_f32_dpp v1, v106, v106 row_ror:8 row_mask:0xf bank_mask:0xf bound_ctrl:1
	ds_bpermute_b32 v39, v132, v1
	v_rcp_f32_e32 v84, v84
	v_rcp_f32_e32 v85, v85
	v_cvt_pk_f16_f32 v38, v40, v41
	v_pk_mul_f32 v[40:41], v[102:103], v[2:3] op_sel_hi:[1,0]
	v_mul_f32_e32 v84, 0xbf1b4598, v84
	v_mul_f32_e32 v85, 0xbf1b4598, v85
	s_waitcnt lgkmcnt(0)
	v_add_f32_e32 v1, v1, v39
	v_mul_f32_e32 v84, 0x3fb8aa3b, v84
	v_mul_f32_e32 v85, 0x3fb8aa3b, v85
	ds_bpermute_b32 v2, v122, v1
	v_exp_f32_e32 v84, v84
	v_exp_f32_e32 v85, v85
	v_pk_mul_f32 v[42:43], v[72:73], v[40:41]
	v_cvt_pk_f16_f32 v39, v36, v37
	v_cvt_pk_f16_f32 v37, -v40, -v41
	v_add_u32_e32 v40, 0x4000, v52
	v_cvt_pk_f16_f32 v49, v42, v43
	v_cvt_pk_f16_f32 v36, -v46, -v47
	ds_write_b128 v61, v[84:87] offset:64
	ds_write2_b64 v40, v[44:45], v[38:39] offset1:4
	ds_write_b64 v52, v[36:37] offset:20512
	ds_write_b64 v52, v[48:49] offset:24608
	ds_write_b64 v52, v[62:63] offset:28704
	ds_write_b64 v52, v[64:65] offset:32800
	s_and_saveexec_b64 s[6:7], s[4:5]
	s_cbranch_execz .LBB0_1024
	s_waitcnt lgkmcnt(6)
	v_add_f32_e32 v2, v1, v2
	v_ashrrev_i32_e32 v1, 31, v0
	v_mad_i64_i32 v[36:37], s[4:5], v57, 48, v[58:59]
	v_lshl_add_u64 v[36:37], v[0:1], 2, v[36:37]
	global_store_dword v[36:37], v2, off

.LBB0_1025:
	v_mov_b32_e32 v1, s47
	s_waitcnt lgkmcnt(6)
	v_mov_b32_e32 v2, s45
	v_cndmask_b32_e64 v43, v1, v2, s[2:3]
	v_mov_b32_e32 v1, s46
	v_mov_b32_e32 v2, s44
	v_cndmask_b32_e64 v42, v1, v2, s[2:3]
	v_lshlrev_b32_e32 v1, 1, v76
	v_bfe_u32 v44, v76, 5, 1
	v_and_b32_e32 v45, 62, v1
	v_lshl_or_b32 v1, v44, 6, v45
	v_readlane_b32 s6, v255, 38
	v_lshlrev_b32_e32 v46, 2, v45
	v_readlane_b32 s7, v255, 39
	v_mad_u32_u24 v176, v1, 40, s6
	v_lshlrev_b32_e32 v1, 8, v44
	s_waitcnt vmcnt(0)
	v_lshlrev_b32_e32 v47, 1, v153
	v_add3_u32 v177, s7, v1, v46
	v_lshl_add_u32 v178, v153, 2, s7
	v_add_u32_e32 v48, s6, v47
	v_ashrrev_i32_e32 v37, 31, v36
	v_readlane_b32 s6, v255, 28
	v_lshl_add_u64 v[42:43], v[36:37], 1, v[42:43]
	v_readlane_b32 s7, v255, 29
	s_lshl_b32 s6, s8, 1
	s_mov_b32 s9, s7
	v_lshl_add_u64 v[42:43], v[42:43], 0, s[6:7]
	v_lshlrev_b32_e32 v2, 1, v74
	v_writelane_b32 v255, s8, 28
	v_lshl_add_u64 v[122:123], v[42:43], 0, v[2:3]
	v_lshlrev_b32_e32 v1, 1, v120
	v_lshlrev_b32_e32 v2, 1, v40
	v_writelane_b32 v255, s9, 29
	v_add3_u32 v179, 0, v1, v2
	v_ashrrev_i32_e32 v1, 31, v0
	v_lshl_add_u64 v[124:125], v[0:1], 2, v[58:59]
	v_mul_u32_u24_e32 v0, 0x900, v44
	v_lshlrev_b32_e32 v45, 1, v45
	v_readlane_b32 s26, v255, 40
	v_lshlrev_b32_e32 v1, 1, v38
	v_or3_b32 v36, v36, v39, v153
	v_add3_u32 v181, s26, v0, v45
	v_lshl_or_b32 v0, v44, 4, 1
	v_lshlrev_b32_e32 v182, 6, v0
	v_mul_u32_u24_e32 v0, 0x90, v0
	v_add3_u32 v183, s26, v0, v45
	v_add_u32_e32 v0, s26, v2
	v_add_u32_e32 v212, v0, v1
	v_add_u32_e32 v217, v0, v47
	v_or_b32_e32 v0, 16, v74
	v_mov_b32_e32 v38, s26
	v_cmp_eq_u32_e32 vcc, v153, v74
	v_or_b32_e32 v2, 1, v153
	v_mad_u32_u24 v0, v0, s89, v38
	v_ashrrev_i32_e32 v37, 31, v36
	v_cndmask_b32_e64 v213, 0, 1.0, vcc
	v_cmp_lt_u32_e64 s[14:15], v2, v74
	v_cmp_eq_u32_e32 vcc, v2, v74
	v_or_b32_e32 v2, 2, v153
	v_add_u32_e32 v223, v0, v1
	v_add_u32_e32 v224, v0, v47
	v_lshlrev_b32_e32 v0, 12, v44
	v_readlane_b32 s36, v254, 53
	v_or_b32_e32 v40, 16, v36
	v_cndmask_b32_e64 v214, 0, 1.0, vcc
	v_cmp_lt_u32_e64 s[16:17], v2, v74
	v_cmp_lt_u32_e64 s[18:19], v74, v2
	v_cmp_eq_u32_e32 vcc, v2, v74
	v_or_b32_e32 v2, 3, v153
	v_add3_u32 v229, 0, v46, v0
	v_lshlrev_b64 v[0:1], 2, v[56:57]
	v_readlane_b32 s37, v254, 54
	v_readlane_b32 s38, v254, 55
	v_readlane_b32 s39, v254, 56
	v_readlane_b32 s40, v254, 57
	v_readlane_b32 s41, v254, 58
	v_readlane_b32 s42, v254, 59
	v_readlane_b32 s43, v254, 60
	v_readlane_b32 s44, v254, 61
	v_readlane_b32 s45, v254, 62
	v_readlane_b32 s46, v254, 63
	v_readlane_b32 s47, v255, 0
	v_lshlrev_b64 v[42:43], 2, v[36:37]
	v_bfe_u32 v174, v76, 6, 2
	v_lshlrev_b32_e32 v175, 10, v44
	v_ashrrev_i32_e32 v41, 31, v40
	v_cndmask_b32_e64 v215, 0, 1.0, vcc
	v_cmp_lt_u32_e64 s[20:21], v2, v74
	v_cmp_lt_u32_e64 s[22:23], v74, v2
	v_cmp_eq_u32_e32 vcc, v2, v74
	v_mul_u32_u24_e32 v2, 40, v74
	v_mad_u32_u24 v219, v74, 40, v48
	v_readlane_b32 s48, v255, 1
	v_readlane_b32 s49, v255, 2
	v_readlane_b32 s50, v255, 3
	v_readlane_b32 s51, v255, 4
	v_lshl_add_u64 v[38:39], s[38:39], 0, v[0:1]
	v_lshl_add_u64 v[0:1], s[42:43], 0, v[0:1]
	v_lshl_add_u64 v[130:131], s[46:47], 0, v[42:43]
	s_mov_b64 s[36:37], s[52:53]
	s_mov_b32 s68, 0
	v_cmp_eq_u32_e64 s[4:5], 0, v174
	v_add_u32_e32 v180, 0xe000, v179
	v_cmp_gt_u32_e64 s[6:7], 8, v74
	v_cmp_eq_u32_e64 s[8:9], v78, v79
	v_or_b32_e32 v184, 0x80, v175
	v_add_u32_e32 v185, 0x90, v183
	v_or_b32_e32 v186, 0xc0, v175
	v_add_u32_e32 v187, 0x120, v183
	v_or_b32_e32 v188, 0x100, v175
	v_add_u32_e32 v189, 0x1b0, v183
	v_or_b32_e32 v190, 0x140, v175
	v_add_u32_e32 v191, 0x240, v183
	v_or_b32_e32 v192, 0x180, v175
	v_add_u32_e32 v193, 0x2d0, v183
	v_or_b32_e32 v194, 0x1c0, v175
	v_add_u32_e32 v195, 0x360, v183
	v_or_b32_e32 v196, 0x200, v175
	v_add_u32_e32 v197, 0x3f0, v183
	v_or_b32_e32 v198, 0x240, v175
	v_add_u32_e32 v199, 0x480, v183
	v_or_b32_e32 v200, 0x280, v175
	v_add_u32_e32 v201, 0x510, v183
	v_or_b32_e32 v202, 0x2c0, v175
	v_add_u32_e32 v203, 0x5a0, v183
	v_or_b32_e32 v204, 0x300, v175
	v_add_u32_e32 v205, 0x630, v183
	v_or_b32_e32 v206, 0x340, v175
	v_add_u32_e32 v207, 0x6c0, v183
	v_or_b32_e32 v208, 0x380, v175
	v_add_u32_e32 v209, 0x750, v183
	v_or_b32_e32 v210, 0x3c0, v175
	v_add_u32_e32 v211, 0x7e0, v183
	v_and_b32_e32 v244, 31, v238
	v_lshlrev_b32_e32 v244, 1, v244
	v_xor_b32_e32 v245, 4, v244
	v_sub_u32_e32 v245, v245, v244
	v_xor_b32_e32 v246, 8, v244
	v_sub_u32_e32 v246, v246, v244
	v_xor_b32_e32 v247, 12, v244
	v_sub_u32_e32 v247, v247, v244
	v_add_u32_e32 v184, v184, v245
	v_add_u32_e32 v186, v186, v245
	v_add_u32_e32 v188, v188, v246
	v_add_u32_e32 v190, v190, v246
	v_add_u32_e32 v192, v192, v247
	v_add_u32_e32 v194, v194, v247
	v_add_u32_e32 v200, v200, v245
	v_add_u32_e32 v202, v202, v245
	v_add_u32_e32 v204, v204, v246
	v_add_u32_e32 v206, v206, v246
	v_add_u32_e32 v208, v208, v247
	v_add_u32_e32 v210, v210, v247
	v_cmp_lt_u32_e64 s[10:11], v153, v74
	v_cmp_lt_u32_e64 s[12:13], v74, v153
	v_cndmask_b32_e64 v216, 0, 1.0, vcc
	v_mad_u32_u24 v218, v75, 40, v48
	v_add_u32_e32 v220, 0x280, v219
	v_add_u32_e32 v221, 0x500, v219
	v_add_u32_e32 v222, 0x780, v219
	v_add_u32_e32 v225, 0xa00, v219
	v_add_u32_e32 v226, 0xc80, v219
	v_add_u32_e32 v227, 0xf00, v219
	v_add_u32_e32 v228, 0x1180, v219
	v_lshl_add_u64 v[126:127], v[38:39], 0, v[42:43]
	v_lshl_add_u64 v[128:129], v[0:1], 0, v[42:43]
	v_lshl_add_u64 v[132:133], s[48:49], 0, v[42:43]
	v_lshl_add_u64 v[134:135], s[50:51], 0, v[42:43]
	v_add_u32_e32 v230, 0, v45
	v_sub_u32_e32 v231, 0x7df, v150
	v_sub_u32_e32 v232, 0, v77
	s_mov_b32 s69, 64
	v_add_u32_e32 v233, v48, v2
	v_lshlrev_b64 v[136:137], 1, v[36:37]
	v_lshlrev_b64 v[138:139], 1, v[40:41]
	s_mov_b32 s76, 0
	s_mov_b64 s[38:39], s[54:55]
	s_mov_b64 s[40:41], s[56:57]
	s_mov_b64 s[42:43], s[58:59]
	s_mov_b64 s[44:45], s[60:61]
	s_mov_b64 s[46:47], s[62:63]
	s_mov_b64 s[50:51], s[66:67]
	s_movk_i32 s48, 0x110
	s_waitcnt lgkmcnt(0)
	s_barrier
	s_branch .LBB0_1028

.LBB0_1028:
	s_andn2_b64 vcc, exec, s[24:25]
	s_mov_b64 s[26:27], -1
	s_cbranch_vccnz .LBB0_1036
	s_and_b32 s26, s76, 1
	v_lshl_add_u32 v0, s26, 13, v229
	ds_read2_b64 v[36:39], v0 offset1:32
	v_mad_u32_u24 v2, s26, v167, v230
	s_waitcnt lgkmcnt(0)
	v_pk_mul_f32 v[66:67], v[36:37], v[38:39]
	v_xor_b32_e32 v90, 16, v0
	ds_read2_b64 v[38:41], v90 offset0:64 offset1:96
	s_waitcnt lgkmcnt(0)
	v_pk_mul_f32 v[64:65], v[66:67], v[38:39]
	s_nop 0
	v_pk_mul_f32 v[60:61], v[64:65], v[40:41]
	v_xor_b32_e32 v91, 32, v0
	ds_read2_b64 v[38:41], v91 offset0:128 offset1:160
	s_waitcnt lgkmcnt(0)
	v_pk_mul_f32 v[54:55], v[60:61], v[38:39]
	s_nop 0
	v_pk_mul_f32 v[48:49], v[54:55], v[40:41]
	v_xor_b32_e32 v92, 48, v0
	ds_read2_b64 v[38:41], v92 offset0:192 offset1:224
	v_add_u32_e32 v0, 0x800, v0
	v_xor_b32_e32 v91, 32, v0
	ds_read2_b64 v[68:71], v91 offset0:128 offset1:160
	s_waitcnt lgkmcnt(1)
	v_pk_mul_f32 v[44:45], v[48:49], v[38:39]
	s_nop 0
	v_pk_mul_f32 v[38:39], v[44:45], v[40:41]
	ds_read2_b64 v[40:43], v0 offset1:32
	s_waitcnt lgkmcnt(0)
	v_pk_mul_f32 v[58:59], v[38:39], v[40:41]
	s_nop 0
	v_pk_mul_f32 v[50:51], v[58:59], v[42:43]
	v_xor_b32_e32 v90, 16, v0
	ds_read2_b64 v[40:43], v90 offset0:64 offset1:96
	s_waitcnt lgkmcnt(0)
	v_pk_mul_f32 v[46:47], v[50:51], v[40:41]
	s_nop 0
	v_pk_mul_f32 v[42:43], v[46:47], v[42:43]
	v_rcp_f32_e32 v40, v38
	v_pk_mul_f32 v[62:63], v[42:43], v[68:69]
	v_rcp_f32_e32 v41, v39
	v_pk_mul_f32 v[56:57], v[62:63], v[70:71]
	v_xor_b32_e32 v92, 48, v0
	ds_read2_b64 v[68:71], v92 offset0:192 offset1:224
	s_waitcnt lgkmcnt(0)
	v_pk_mul_f32 v[52:53], v[56:57], v[68:69]
	s_nop 0
	v_pk_mul_f32 v[0:1], v[52:53], v[70:71]
	s_and_saveexec_b64 s[26:27], s[4:5]
	s_cbranch_execz .LBB0_1031
	v_lshl_add_u32 v251, v175, 1, v2
	ds_read2st64_b32 v[72:73], v251 offset0:96 offset1:112
	ds_read2st64_b32 v[68:69], v251 offset0:64 offset1:80
	v_lshl_add_u32 v74, v175, 1, v2
	s_nop 0
	ds_read_b32 v84, v74 offset:32768
	s_nop 0
	v_rcp_f32_e32 v70, v36
	v_rcp_f32_e32 v71, v37
	s_nop 0
	s_nop 0
	s_waitcnt lgkmcnt(2)
	v_cvt_f32_f16_e32 v78, v73
	v_cvt_f32_f16_sdwa v79, v73 dst_sel:DWORD dst_unused:UNUSED_PAD src0_sel:WORD_1
	v_lshl_add_u32 v251, v182, 1, v2
	ds_read2st64_b32 v[146:147], v251 offset0:64 offset1:80
	s_waitcnt lgkmcnt(2)
	v_cvt_f32_f16_e32 v74, v68
	v_cvt_f32_f16_sdwa v75, v68 dst_sel:DWORD dst_unused:UNUSED_PAD src0_sel:WORD_1
	v_cvt_f32_f16_e32 v76, v72
	ds_read2st64_b32 v[148:149], v251 offset0:96 offset1:112
	v_cvt_f32_f16_sdwa v77, v72 dst_sel:DWORD dst_unused:UNUSED_PAD src0_sel:WORD_1
	v_cvt_f32_f16_e32 v72, v69
	v_cvt_f32_f16_sdwa v73, v69 dst_sel:DWORD dst_unused:UNUSED_PAD src0_sel:WORD_1
	v_pk_mul_f32 v[78:79], v[36:37], v[78:79]
	v_pk_mul_f32 v[76:77], v[70:71], v[76:77]
	v_pk_mul_f32 v[70:71], v[70:71], v[74:75]
	v_pk_mul_f32 v[72:73], v[40:41], v[72:73]
	v_pk_mul_f32 v[74:75], v[40:41], v[78:79]
	v_cvt_pk_f16_f32 v68, v78, v79
	v_pk_mul_f32 v[80:81], v[38:39], v[76:77]
	v_pk_mul_f32 v[82:83], v[38:39], v[70:71]
	ds_write2st64_b32 v181, v69, v68 offset1:18
	v_cvt_pk_f16_f32 v68, v72, v73
	v_cvt_pk_f16_f32 v69, v74, v75
	v_pk_mul_f32 v[76:77], v[0:1], v[76:77]
	ds_write2st64_b32 v181, v68, v69 offset0:36 offset1:54
	v_cvt_pk_f16_f32 v68, v80, v81
	v_cvt_pk_f16_f32 v69, v82, v83
	ds_write2st64_b32 v181, v68, v69 offset0:72 offset1:90
	v_cvt_f16_f32_e32 v68, v76
	v_pk_mul_f32 v[70:71], v[0:1], v[70:71]
	v_cvt_f16_f32_e32 v69, v77
	v_cvt_f16_f32_e32 v70, v70
	v_cvt_f16_f32_e32 v71, v71
	ds_write_b16 v176, v68
	ds_write_b16 v176, v69 offset:40
	ds_write_b16 v176, v70 offset:5120
	ds_write_b16 v176, v71 offset:5160
	s_waitcnt lgkmcnt(9)
	ds_write_b16 v176, v84 offset:10240
	v_lshl_add_u32 v74, v182, 1, v2
	s_nop 0
	s_nop 0
	ds_read_b32 v82, v74 offset:32768
	v_rcp_f32_e32 v70, v66
	v_rcp_f32_e32 v71, v67
	s_waitcnt lgkmcnt(10)
	v_cvt_f32_f16_e32 v76, v147
	v_cvt_f32_f16_sdwa v77, v147 dst_sel:DWORD dst_unused:UNUSED_PAD src0_sel:WORD_1
	s_waitcnt lgkmcnt(9)
	v_cvt_f32_f16_e32 v80, v149
	v_cvt_f32_f16_sdwa v81, v149 dst_sel:DWORD dst_unused:UNUSED_PAD src0_sel:WORD_1
	v_lshl_add_u32 v251, v184, 1, v2
	ds_read2st64_b32 v[162:163], v251 offset0:64 offset1:80
	v_cvt_f32_f16_e32 v74, v146
	v_cvt_f32_f16_e32 v78, v148
	v_cvt_f32_f16_sdwa v79, v148 dst_sel:DWORD dst_unused:UNUSED_PAD src0_sel:WORD_1
	ds_read2st64_b32 v[148:149], v251 offset0:96 offset1:112
	v_cvt_f32_f16_sdwa v75, v146 dst_sel:DWORD dst_unused:UNUSED_PAD src0_sel:WORD_1
	v_pk_mul_f32 v[36:37], v[36:37], v[76:77]
	v_pk_mul_f32 v[68:69], v[66:67], v[80:81]
	v_pk_mul_f32 v[72:73], v[70:71], v[78:79]
	v_pk_mul_f32 v[70:71], v[70:71], v[74:75]
	v_pk_mul_f32 v[74:75], v[40:41], v[36:37]
	v_pk_mul_f32 v[76:77], v[40:41], v[68:69]
	v_cvt_pk_f16_f32 v36, v36, v37
	v_cvt_pk_f16_f32 v37, v68, v69
	v_pk_mul_f32 v[78:79], v[38:39], v[72:73]
	v_pk_mul_f32 v[80:81], v[38:39], v[70:71]
	ds_write2st64_b32 v183, v36, v37 offset1:18
	v_cvt_pk_f16_f32 v36, v74, v75
	v_cvt_pk_f16_f32 v37, v76, v77
	v_pk_mul_f32 v[72:73], v[0:1], v[72:73]
	ds_write2st64_b32 v183, v36, v37 offset0:36 offset1:54
	v_cvt_pk_f16_f32 v36, v78, v79
	v_cvt_pk_f16_f32 v37, v80, v81
	ds_write2st64_b32 v183, v36, v37 offset0:72 offset1:90
	v_cvt_f16_f32_e32 v36, v72
	v_pk_mul_f32 v[70:71], v[0:1], v[70:71]
	v_cvt_f16_f32_e32 v37, v73
	v_cvt_f16_f32_e32 v68, v70
	v_cvt_f16_f32_e32 v69, v71
	ds_write_b16 v176, v36 offset:2
	s_waitcnt lgkmcnt(14)
	ds_write_b16 v176, v37 offset:42
	s_waitcnt lgkmcnt(14)
	ds_write_b16 v176, v68 offset:5122
	s_waitcnt lgkmcnt(14)
	ds_write_b16 v176, v69 offset:5162
	s_waitcnt lgkmcnt(9)
	ds_write_b16 v176, v82 offset:10242
	v_lshl_add_u32 v72, v184, 1, v2
	s_nop 0
	s_nop 0
	ds_read_b32 v80, v72 offset:32768
	v_rcp_f32_e32 v68, v64
	v_rcp_f32_e32 v69, v65
	s_waitcnt lgkmcnt(10)
	v_cvt_f32_f16_e32 v74, v163
	v_cvt_f32_f16_sdwa v75, v163 dst_sel:DWORD dst_unused:UNUSED_PAD src0_sel:WORD_1
	s_waitcnt lgkmcnt(9)
	v_cvt_f32_f16_e32 v78, v149
	v_cvt_f32_f16_sdwa v79, v149 dst_sel:DWORD dst_unused:UNUSED_PAD src0_sel:WORD_1
	v_lshl_add_u32 v251, v186, 1, v2
	ds_read2st64_b32 v[146:147], v251 offset0:64 offset1:80
	v_cvt_f32_f16_e32 v72, v162
	v_cvt_f32_f16_e32 v76, v148
	v_cvt_f32_f16_sdwa v77, v148 dst_sel:DWORD dst_unused:UNUSED_PAD src0_sel:WORD_1
	ds_read2st64_b32 v[148:149], v251 offset0:96 offset1:112
	v_cvt_f32_f16_sdwa v73, v162 dst_sel:DWORD dst_unused:UNUSED_PAD src0_sel:WORD_1
	v_pk_mul_f32 v[36:37], v[66:67], v[74:75]
	v_pk_mul_f32 v[66:67], v[64:65], v[78:79]
	v_pk_mul_f32 v[70:71], v[68:69], v[76:77]
	v_pk_mul_f32 v[68:69], v[68:69], v[72:73]
	v_pk_mul_f32 v[72:73], v[40:41], v[36:37]
	v_pk_mul_f32 v[74:75], v[40:41], v[66:67]
	v_cvt_pk_f16_f32 v36, v36, v37
	v_cvt_pk_f16_f32 v37, v66, v67
	v_pk_mul_f32 v[76:77], v[38:39], v[70:71]
	v_pk_mul_f32 v[78:79], v[38:39], v[68:69]
	ds_write2st64_b32 v185, v36, v37 offset1:18
	v_cvt_pk_f16_f32 v36, v72, v73
	v_cvt_pk_f16_f32 v37, v74, v75
	v_pk_mul_f32 v[70:71], v[0:1], v[70:71]
	ds_write2st64_b32 v185, v36, v37 offset0:36 offset1:54
	v_cvt_pk_f16_f32 v36, v76, v77
	v_cvt_pk_f16_f32 v37, v78, v79
	ds_write2st64_b32 v185, v36, v37 offset0:72 offset1:90
	v_cvt_f16_f32_e32 v36, v70
	v_pk_mul_f32 v[68:69], v[0:1], v[68:69]
	v_cvt_f16_f32_e32 v37, v71
	v_cvt_f16_f32_e32 v66, v68
	v_cvt_f16_f32_e32 v67, v69
	ds_write_b16 v176, v36 offset:4
	s_waitcnt lgkmcnt(14)
	ds_write_b16 v176, v37 offset:44
	s_waitcnt lgkmcnt(14)
	ds_write_b16 v176, v66 offset:5124
	s_waitcnt lgkmcnt(14)
	ds_write_b16 v176, v67 offset:5164
	s_waitcnt lgkmcnt(9)
	ds_write_b16 v176, v80 offset:10244
	v_lshl_add_u32 v70, v186, 1, v2
	s_nop 0
	s_nop 0
	ds_read_b32 v78, v70 offset:32768
	v_rcp_f32_e32 v66, v60
	v_rcp_f32_e32 v67, v61
	s_waitcnt lgkmcnt(10)
	v_cvt_f32_f16_e32 v72, v147
	v_cvt_f32_f16_sdwa v73, v147 dst_sel:DWORD dst_unused:UNUSED_PAD src0_sel:WORD_1
	s_waitcnt lgkmcnt(9)
	v_cvt_f32_f16_e32 v76, v149
	v_cvt_f32_f16_sdwa v77, v149 dst_sel:DWORD dst_unused:UNUSED_PAD src0_sel:WORD_1
	v_cvt_f32_f16_e32 v70, v146
	v_cvt_f32_f16_e32 v74, v148
	v_cvt_f32_f16_sdwa v75, v148 dst_sel:DWORD dst_unused:UNUSED_PAD src0_sel:WORD_1
	v_cvt_f32_f16_sdwa v71, v146 dst_sel:DWORD dst_unused:UNUSED_PAD src0_sel:WORD_1
	v_pk_mul_f32 v[36:37], v[64:65], v[72:73]
	v_pk_mul_f32 v[64:65], v[60:61], v[76:77]
	v_pk_mul_f32 v[68:69], v[66:67], v[74:75]
	v_pk_mul_f32 v[66:67], v[66:67], v[70:71]
	v_pk_mul_f32 v[70:71], v[40:41], v[36:37]
	v_pk_mul_f32 v[72:73], v[40:41], v[64:65]
	v_cvt_pk_f16_f32 v36, v36, v37
	v_cvt_pk_f16_f32 v37, v64, v65
	v_pk_mul_f32 v[74:75], v[38:39], v[68:69]
	v_pk_mul_f32 v[76:77], v[38:39], v[66:67]
	ds_write2st64_b32 v187, v36, v37 offset1:18
	v_cvt_pk_f16_f32 v36, v70, v71
	v_cvt_pk_f16_f32 v37, v72, v73
	v_pk_mul_f32 v[68:69], v[0:1], v[68:69]
	ds_write2st64_b32 v187, v36, v37 offset0:36 offset1:54
	v_cvt_pk_f16_f32 v36, v74, v75
	v_cvt_pk_f16_f32 v37, v76, v77
	ds_write2st64_b32 v187, v36, v37 offset0:72 offset1:90
	v_cvt_f16_f32_e32 v36, v68
	v_pk_mul_f32 v[66:67], v[0:1], v[66:67]
	v_cvt_f16_f32_e32 v37, v69
	v_cvt_f16_f32_e32 v64, v66
	v_cvt_f16_f32_e32 v65, v67
	ds_write_b16 v176, v36 offset:6
	ds_write_b16 v176, v37 offset:46
	ds_write_b16 v176, v64 offset:5126
	s_waitcnt lgkmcnt(14)
	ds_write_b16 v176, v65 offset:5166
	s_nop 0
	s_waitcnt lgkmcnt(7)
	ds_write_b16 v176, v78 offset:10246
	v_perm_b32 v36, v82, v84, s35
	v_perm_b32 v37, v78, v80, s35
	ds_write_b64 v176, v[36:37] offset:10280
